# v23 + counted waits at first consumer in the down / out / proj epilogues (the single vmcnt(0) after each load batch replaced by per-load counted waits)
# speedup vs baseline: 1.0085x; 1.0067x over previous
; #define PG8_STAGE(bufoff, gbase, voff) do { _Pragma("unroll") for (int _i = 0; _i < 2; ++_i) \
;         __builtin_amdgcn_global_load_lds((const unsigned*)((const char*)(gbase) + (voff)[_i]), (LAS unsigned*)(lds + (bufoff) + ldsw + _i * 8192), 16, 0, 0); } while (0)
; #define PG8_LDA(dst, b, h) do { _Pragma("unroll") for (int m = 0; m < 4; ++m) _Pragma("unroll") for (int k = 0; k < 2; ++k) dst[m][k] = *(const LAS bf16x8*)(lds + PG8_SA(b, h) + aoff + m * 2048 + k * 1024); } while (0)
; #define PG8_WAIT_V(n) asm volatile("s_waitcnt vmcnt(" #n ")" ::: "memory")
; template <class Epi, class Sched>
; __device__ __forceinline__ void gemm_phase(const int wv, LAS unsigned char* lds, const Gemm g, const Sched& S, const Epi& E) {
;     ...
;         for (int t = 0; t < nt; t += 2) {
;             const bool last = (t == nt - 2);
;             const char* a1 = cA + (size_t)(t + 1) * kstepA;
;             const char* a2 = last ? nA : cA + (size_t)(t + 2) * kstepA; const char* b2 = last ? nB : cB + (size_t)(t + 2) * kstep;
;             const char* a3 = a2 + kstepA; const char* b3 = b2 + kstep;
;             if (last && has_next) S.a_ready(nxt);
;             PG8_LDB(B0, 0, 0); PG8_SCHED; PG8_LDA(At, 0, 0); PG8_STAGE(PG8_SA(1, 1), a1 + hstepA, voffA);
;             PG8_WAIT_L(8); PG8_BAR; PG8_WAIT_L(0); PG8_MMA(0, 0, At, B0); PG8_BAR; PG8_SCHED;
;             PG8_LDB(B1, 0, 1); PG8_STAGE(PG8_SB(0, 0), b2, voffB);
;             PG8_BAR; PG8_WAIT_L(0); PG8_MMA(0, 1, At, B1); PG8_BAR;
;             PG8_LDA(At, 0, 1); PG8_STAGE(PG8_SA(0, 0), a2, voffA);
;             PG8_BAR; PG8_WAIT_L(0); PG8_MMA(1, 0, At, B0); PG8_BAR; PG8_SCHED;
;             PG8_STAGE(PG8_SB(0, 1), b2 + hstepB, voffB);
;             PG8_WAIT_V(6); PG8_BAR; PG8_MMA(1, 1, At, B1); PG8_BAR;
;             PG8_LDB(B0, 1, 0); PG8_SCHED; PG8_LDA(At, 1, 0); PG8_STAGE(PG8_SA(0, 1), a2 + hstepA, voffA);
;             PG8_WAIT_L(8); PG8_BAR; PG8_WAIT_L(0); PG8_MMA(0, 0, At, B0); PG8_BAR; PG8_SCHED;
;             PG8_LDB(B1, 1, 1); PG8_STAGE(PG8_SB(1, 0), b3, voffB);
;             PG8_BAR; PG8_WAIT_L(0); PG8_MMA(0, 1, At, B1); PG8_BAR;
;             PG8_LDA(At, 1, 1); PG8_STAGE(PG8_SA(1, 0), a3, voffA);
;             PG8_BAR; PG8_WAIT_L(0); PG8_MMA(1, 0, At, B0); PG8_BAR; PG8_SCHED;
;             PG8_STAGE(PG8_SB(1, 1), b3 + hstepB, voffB);
;             PG8_WAIT_V(6); PG8_BAR; PG8_MMA(1, 1, At, B1); PG8_BAR;
.LBB0_577:
	ds_read_b128 v[144:147], v151
	ds_read_b128 v[154:157], v151 offset:1024
	ds_read_b128 v[158:161], v151 offset:2048
	ds_read_b128 v[162:165], v151 offset:3072
	s_add_u32 s22, s20, 0xfffe0080
	s_addc_u32 s23, s21, -1
	s_cmp_eq_u32 s46, 4
	s_cselect_b32 s25, s13, s23
	s_cselect_b32 s24, s42, s22
	s_cselect_b32 s23, s11, s45
	s_cselect_b32 s22, s43, s44
	v_lshl_add_u64 v[200:201], s[20:21], 0, v[136:137]
	s_add_i32 m0, s19, 0xc000
	ds_read_b128 v[166:169], v152
	ds_read_b128 v[170:173], v152 offset:1024
	ds_read_b128 v[174:177], v152 offset:2048
	ds_read_b128 v[180:183], v152 offset:3072
	ds_read_b128 v[184:187], v152 offset:4096
	ds_read_b128 v[188:191], v152 offset:5120
	ds_read_b128 v[192:195], v152 offset:6144
	ds_read_b128 v[196:199], v152 offset:7168
	global_load_lds_dwordx4 v[200:201], off
	s_add_i32 m0, s19, 0xe000
	v_lshl_add_u64 v[200:201], s[20:21], 0, v[138:139]
	global_load_lds_dwordx4 v[200:201], off
	s_waitcnt lgkmcnt(8)
	s_barrier
	s_waitcnt lgkmcnt(0)
	v_mfma_f32_16x16x32_bf16 v[124:127], v[144:147], v[166:169], v[124:127]
	v_mfma_f32_16x16x32_bf16 v[120:123], v[158:161], v[166:169], v[120:123]
	v_mfma_f32_16x16x32_bf16 v[116:119], v[144:147], v[174:177], v[116:119]
	v_mfma_f32_16x16x32_bf16 v[104:107], v[158:161], v[174:177], v[104:107]
	v_mfma_f32_16x16x32_bf16 v[96:99], v[144:147], v[184:187], v[96:99]
	v_mfma_f32_16x16x32_bf16 v[88:91], v[158:161], v[184:187], v[88:91]
	v_mfma_f32_16x16x32_bf16 v[80:83], v[144:147], v[192:195], v[80:83]
	v_mfma_f32_16x16x32_bf16 v[72:75], v[158:161], v[192:195], v[72:75]
	v_mfma_f32_16x16x32_bf16 v[124:127], v[154:157], v[170:173], v[124:127]
	v_mfma_f32_16x16x32_bf16 v[120:123], v[162:165], v[170:173], v[120:123]
	v_mfma_f32_16x16x32_bf16 v[116:119], v[154:157], v[180:183], v[116:119]
	v_mfma_f32_16x16x32_bf16 v[104:107], v[162:165], v[180:183], v[104:107]
	v_mfma_f32_16x16x32_bf16 v[96:99], v[154:157], v[188:191], v[96:99]
	v_mfma_f32_16x16x32_bf16 v[88:91], v[162:165], v[188:191], v[88:91]
	v_mfma_f32_16x16x32_bf16 v[80:83], v[154:157], v[196:199], v[80:83]
	v_mfma_f32_16x16x32_bf16 v[72:75], v[162:165], v[196:199], v[72:75]
	s_barrier
	s_add_i32 s47, s39, s31
	v_lshl_add_u64 v[216:217], s[22:23], 0, v[130:131]
	s_mov_b32 m0, s47
	ds_read_b128 v[200:203], v153
	ds_read_b128 v[204:207], v153 offset:1024
	ds_read_b128 v[208:211], v153 offset:2048
	ds_read_b128 v[212:215], v153 offset:3072
	global_load_lds_dwordx4 v[216:217], off
	s_add_i32 m0, s47, 0x2000
	v_lshl_add_u64 v[218:219], s[22:23], 0, v[134:135]
	global_load_lds_dwordx4 v[218:219], off
	s_barrier
	s_waitcnt lgkmcnt(0)
	v_mfma_f32_16x16x32_bf16 v[112:115], v[200:203], v[166:169], v[112:115]
	v_mfma_f32_16x16x32_bf16 v[108:111], v[208:211], v[166:169], v[108:111]
	v_mfma_f32_16x16x32_bf16 v[100:103], v[200:203], v[174:177], v[100:103]
	v_mfma_f32_16x16x32_bf16 v[92:95], v[208:211], v[174:177], v[92:95]
	v_mfma_f32_16x16x32_bf16 v[84:87], v[200:203], v[184:187], v[84:87]
	v_mfma_f32_16x16x32_bf16 v[76:79], v[208:211], v[184:187], v[76:79]
	v_mfma_f32_16x16x32_bf16 v[68:71], v[200:203], v[192:195], v[68:71]
	v_mfma_f32_16x16x32_bf16 v[64:67], v[208:211], v[192:195], v[64:67]
	v_mfma_f32_16x16x32_bf16 v[112:115], v[204:207], v[170:173], v[112:115]
	v_mfma_f32_16x16x32_bf16 v[108:111], v[212:215], v[170:173], v[108:111]
	v_mfma_f32_16x16x32_bf16 v[100:103], v[204:207], v[180:183], v[100:103]
	v_mfma_f32_16x16x32_bf16 v[92:95], v[212:215], v[180:183], v[92:95]
	v_mfma_f32_16x16x32_bf16 v[84:87], v[204:207], v[188:191], v[84:87]
	v_mfma_f32_16x16x32_bf16 v[76:79], v[212:215], v[188:191], v[76:79]
	v_mfma_f32_16x16x32_bf16 v[68:71], v[204:207], v[196:199], v[68:71]
	v_mfma_f32_16x16x32_bf16 v[64:67], v[212:215], v[196:199], v[64:67]
	s_mov_b32 m0, s19
	v_lshl_add_u64 v[220:221], s[24:25], 0, v[128:129]
	s_barrier
	ds_read_b128 v[166:169], v152 offset:16384
	ds_read_b128 v[170:173], v152 offset:17408
	ds_read_b128 v[174:177], v152 offset:18432
	ds_read_b128 v[180:183], v152 offset:19456
	ds_read_b128 v[184:187], v152 offset:20480
	ds_read_b128 v[188:191], v152 offset:21504
	ds_read_b128 v[192:195], v152 offset:22528
	ds_read_b128 v[196:199], v152 offset:23552
	global_load_lds_dwordx4 v[220:221], off
	s_mov_b32 m0, s33
	v_lshl_add_u64 v[222:223], s[24:25], 0, v[132:133]
	global_load_lds_dwordx4 v[222:223], off
	s_barrier
	s_waitcnt lgkmcnt(0)
	v_mfma_f32_16x16x32_bf16 v[60:63], v[144:147], v[166:169], v[60:63]
	v_mfma_f32_16x16x32_bf16 v[56:59], v[158:161], v[166:169], v[56:59]
	v_mfma_f32_16x16x32_bf16 v[48:51], v[144:147], v[174:177], v[48:51]
	v_mfma_f32_16x16x32_bf16 v[40:43], v[158:161], v[174:177], v[40:43]
	v_mfma_f32_16x16x32_bf16 v[32:35], v[144:147], v[184:187], v[32:35]
	v_mfma_f32_16x16x32_bf16 v[24:27], v[158:161], v[184:187], v[24:27]
	v_mfma_f32_16x16x32_bf16 v[16:19], v[144:147], v[192:195], v[16:19]
	v_mfma_f32_16x16x32_bf16 v[8:11], v[158:161], v[192:195], v[8:11]
	v_mfma_f32_16x16x32_bf16 v[60:63], v[154:157], v[170:173], v[60:63]
	v_mfma_f32_16x16x32_bf16 v[56:59], v[162:165], v[170:173], v[56:59]
	v_mfma_f32_16x16x32_bf16 v[48:51], v[154:157], v[180:183], v[48:51]
	v_mfma_f32_16x16x32_bf16 v[40:43], v[162:165], v[180:183], v[40:43]
	v_mfma_f32_16x16x32_bf16 v[32:35], v[154:157], v[188:191], v[32:35]
	v_mfma_f32_16x16x32_bf16 v[24:27], v[162:165], v[188:191], v[24:27]
	v_mfma_f32_16x16x32_bf16 v[16:19], v[154:157], v[196:199], v[16:19]
	v_mfma_f32_16x16x32_bf16 v[8:11], v[162:165], v[196:199], v[8:11]
	s_barrier
	s_add_u32 s48, s22, 0x20000
	s_addc_u32 s49, s23, 0
	s_add_i32 s47, s40, s31
	s_mov_b32 m0, s47
	v_lshl_add_u64 v[144:145], s[48:49], 0, v[130:131]
	global_load_lds_dwordx4 v[144:145], off
	s_add_i32 m0, s47, 0x2000
	v_lshl_add_u64 v[144:145], s[48:49], 0, v[134:135]
	global_load_lds_dwordx4 v[144:145], off
	s_waitcnt vmcnt(6)
	s_barrier
; #define PG8_STAGE(bufoff, gbase, voff) do { _Pragma("unroll") for (int _i = 0; _i < 2; ++_i) \
;         __builtin_amdgcn_global_load_lds((const unsigned*)((const char*)(gbase) + (voff)[_i]), (LAS unsigned*)(lds + (bufoff) + ldsw + _i * 8192), 16, 0, 0); } while (0)
; #define PG8_LDA(dst, b, h) do { _Pragma("unroll") for (int m = 0; m < 4; ++m) _Pragma("unroll") for (int k = 0; k < 2; ++k) dst[m][k] = *(const LAS bf16x8*)(lds + PG8_SA(b, h) + aoff + m * 2048 + k * 1024); } while (0)
; #define PG8_LDB(dst, b, h) do { _Pragma("unroll") for (int n = 0; n < 2; ++n) _Pragma("unroll") for (int k = 0; k < 2; ++k) dst[n][k] = *(const LAS bf16x8*)(lds + PG8_SB(b, h) + boff + n * 2048 + k * 1024); } while (0)
; #define PG8_WAIT_V(n) asm volatile("s_waitcnt vmcnt(" #n ")" ::: "memory")
; #define PG8_WAIT_L(n) asm volatile("s_waitcnt lgkmcnt(" #n ")" ::: "memory")
; #define PG8_BAR __builtin_amdgcn_s_barrier()
; #define PG8_SCHED __builtin_amdgcn_sched_barrier(0)
; template <class Epi, class Sched>
; __device__ __forceinline__ void gemm_phase(const int wv, LAS unsigned char* lds, const Gemm g, const Sched& S, const Epi& E) {
;     ...
;             PG8_LDB(B0, 0, 0); PG8_SCHED; PG8_LDA(At, 0, 0); PG8_STAGE(PG8_SA(1, 1), a1 + hstepA, voffA);
;             PG8_WAIT_L(8); PG8_BAR; PG8_WAIT_L(0); PG8_MMA(0, 0, At, B0); PG8_BAR; PG8_SCHED;
;             PG8_LDB(B1, 0, 1); PG8_STAGE(PG8_SB(0, 0), b2, voffB);
;             PG8_BAR; PG8_WAIT_L(0); PG8_MMA(0, 1, At, B1); PG8_BAR;
;             PG8_LDA(At, 0, 1); PG8_STAGE(PG8_SA(0, 0), a2, voffA);
;             PG8_BAR; PG8_WAIT_L(0); PG8_MMA(1, 0, At, B0); PG8_BAR; PG8_SCHED;
;             PG8_STAGE(PG8_SB(0, 1), b2 + hstepB, voffB);
;             PG8_WAIT_V(6); PG8_BAR; PG8_MMA(1, 1, At, B1); PG8_BAR;
;             PG8_LDB(B0, 1, 0); PG8_SCHED; PG8_LDA(At, 1, 0); PG8_STAGE(PG8_SA(0, 1), a2 + hstepA, voffA);
;             PG8_WAIT_L(8); PG8_BAR; PG8_WAIT_L(0); PG8_MMA(0, 0, At, B0); PG8_BAR; PG8_SCHED;
;             PG8_LDB(B1, 1, 1); PG8_STAGE(PG8_SB(1, 0), b3, voffB);
;             PG8_BAR; PG8_WAIT_L(0); PG8_MMA(0, 1, At, B1); PG8_BAR;
;             PG8_LDA(At, 1, 1); PG8_STAGE(PG8_SA(1, 0), a3, voffA);
;             PG8_BAR; PG8_WAIT_L(0); PG8_MMA(1, 0, At, B0); PG8_BAR; PG8_SCHED;
;             PG8_STAGE(PG8_SB(1, 1), b3 + hstepB, voffB);
;             PG8_WAIT_V(6); PG8_BAR; PG8_MMA(1, 1, At, B1); PG8_BAR;
	v_mfma_f32_16x16x32_bf16 v[52:55], v[200:203], v[166:169], v[52:55]
	v_mfma_f32_16x16x32_bf16 v[44:47], v[208:211], v[166:169], v[44:47]
	v_mfma_f32_16x16x32_bf16 v[36:39], v[200:203], v[174:177], v[36:39]
	v_mfma_f32_16x16x32_bf16 v[28:31], v[208:211], v[174:177], v[28:31]
	v_mfma_f32_16x16x32_bf16 v[20:23], v[200:203], v[184:187], v[20:23]
	v_mfma_f32_16x16x32_bf16 v[12:15], v[208:211], v[184:187], v[12:15]
	v_mfma_f32_16x16x32_bf16 v[4:7], v[200:203], v[192:195], v[4:7]
	v_mfma_f32_16x16x32_bf16 v[0:3], v[208:211], v[192:195], v[0:3]
	v_mfma_f32_16x16x32_bf16 v[52:55], v[204:207], v[170:173], v[52:55]
	v_mfma_f32_16x16x32_bf16 v[44:47], v[212:215], v[170:173], v[44:47]
	v_mfma_f32_16x16x32_bf16 v[36:39], v[204:207], v[180:183], v[36:39]
	v_mfma_f32_16x16x32_bf16 v[28:31], v[212:215], v[180:183], v[28:31]
	v_mfma_f32_16x16x32_bf16 v[20:23], v[204:207], v[188:191], v[20:23]
	v_mfma_f32_16x16x32_bf16 v[12:15], v[212:215], v[188:191], v[12:15]
	v_mfma_f32_16x16x32_bf16 v[4:7], v[204:207], v[196:199], v[4:7]
	v_mfma_f32_16x16x32_bf16 v[0:3], v[212:215], v[196:199], v[0:3]
	s_add_i32 s47, 0, 0x18000
	v_add_u32_e32 v162, s47, v149
	s_barrier
	ds_read_b128 v[144:147], v162
	ds_read_b128 v[154:157], v162 offset:1024
	ds_read_b128 v[158:161], v162 offset:2048
	ds_read_b128 v[162:165], v162 offset:3072
	s_add_u32 s24, s24, 0x20000
	s_addc_u32 s25, s25, 0
	s_mov_b32 m0, s34
	v_lshl_add_u64 v[200:201], s[24:25], 0, v[128:129]
	ds_read_b128 v[166:169], v152 offset:32768
	ds_read_b128 v[170:173], v152 offset:33792
	ds_read_b128 v[174:177], v152 offset:34816
	ds_read_b128 v[180:183], v152 offset:35840
	ds_read_b128 v[184:187], v152 offset:36864
	ds_read_b128 v[188:191], v152 offset:37888
	ds_read_b128 v[192:195], v152 offset:38912
	ds_read_b128 v[196:199], v152 offset:39936
	global_load_lds_dwordx4 v[200:201], off
	s_mov_b32 m0, s35
	v_lshl_add_u64 v[200:201], s[24:25], 0, v[132:133]
	global_load_lds_dwordx4 v[200:201], off
	s_waitcnt lgkmcnt(8)
	s_barrier
	s_waitcnt lgkmcnt(0)
	v_mfma_f32_16x16x32_bf16 v[124:127], v[144:147], v[166:169], v[124:127]
	v_mfma_f32_16x16x32_bf16 v[120:123], v[158:161], v[166:169], v[120:123]
	v_mfma_f32_16x16x32_bf16 v[116:119], v[144:147], v[174:177], v[116:119]
	v_mfma_f32_16x16x32_bf16 v[104:107], v[158:161], v[174:177], v[104:107]
	v_mfma_f32_16x16x32_bf16 v[96:99], v[144:147], v[184:187], v[96:99]
	v_mfma_f32_16x16x32_bf16 v[88:91], v[158:161], v[184:187], v[88:91]
	v_mfma_f32_16x16x32_bf16 v[80:83], v[144:147], v[192:195], v[80:83]
	v_mfma_f32_16x16x32_bf16 v[72:75], v[158:161], v[192:195], v[72:75]
	v_mfma_f32_16x16x32_bf16 v[124:127], v[154:157], v[170:173], v[124:127]
	v_mfma_f32_16x16x32_bf16 v[120:123], v[162:165], v[170:173], v[120:123]
	v_mfma_f32_16x16x32_bf16 v[116:119], v[154:157], v[180:183], v[116:119]
	v_mfma_f32_16x16x32_bf16 v[104:107], v[162:165], v[180:183], v[104:107]
	v_mfma_f32_16x16x32_bf16 v[96:99], v[154:157], v[188:191], v[96:99]
	v_mfma_f32_16x16x32_bf16 v[88:91], v[162:165], v[188:191], v[88:91]
	v_mfma_f32_16x16x32_bf16 v[80:83], v[154:157], v[196:199], v[80:83]
	v_mfma_f32_16x16x32_bf16 v[72:75], v[162:165], v[196:199], v[72:75]
	s_barrier
	s_add_i32 s24, 0, 0x1c000
	s_add_i32 s25, s47, s31
	v_add_u32_e32 v212, s24, v149
	v_lshl_add_u64 v[216:217], v[216:217], 0, s[8:9]
	s_mov_b32 m0, s25
	ds_read_b128 v[200:203], v212
	ds_read_b128 v[204:207], v212 offset:1024
	ds_read_b128 v[208:211], v212 offset:2048
	ds_read_b128 v[212:215], v212 offset:3072
	global_load_lds_dwordx4 v[216:217], off
	s_add_i32 m0, s25, 0x2000
	v_lshl_add_u64 v[216:217], v[218:219], 0, s[8:9]
	global_load_lds_dwordx4 v[216:217], off
	s_barrier
	s_waitcnt lgkmcnt(0)
	v_mfma_f32_16x16x32_bf16 v[112:115], v[200:203], v[166:169], v[112:115]
	v_mfma_f32_16x16x32_bf16 v[108:111], v[208:211], v[166:169], v[108:111]
	v_mfma_f32_16x16x32_bf16 v[100:103], v[200:203], v[174:177], v[100:103]
	v_mfma_f32_16x16x32_bf16 v[92:95], v[208:211], v[174:177], v[92:95]
	v_mfma_f32_16x16x32_bf16 v[84:87], v[200:203], v[184:187], v[84:87]
	v_mfma_f32_16x16x32_bf16 v[76:79], v[208:211], v[184:187], v[76:79]
	v_mfma_f32_16x16x32_bf16 v[68:71], v[200:203], v[192:195], v[68:71]
	v_mfma_f32_16x16x32_bf16 v[64:67], v[208:211], v[192:195], v[64:67]
	v_mfma_f32_16x16x32_bf16 v[112:115], v[204:207], v[170:173], v[112:115]
	v_mfma_f32_16x16x32_bf16 v[108:111], v[212:215], v[170:173], v[108:111]
	v_mfma_f32_16x16x32_bf16 v[100:103], v[204:207], v[180:183], v[100:103]
	v_mfma_f32_16x16x32_bf16 v[92:95], v[212:215], v[180:183], v[92:95]
	v_mfma_f32_16x16x32_bf16 v[84:87], v[204:207], v[188:191], v[84:87]
	v_mfma_f32_16x16x32_bf16 v[76:79], v[212:215], v[188:191], v[76:79]
	v_mfma_f32_16x16x32_bf16 v[68:71], v[204:207], v[196:199], v[68:71]
	v_mfma_f32_16x16x32_bf16 v[64:67], v[212:215], v[196:199], v[64:67]
	s_mov_b32 m0, s37
	v_lshl_add_u64 v[216:217], v[220:221], 0, s[8:9]
	s_barrier
	ds_read_b128 v[166:169], v152 offset:49152
	ds_read_b128 v[170:173], v152 offset:50176
	ds_read_b128 v[174:177], v152 offset:51200
	ds_read_b128 v[180:183], v152 offset:52224
	ds_read_b128 v[184:187], v152 offset:53248
	ds_read_b128 v[188:191], v152 offset:54272
	ds_read_b128 v[192:195], v152 offset:55296
	ds_read_b128 v[196:199], v152 offset:56320
	global_load_lds_dwordx4 v[216:217], off
	s_mov_b32 m0, s38
	v_lshl_add_u64 v[216:217], v[222:223], 0, s[8:9]
	global_load_lds_dwordx4 v[216:217], off
	s_barrier
; #define PG8_WAIT_V(n) asm volatile("s_waitcnt vmcnt(" #n ")" ::: "memory")
; template <class Epi, class Sched>
; __device__ __forceinline__ void gemm_phase(const int wv, LAS unsigned char* lds, const Gemm g, const Sched& S, const Epi& E) {
;     ...
;             PG8_LDB(B0, 0, 0); PG8_SCHED; PG8_LDA(At, 0, 0); PG8_STAGE(PG8_SA(1, 1), a1 + hstepA, voffA);
;             PG8_WAIT_L(8); PG8_BAR; PG8_WAIT_L(0); PG8_MMA(0, 0, At, B0); PG8_BAR; PG8_SCHED;
;             PG8_LDB(B1, 0, 1); PG8_STAGE(PG8_SB(0, 0), b2, voffB);
;             PG8_BAR; PG8_WAIT_L(0); PG8_MMA(0, 1, At, B1); PG8_BAR;
;             PG8_LDA(At, 0, 1); PG8_STAGE(PG8_SA(0, 0), a2, voffA);
;             PG8_BAR; PG8_WAIT_L(0); PG8_MMA(1, 0, At, B0); PG8_BAR; PG8_SCHED;
;             PG8_STAGE(PG8_SB(0, 1), b2 + hstepB, voffB);
;             PG8_WAIT_V(6); PG8_BAR; PG8_MMA(1, 1, At, B1); PG8_BAR;
;             PG8_LDB(B0, 1, 0); PG8_SCHED; PG8_LDA(At, 1, 0); PG8_STAGE(PG8_SA(0, 1), a2 + hstepA, voffA);
;             PG8_WAIT_L(8); PG8_BAR; PG8_WAIT_L(0); PG8_MMA(0, 0, At, B0); PG8_BAR; PG8_SCHED;
;             PG8_LDB(B1, 1, 1); PG8_STAGE(PG8_SB(1, 0), b3, voffB);
;             PG8_BAR; PG8_WAIT_L(0); PG8_MMA(0, 1, At, B1); PG8_BAR;
;             PG8_LDA(At, 1, 1); PG8_STAGE(PG8_SA(1, 0), a3, voffA);
;             PG8_BAR; PG8_WAIT_L(0); PG8_MMA(1, 0, At, B0); PG8_BAR; PG8_SCHED;
;             PG8_STAGE(PG8_SB(1, 1), b3 + hstepB, voffB);
;             PG8_WAIT_V(6); PG8_BAR; PG8_MMA(1, 1, At, B1); PG8_BAR;
;         }
;     __device__ __forceinline__ void operator()(const f32x4 (&acc)[2][2][4][2], const Unit& u, int wr, int wc, int fr, int fq) const {
;         const int row0 = u.pm * 256 + wr * 64 + fr; const int col0 = u.pn * 256 + wc * 32 + 8 * fq;
; #pragma unroll
;         for (int ai = 0; ai < 2; ++ai) {
;             u32x4 gv[4][2], yv[4][2];
; #pragma unroll
;             for (int m = 0; m < 4; ++m)
; #pragma unroll
;                 for (int bj = 0; bj < 2; ++bj) {
;                     const int row = row0 + ai * 128 + m * 16, col = col0 + bj * 128;
;                     gv[m][bj] = *(const u32x4*)(gates + (size_t)row * 2048 + SECOND * 1024 + col);
;                     if (SECOND) yv[m][bj] = *(const u32x4*)(Y + (size_t)row * 1024 + col);
;                 }
; #pragma unroll
;             for (int m = 0; m < 4; ++m)
; #pragma unroll
;                 for (int bj = 0; bj < 2; ++bj) {
	s_waitcnt lgkmcnt(0)
	v_mfma_f32_16x16x32_bf16 v[60:63], v[144:147], v[166:169], v[60:63]
	v_mfma_f32_16x16x32_bf16 v[56:59], v[158:161], v[166:169], v[56:59]
	v_mfma_f32_16x16x32_bf16 v[48:51], v[144:147], v[174:177], v[48:51]
	v_mfma_f32_16x16x32_bf16 v[40:43], v[158:161], v[174:177], v[40:43]
	v_mfma_f32_16x16x32_bf16 v[32:35], v[144:147], v[184:187], v[32:35]
	v_mfma_f32_16x16x32_bf16 v[24:27], v[158:161], v[184:187], v[24:27]
	v_mfma_f32_16x16x32_bf16 v[16:19], v[144:147], v[192:195], v[16:19]
	v_mfma_f32_16x16x32_bf16 v[8:11], v[158:161], v[192:195], v[8:11]
	v_mfma_f32_16x16x32_bf16 v[60:63], v[154:157], v[170:173], v[60:63]
	v_mfma_f32_16x16x32_bf16 v[56:59], v[162:165], v[170:173], v[56:59]
	v_mfma_f32_16x16x32_bf16 v[48:51], v[154:157], v[180:183], v[48:51]
	v_mfma_f32_16x16x32_bf16 v[40:43], v[162:165], v[180:183], v[40:43]
	v_mfma_f32_16x16x32_bf16 v[32:35], v[154:157], v[188:191], v[32:35]
	v_mfma_f32_16x16x32_bf16 v[24:27], v[162:165], v[188:191], v[24:27]
	v_mfma_f32_16x16x32_bf16 v[16:19], v[154:157], v[196:199], v[16:19]
	v_mfma_f32_16x16x32_bf16 v[8:11], v[162:165], v[196:199], v[8:11]
	s_barrier
	s_add_u32 s22, s22, 0x20080
	s_addc_u32 s23, s23, 0
	s_add_i32 s24, s24, s31
	s_mov_b32 m0, s24
	v_lshl_add_u64 v[144:145], s[22:23], 0, v[130:131]
	global_load_lds_dwordx4 v[144:145], off
	s_add_i32 m0, s24, 0x2000
	v_lshl_add_u64 v[144:145], s[22:23], 0, v[134:135]
	global_load_lds_dwordx4 v[144:145], off
	s_waitcnt vmcnt(6)
	s_barrier
	v_mfma_f32_16x16x32_bf16 v[52:55], v[200:203], v[166:169], v[52:55]
	v_mfma_f32_16x16x32_bf16 v[44:47], v[208:211], v[166:169], v[44:47]
	v_mfma_f32_16x16x32_bf16 v[36:39], v[200:203], v[174:177], v[36:39]
	v_mfma_f32_16x16x32_bf16 v[28:31], v[208:211], v[174:177], v[28:31]
	v_mfma_f32_16x16x32_bf16 v[20:23], v[200:203], v[184:187], v[20:23]
	v_mfma_f32_16x16x32_bf16 v[12:15], v[208:211], v[184:187], v[12:15]
	v_mfma_f32_16x16x32_bf16 v[4:7], v[200:203], v[192:195], v[4:7]
	v_mfma_f32_16x16x32_bf16 v[0:3], v[208:211], v[192:195], v[0:3]
	v_mfma_f32_16x16x32_bf16 v[52:55], v[204:207], v[170:173], v[52:55]
	v_mfma_f32_16x16x32_bf16 v[44:47], v[212:215], v[170:173], v[44:47]
	v_mfma_f32_16x16x32_bf16 v[36:39], v[204:207], v[180:183], v[36:39]
	v_mfma_f32_16x16x32_bf16 v[28:31], v[212:215], v[180:183], v[28:31]
	v_mfma_f32_16x16x32_bf16 v[20:23], v[204:207], v[188:191], v[20:23]
	v_mfma_f32_16x16x32_bf16 v[12:15], v[212:215], v[188:191], v[12:15]
	v_mfma_f32_16x16x32_bf16 v[4:7], v[204:207], v[196:199], v[4:7]
	v_mfma_f32_16x16x32_bf16 v[0:3], v[212:215], v[196:199], v[0:3]
	s_add_i32 s46, s46, 2
	s_add_u32 s20, s20, 0x100
	s_addc_u32 s21, s21, 0
	s_add_u32 s44, s44, 0x100
	s_addc_u32 s45, s45, 0
	s_cmp_gt_u32 s46, 5
	s_barrier
	s_cbranch_scc0 .LBB0_577
	v_lshl_add_u32 v146, s18, 8, v148
	v_lshl_or_b32 v144, s41, 8, v150
	v_ashrrev_i32_e32 v147, 31, v146
	v_or_b32_e32 v170, 16, v146
	v_ashrrev_i32_e32 v145, 31, v144
	v_lshlrev_b64 v[154:155], 12, v[146:147]
	v_ashrrev_i32_e32 v171, 31, v170
	v_lshl_add_u64 v[154:155], s[4:5], 0, v[154:155]
	v_lshlrev_b64 v[144:145], 1, v[144:145]
	v_lshlrev_b64 v[162:163], 12, v[170:171]
	v_lshl_add_u64 v[158:159], v[154:155], 0, v[144:145]
	v_lshl_add_u64 v[162:163], s[4:5], 0, v[162:163]
	global_load_dwordx4 v[154:157], v[158:159], off
	s_nop 0
	global_load_dwordx4 v[158:161], v[158:159], off offset:256
	v_lshl_add_u64 v[166:167], v[162:163], 0, v[144:145]
	global_load_dwordx4 v[162:165], v[166:167], off
	v_or_b32_e32 v188, 32, v146
	global_load_dwordx4 v[166:169], v[166:167], off offset:256
	v_or_b32_e32 v190, 48, v146
	v_ashrrev_i32_e32 v189, 31, v188
	v_ashrrev_i32_e32 v191, 31, v190
	v_lshlrev_b64 v[174:175], 12, v[188:189]
	v_lshlrev_b64 v[176:177], 12, v[190:191]
	v_lshlrev_b64 v[172:173], 11, v[146:147]
	v_lshlrev_b64 v[192:193], 11, v[170:171]
	v_lshl_add_u64 v[170:171], s[4:5], 0, v[174:175]
	v_lshl_add_u64 v[174:175], s[4:5], 0, v[176:177]
	v_lshl_add_u64 v[172:173], s[2:3], 0, v[172:173]
	v_lshl_add_u64 v[176:177], v[170:171], 0, v[144:145]
	v_lshl_add_u64 v[184:185], v[174:175], 0, v[144:145]
	v_lshl_add_u64 v[194:195], v[172:173], 0, v[144:145]
	global_load_dwordx4 v[170:173], v[176:177], off
	s_nop 0
	global_load_dwordx4 v[174:177], v[176:177], off offset:256
	s_nop 0
	global_load_dwordx4 v[180:183], v[184:185], off
	s_nop 0
	global_load_dwordx4 v[184:187], v[184:185], off offset:256
	s_and_b64 vcc, exec, s[0:1]
	s_mov_b32 s41, s10
	s_mov_b32 s18, s12
	s_mov_b64 s[22:23], s[16:17]
	s_mov_b64 s[20:21], s[14:15]
	s_waitcnt vmcnt(7)
	v_lshlrev_b32_e32 v147, 16, v154
	s_waitcnt vmcnt(6)
	v_lshlrev_b32_e32 v201, 16, v160
	v_and_b32_e32 v154, 0xffff0000, v154
	v_lshlrev_b32_e32 v196, 16, v155
	v_and_b32_e32 v155, 0xffff0000, v155
	v_lshlrev_b32_e32 v197, 16, v156
	v_and_b32_e32 v156, 0xffff0000, v156
	v_lshlrev_b32_e32 v198, 16, v157
	v_and_b32_e32 v157, 0xffff0000, v157
	v_and_b32_e32 v160, 0xffff0000, v160
	v_lshlrev_b32_e32 v202, 16, v161
	v_and_b32_e32 v161, 0xffff0000, v161
	v_mul_f32_e32 v124, v124, v147
	v_mul_f32_e32 v147, v108, v201
	s_waitcnt vmcnt(5)
; __device__ __forceinline__ unsigned cvt_pk_bf16(float lo, float hi) { unsigned r; asm volatile("v_cvt_pk_bf16_f32 %0, %1, %2" : "=v"(r) : "v"(lo), "v"(hi)); return r; }
; __device__ __forceinline__ float bflo(unsigned u) { return __uint_as_float(u << 16); }
; __device__ __forceinline__ float bfhi(unsigned u) { return __uint_as_float(u & 0xffff0000u); }
;     __device__ __forceinline__ void operator()(const f32x4 (&acc)[2][2][4][2], const Unit& u, int wr, int wc, int fr, int fq) const {
;     ...
;         for (int ai = 0; ai < 2; ++ai) {
;             u32x4 gv[4][2], yv[4][2];
; #pragma unroll
;             for (int m = 0; m < 4; ++m)
; #pragma unroll
;                 for (int bj = 0; bj < 2; ++bj) {
;                     const int row = row0 + ai * 128 + m * 16, col = col0 + bj * 128;
;                     gv[m][bj] = *(const u32x4*)(gates + (size_t)row * 2048 + SECOND * 1024 + col);
;                     if (SECOND) yv[m][bj] = *(const u32x4*)(Y + (size_t)row * 1024 + col);
;                 }
; #pragma unroll
;             for (int m = 0; m < 4; ++m)
; #pragma unroll
;                 for (int bj = 0; bj < 2; ++bj) {
;                     const int row = row0 + ai * 128 + m * 16, col = col0 + bj * 128;
;                     const u32x4 g = gv[m][bj];
;                     const f32x4 a0 = acc[ai][bj][m][0], a1 = acc[ai][bj][m][1];
;                     float r[8] = {a0[0] * bflo(g.x), a0[1] * bfhi(g.x), a0[2] * bflo(g.y), a0[3] * bfhi(g.y), a1[0] * bflo(g.z), a1[1] * bfhi(g.z), a1[2] * bflo(g.w), a1[3] * bfhi(g.w)};
;                     if (SECOND) { const u32x4 y = yv[m][bj];
;                         r[0] += bflo(y.x); r[1] += bfhi(y.x); r[2] += bflo(y.y); r[3] += bfhi(y.y); r[4] += bflo(y.z); r[5] += bfhi(y.z); r[6] += bflo(y.w); r[7] += bfhi(y.w); }
;                     u32x4 w; w.x = cvt_pk_bf16(r[0], r[1]); w.y = cvt_pk_bf16(r[2], r[3]); w.z = cvt_pk_bf16(r[4], r[5]); w.w = cvt_pk_bf16(r[6], r[7]);
;                     *(u32x4*)(Y + (size_t)row * 1024 + col) = w;
	v_lshlrev_b32_e32 v108, 16, v162
	v_lshlrev_b32_e32 v199, 16, v158
	v_and_b32_e32 v158, 0xffff0000, v158
	v_lshlrev_b32_e32 v200, 16, v159
	v_and_b32_e32 v159, 0xffff0000, v159
	v_mul_f32_e32 v125, v125, v154
	v_mul_f32_e32 v127, v127, v155
	v_mul_f32_e32 v120, v120, v197
	v_mul_f32_e32 v121, v121, v156
	v_mul_f32_e32 v123, v123, v157
	v_mul_f32_e32 v154, v109, v160
	v_mul_f32_e32 v155, v110, v202
	v_mul_f32_e32 v156, v111, v161
	v_and_b32_e32 v109, 0xffff0000, v162
	v_lshlrev_b32_e32 v110, 16, v163
	v_and_b32_e32 v111, 0xffff0000, v163
	v_lshlrev_b32_e32 v157, 16, v164
	v_mul_f32_e32 v116, v116, v108
	v_cvt_pk_bf16_f32 v108, v124, v125
	v_mul_f32_e32 v126, v126, v196
	v_mul_f32_e32 v122, v122, v198
	v_mul_f32_e32 v112, v112, v199
	v_mul_f32_e32 v113, v113, v158
	v_mul_f32_e32 v115, v115, v159
	v_lshlrev_b32_e32 v159, 16, v165
	v_mul_f32_e32 v117, v117, v109
	v_mul_f32_e32 v118, v118, v110
	v_mul_f32_e32 v119, v119, v111
	v_cvt_pk_bf16_f32 v109, v126, v127
	v_cvt_pk_bf16_f32 v110, v120, v121
	v_cvt_pk_bf16_f32 v111, v122, v123
	v_mul_f32_e32 v120, v104, v157
	global_store_dwordx4 v[194:195], v[108:111], off
	v_and_b32_e32 v104, 0xffff0000, v165
	v_mul_f32_e32 v114, v114, v200
	v_cvt_pk_bf16_f32 v108, v112, v113
	v_and_b32_e32 v158, 0xffff0000, v164
	v_cvt_pk_bf16_f32 v109, v114, v115
	v_cvt_pk_bf16_f32 v110, v147, v154
	v_cvt_pk_bf16_f32 v111, v155, v156
	global_store_dwordx4 v[194:195], v[108:111], off offset:256
	v_mul_f32_e32 v107, v107, v104
	v_mul_f32_e32 v121, v105, v158
	v_mul_f32_e32 v108, v106, v159
	v_cvt_pk_bf16_f32 v104, v116, v117
	v_cvt_pk_bf16_f32 v105, v118, v119
	v_cvt_pk_bf16_f32 v106, v120, v121
	v_cvt_pk_bf16_f32 v107, v108, v107
	v_lshl_add_u64 v[108:109], s[2:3], 0, v[192:193]
	v_lshl_add_u64 v[108:109], v[108:109], 0, v[144:145]
	global_store_dwordx4 v[108:109], v[104:107], off
	s_nop 1
	s_waitcnt vmcnt(7)
	v_lshlrev_b32_e32 v104, 16, v166
	v_mul_f32_e32 v100, v100, v104
	v_and_b32_e32 v104, 0xffff0000, v166
	v_mul_f32_e32 v101, v101, v104
	v_lshlrev_b32_e32 v104, 16, v167
	v_mul_f32_e32 v102, v102, v104
	v_and_b32_e32 v104, 0xffff0000, v167
	v_mul_f32_e32 v103, v103, v104
	v_lshlrev_b32_e32 v104, 16, v168
	v_mul_f32_e32 v104, v92, v104
	v_and_b32_e32 v92, 0xffff0000, v168
	v_mul_f32_e32 v105, v93, v92
	v_lshlrev_b32_e32 v92, 16, v169
	v_mul_f32_e32 v106, v94, v92
	v_and_b32_e32 v92, 0xffff0000, v169
	v_mul_f32_e32 v95, v95, v92
	v_cvt_pk_bf16_f32 v92, v100, v101
	v_cvt_pk_bf16_f32 v93, v102, v103
	v_cvt_pk_bf16_f32 v94, v104, v105
	v_cvt_pk_bf16_f32 v95, v106, v95
	global_store_dwordx4 v[108:109], v[92:95], off offset:256
	v_add_u32_e32 v102, 0xb0, v146
	v_ashrrev_i32_e32 v103, 31, v102
	s_waitcnt vmcnt(7)
	v_lshlrev_b32_e32 v94, 16, v170
	v_mul_f32_e32 v94, v96, v94
	v_lshlrev_b32_e32 v96, 16, v171
	v_and_b32_e32 v95, 0xffff0000, v170
	v_mul_f32_e32 v96, v98, v96
	v_lshlrev_b32_e32 v98, 16, v172
	v_mul_f32_e32 v95, v97, v95
	v_and_b32_e32 v97, 0xffff0000, v171
	v_mul_f32_e32 v98, v88, v98
	v_and_b32_e32 v88, 0xffff0000, v172
	v_lshlrev_b64 v[92:93], 11, v[188:189]
	v_mul_f32_e32 v97, v99, v97
	v_mul_f32_e32 v99, v89, v88
	v_lshlrev_b32_e32 v88, 16, v173
	v_mul_f32_e32 v100, v90, v88
	v_and_b32_e32 v88, 0xffff0000, v173
	v_lshl_add_u64 v[92:93], s[2:3], 0, v[92:93]
	v_mul_f32_e32 v91, v91, v88
	v_cvt_pk_bf16_f32 v88, v94, v95
	v_lshl_add_u64 v[92:93], v[92:93], 0, v[144:145]
	v_cvt_pk_bf16_f32 v89, v96, v97
	v_cvt_pk_bf16_f32 v90, v98, v99
	v_cvt_pk_bf16_f32 v91, v100, v91
	global_store_dwordx4 v[92:93], v[88:91], off
	v_add_u32_e32 v96, 0x80, v146
	v_ashrrev_i32_e32 v97, 31, v96
	s_waitcnt vmcnt(7)
	v_lshlrev_b32_e32 v88, 16, v174
	v_mul_f32_e32 v84, v84, v88
	v_and_b32_e32 v88, 0xffff0000, v174
	v_mul_f32_e32 v85, v85, v88
	v_lshlrev_b32_e32 v88, 16, v175
	v_mul_f32_e32 v86, v86, v88
	v_and_b32_e32 v88, 0xffff0000, v175
	v_mul_f32_e32 v87, v87, v88
	v_lshlrev_b32_e32 v88, 16, v176
	v_mul_f32_e32 v88, v76, v88
	v_and_b32_e32 v76, 0xffff0000, v176
	v_mul_f32_e32 v89, v77, v76
	v_lshlrev_b32_e32 v76, 16, v177
	v_mul_f32_e32 v90, v78, v76
	v_and_b32_e32 v76, 0xffff0000, v177
	v_mul_f32_e32 v79, v79, v76
	v_cvt_pk_bf16_f32 v76, v84, v85
	v_cvt_pk_bf16_f32 v77, v86, v87
	v_cvt_pk_bf16_f32 v78, v88, v89
	v_cvt_pk_bf16_f32 v79, v90, v79
	global_store_dwordx4 v[92:93], v[76:79], off offset:256
	v_add_u32_e32 v98, 0x90, v146
	v_ashrrev_i32_e32 v99, 31, v98
	s_waitcnt vmcnt(7)
	v_lshlrev_b32_e32 v78, 16, v180
	v_mul_f32_e32 v78, v80, v78
	v_lshlrev_b32_e32 v80, 16, v181
	v_and_b32_e32 v79, 0xffff0000, v180
	v_mul_f32_e32 v80, v82, v80
	v_lshlrev_b32_e32 v82, 16, v182
	v_mul_f32_e32 v79, v81, v79
	v_and_b32_e32 v81, 0xffff0000, v181
	v_mul_f32_e32 v82, v72, v82
	v_and_b32_e32 v72, 0xffff0000, v182
	v_lshlrev_b64 v[76:77], 11, v[190:191]
	v_mul_f32_e32 v81, v83, v81
	v_mul_f32_e32 v83, v73, v72
	v_lshlrev_b32_e32 v72, 16, v183
	v_mul_f32_e32 v84, v74, v72
	v_and_b32_e32 v72, 0xffff0000, v183
	v_lshl_add_u64 v[76:77], s[2:3], 0, v[76:77]
	v_mul_f32_e32 v75, v75, v72
	v_cvt_pk_bf16_f32 v72, v78, v79
	v_lshl_add_u64 v[76:77], v[76:77], 0, v[144:145]
	v_cvt_pk_bf16_f32 v73, v80, v81
	v_cvt_pk_bf16_f32 v74, v82, v83
	v_cvt_pk_bf16_f32 v75, v84, v75
	global_store_dwordx4 v[76:77], v[72:75], off
	v_add_u32_e32 v100, 0xa0, v146
	v_ashrrev_i32_e32 v101, 31, v100
	s_waitcnt vmcnt(7)
; __device__ __forceinline__ unsigned cvt_pk_bf16(float lo, float hi) { unsigned r; asm volatile("v_cvt_pk_bf16_f32 %0, %1, %2" : "=v"(r) : "v"(lo), "v"(hi)); return r; }
; __device__ __forceinline__ float bflo(unsigned u) { return __uint_as_float(u << 16); }
; __device__ __forceinline__ float bfhi(unsigned u) { return __uint_as_float(u & 0xffff0000u); }
;     __device__ __forceinline__ void operator()(const f32x4 (&acc)[2][2][4][2], const Unit& u, int wr, int wc, int fr, int fq) const {
;     ...
;         for (int ai = 0; ai < 2; ++ai) {
;             u32x4 gv[4][2], yv[4][2];
; #pragma unroll
;             for (int m = 0; m < 4; ++m)
; #pragma unroll
;                 for (int bj = 0; bj < 2; ++bj) {
;                     const int row = row0 + ai * 128 + m * 16, col = col0 + bj * 128;
;                     gv[m][bj] = *(const u32x4*)(gates + (size_t)row * 2048 + SECOND * 1024 + col);
;                     if (SECOND) yv[m][bj] = *(const u32x4*)(Y + (size_t)row * 1024 + col);
;                 }
; #pragma unroll
;             for (int m = 0; m < 4; ++m)
; #pragma unroll
;                 for (int bj = 0; bj < 2; ++bj) {
;                     const int row = row0 + ai * 128 + m * 16, col = col0 + bj * 128;
;                     const u32x4 g = gv[m][bj];
;                     const f32x4 a0 = acc[ai][bj][m][0], a1 = acc[ai][bj][m][1];
;                     float r[8] = {a0[0] * bflo(g.x), a0[1] * bfhi(g.x), a0[2] * bflo(g.y), a0[3] * bfhi(g.y), a1[0] * bflo(g.z), a1[1] * bfhi(g.z), a1[2] * bflo(g.w), a1[3] * bfhi(g.w)};
;                     if (SECOND) { const u32x4 y = yv[m][bj];
;                         r[0] += bflo(y.x); r[1] += bfhi(y.x); r[2] += bflo(y.y); r[3] += bfhi(y.y); r[4] += bflo(y.z); r[5] += bfhi(y.z); r[6] += bflo(y.w); r[7] += bfhi(y.w); }
;                     u32x4 w; w.x = cvt_pk_bf16(r[0], r[1]); w.y = cvt_pk_bf16(r[2], r[3]); w.z = cvt_pk_bf16(r[4], r[5]); w.w = cvt_pk_bf16(r[6], r[7]);
;                     *(u32x4*)(Y + (size_t)row * 1024 + col) = w;
	v_lshlrev_b32_e32 v72, 16, v184
	v_mul_f32_e32 v68, v68, v72
	v_and_b32_e32 v72, 0xffff0000, v184
	v_mul_f32_e32 v69, v69, v72
	v_lshlrev_b32_e32 v72, 16, v185
	v_mul_f32_e32 v70, v70, v72
	v_and_b32_e32 v72, 0xffff0000, v185
	v_mul_f32_e32 v71, v71, v72
	v_lshlrev_b32_e32 v72, 16, v186
	v_mul_f32_e32 v72, v64, v72
	v_and_b32_e32 v64, 0xffff0000, v186
	v_mul_f32_e32 v73, v65, v64
	v_lshlrev_b32_e32 v64, 16, v187
	v_mul_f32_e32 v74, v66, v64
	v_and_b32_e32 v64, 0xffff0000, v187
	v_mul_f32_e32 v67, v67, v64
	v_cvt_pk_bf16_f32 v64, v68, v69
	v_cvt_pk_bf16_f32 v65, v70, v71
	v_cvt_pk_bf16_f32 v66, v72, v73
	v_cvt_pk_bf16_f32 v67, v74, v67
	global_store_dwordx4 v[76:77], v[64:67], off offset:256
	v_lshlrev_b64 v[72:73], 12, v[98:99]
	v_lshl_add_u64 v[72:73], s[4:5], 0, v[72:73]
	v_lshlrev_b64 v[64:65], 12, v[96:97]
	v_lshl_add_u64 v[64:65], s[4:5], 0, v[64:65]
	v_lshl_add_u64 v[68:69], v[64:65], 0, v[144:145]
	global_load_dwordx4 v[64:67], v[68:69], off
	s_nop 0
	global_load_dwordx4 v[68:71], v[68:69], off offset:256
	v_lshl_add_u64 v[76:77], v[72:73], 0, v[144:145]
	global_load_dwordx4 v[72:75], v[76:77], off
	s_nop 0
	global_load_dwordx4 v[76:79], v[76:77], off offset:256
	v_lshlrev_b64 v[80:81], 12, v[100:101]
	v_lshl_add_u64 v[80:81], s[4:5], 0, v[80:81]
	v_lshl_add_u64 v[84:85], v[80:81], 0, v[144:145]
	global_load_dwordx4 v[80:83], v[84:85], off
	s_nop 0
	global_load_dwordx4 v[84:87], v[84:85], off offset:256
	v_lshlrev_b64 v[88:89], 12, v[102:103]
	v_lshl_add_u64 v[88:89], s[4:5], 0, v[88:89]
	v_lshl_add_u64 v[92:93], v[88:89], 0, v[144:145]
	global_load_dwordx4 v[88:91], v[92:93], off
	s_nop 0
	global_load_dwordx4 v[92:95], v[92:93], off offset:256
	v_lshlrev_b64 v[96:97], 11, v[96:97]
	s_waitcnt vmcnt(7)
	v_lshlrev_b32_e32 v104, 16, v64
	v_and_b32_e32 v64, 0xffff0000, v64
	v_mul_f32_e32 v61, v61, v64
	v_lshlrev_b32_e32 v64, 16, v65
	v_mul_f32_e32 v62, v62, v64
	v_and_b32_e32 v64, 0xffff0000, v65
	v_mul_f32_e32 v63, v63, v64
	v_lshlrev_b32_e32 v64, 16, v66
	v_mul_f32_e32 v64, v56, v64
	v_and_b32_e32 v56, 0xffff0000, v66
	v_mul_f32_e32 v65, v57, v56
	v_lshlrev_b32_e32 v56, 16, v67
	v_mul_f32_e32 v60, v60, v104
	v_mul_f32_e32 v66, v58, v56
	v_and_b32_e32 v56, 0xffff0000, v67
	v_mul_f32_e32 v59, v59, v56
	v_cvt_pk_bf16_f32 v56, v60, v61
	v_lshl_add_u64 v[60:61], s[2:3], 0, v[96:97]
	v_lshl_add_u64 v[60:61], v[60:61], 0, v[144:145]
	v_cvt_pk_bf16_f32 v57, v62, v63
	v_cvt_pk_bf16_f32 v58, v64, v65
	v_cvt_pk_bf16_f32 v59, v66, v59
	global_store_dwordx4 v[60:61], v[56:59], off
	s_nop 1
	s_waitcnt vmcnt(7)
	v_lshlrev_b32_e32 v56, 16, v68
	v_mul_f32_e32 v52, v52, v56
	v_and_b32_e32 v56, 0xffff0000, v68
	v_mul_f32_e32 v53, v53, v56
	v_lshlrev_b32_e32 v56, 16, v69
	v_mul_f32_e32 v54, v54, v56
	v_and_b32_e32 v56, 0xffff0000, v69
	v_mul_f32_e32 v55, v55, v56
	v_lshlrev_b32_e32 v56, 16, v70
	v_mul_f32_e32 v56, v44, v56
	v_and_b32_e32 v44, 0xffff0000, v70
	v_mul_f32_e32 v57, v45, v44
	v_lshlrev_b32_e32 v44, 16, v71
	v_mul_f32_e32 v58, v46, v44
	v_and_b32_e32 v44, 0xffff0000, v71
	v_mul_f32_e32 v47, v47, v44
	v_cvt_pk_bf16_f32 v44, v52, v53
	v_cvt_pk_bf16_f32 v45, v54, v55
	v_cvt_pk_bf16_f32 v46, v56, v57
	v_cvt_pk_bf16_f32 v47, v58, v47
	global_store_dwordx4 v[60:61], v[44:47], off offset:256
	s_nop 1
	s_waitcnt vmcnt(7)
	v_lshlrev_b32_e32 v46, 16, v72
	v_mul_f32_e32 v46, v48, v46
	v_lshlrev_b32_e32 v48, 16, v73
	v_and_b32_e32 v47, 0xffff0000, v72
	v_mul_f32_e32 v48, v50, v48
	v_lshlrev_b32_e32 v50, 16, v74
	v_mul_f32_e32 v47, v49, v47
	v_and_b32_e32 v49, 0xffff0000, v73
	v_mul_f32_e32 v50, v40, v50
	v_and_b32_e32 v40, 0xffff0000, v74
	v_lshlrev_b64 v[44:45], 11, v[98:99]
	v_mul_f32_e32 v49, v51, v49
	v_mul_f32_e32 v51, v41, v40
	v_lshlrev_b32_e32 v40, 16, v75
	v_mul_f32_e32 v52, v42, v40
	v_and_b32_e32 v40, 0xffff0000, v75
	v_lshl_add_u64 v[44:45], s[2:3], 0, v[44:45]
	v_mul_f32_e32 v43, v43, v40
	v_cvt_pk_bf16_f32 v40, v46, v47
	v_lshl_add_u64 v[44:45], v[44:45], 0, v[144:145]
	v_cvt_pk_bf16_f32 v41, v48, v49
	v_cvt_pk_bf16_f32 v42, v50, v51
	v_cvt_pk_bf16_f32 v43, v52, v43
	global_store_dwordx4 v[44:45], v[40:43], off
	s_nop 1
	s_waitcnt vmcnt(7)
; __device__ __forceinline__ unsigned cvt_pk_bf16(float lo, float hi) { unsigned r; asm volatile("v_cvt_pk_bf16_f32 %0, %1, %2" : "=v"(r) : "v"(lo), "v"(hi)); return r; }
; __device__ __forceinline__ float bflo(unsigned u) { return __uint_as_float(u << 16); }
; __device__ __forceinline__ float bfhi(unsigned u) { return __uint_as_float(u & 0xffff0000u); }
;     __device__ __forceinline__ void operator()(const f32x4 (&acc)[2][2][4][2], const Unit& u, int wr, int wc, int fr, int fq) const {
;     ...
;         for (int ai = 0; ai < 2; ++ai) {
;             u32x4 gv[4][2], yv[4][2];
; #pragma unroll
;             for (int m = 0; m < 4; ++m)
; #pragma unroll
;                 for (int bj = 0; bj < 2; ++bj) {
;                     const int row = row0 + ai * 128 + m * 16, col = col0 + bj * 128;
;                     gv[m][bj] = *(const u32x4*)(gates + (size_t)row * 2048 + SECOND * 1024 + col);
;                     if (SECOND) yv[m][bj] = *(const u32x4*)(Y + (size_t)row * 1024 + col);
;                 }
; #pragma unroll
;             for (int m = 0; m < 4; ++m)
; #pragma unroll
;                 for (int bj = 0; bj < 2; ++bj) {
;                     const int row = row0 + ai * 128 + m * 16, col = col0 + bj * 128;
;                     const u32x4 g = gv[m][bj];
;                     const f32x4 a0 = acc[ai][bj][m][0], a1 = acc[ai][bj][m][1];
;                     float r[8] = {a0[0] * bflo(g.x), a0[1] * bfhi(g.x), a0[2] * bflo(g.y), a0[3] * bfhi(g.y), a1[0] * bflo(g.z), a1[1] * bfhi(g.z), a1[2] * bflo(g.w), a1[3] * bfhi(g.w)};
;                     if (SECOND) { const u32x4 y = yv[m][bj];
;                         r[0] += bflo(y.x); r[1] += bfhi(y.x); r[2] += bflo(y.y); r[3] += bfhi(y.y); r[4] += bflo(y.z); r[5] += bfhi(y.z); r[6] += bflo(y.w); r[7] += bfhi(y.w); }
;                     u32x4 w; w.x = cvt_pk_bf16(r[0], r[1]); w.y = cvt_pk_bf16(r[2], r[3]); w.z = cvt_pk_bf16(r[4], r[5]); w.w = cvt_pk_bf16(r[6], r[7]);
;                     *(u32x4*)(Y + (size_t)row * 1024 + col) = w;
	v_lshlrev_b32_e32 v40, 16, v76
	v_mul_f32_e32 v36, v36, v40
	v_and_b32_e32 v40, 0xffff0000, v76
	v_mul_f32_e32 v37, v37, v40
	v_lshlrev_b32_e32 v40, 16, v77
	v_mul_f32_e32 v38, v38, v40
	v_and_b32_e32 v40, 0xffff0000, v77
	v_mul_f32_e32 v39, v39, v40
	v_lshlrev_b32_e32 v40, 16, v78
	v_mul_f32_e32 v40, v28, v40
	v_and_b32_e32 v28, 0xffff0000, v78
	v_mul_f32_e32 v41, v29, v28
	v_lshlrev_b32_e32 v28, 16, v79
	v_mul_f32_e32 v42, v30, v28
	v_and_b32_e32 v28, 0xffff0000, v79
	v_mul_f32_e32 v31, v31, v28
	v_cvt_pk_bf16_f32 v28, v36, v37
	v_cvt_pk_bf16_f32 v29, v38, v39
	v_cvt_pk_bf16_f32 v30, v40, v41
	v_cvt_pk_bf16_f32 v31, v42, v31
	global_store_dwordx4 v[44:45], v[28:31], off offset:256
	s_nop 1
	s_waitcnt vmcnt(7)
	v_lshlrev_b32_e32 v30, 16, v80
	v_mul_f32_e32 v30, v32, v30
	v_lshlrev_b32_e32 v32, 16, v81
	v_and_b32_e32 v31, 0xffff0000, v80
	v_mul_f32_e32 v32, v34, v32
	v_lshlrev_b32_e32 v34, 16, v82
	v_mul_f32_e32 v31, v33, v31
	v_and_b32_e32 v33, 0xffff0000, v81
	v_mul_f32_e32 v34, v24, v34
	v_and_b32_e32 v24, 0xffff0000, v82
	v_lshlrev_b64 v[28:29], 11, v[100:101]
	v_mul_f32_e32 v33, v35, v33
	v_mul_f32_e32 v35, v25, v24
	v_lshlrev_b32_e32 v24, 16, v83
	v_mul_f32_e32 v36, v26, v24
	v_and_b32_e32 v24, 0xffff0000, v83
	v_lshl_add_u64 v[28:29], s[2:3], 0, v[28:29]
	v_mul_f32_e32 v27, v27, v24
	v_cvt_pk_bf16_f32 v24, v30, v31
	v_lshl_add_u64 v[28:29], v[28:29], 0, v[144:145]
	v_cvt_pk_bf16_f32 v25, v32, v33
	v_cvt_pk_bf16_f32 v26, v34, v35
	v_cvt_pk_bf16_f32 v27, v36, v27
	global_store_dwordx4 v[28:29], v[24:27], off
	s_nop 1
	s_waitcnt vmcnt(7)
	v_lshlrev_b32_e32 v24, 16, v84
	v_mul_f32_e32 v20, v20, v24
	v_and_b32_e32 v24, 0xffff0000, v84
	v_mul_f32_e32 v21, v21, v24
	v_lshlrev_b32_e32 v24, 16, v85
	v_mul_f32_e32 v22, v22, v24
	v_and_b32_e32 v24, 0xffff0000, v85
	v_mul_f32_e32 v23, v23, v24
	v_lshlrev_b32_e32 v24, 16, v86
	v_mul_f32_e32 v24, v12, v24
	v_and_b32_e32 v12, 0xffff0000, v86
	v_mul_f32_e32 v25, v13, v12
	v_lshlrev_b32_e32 v12, 16, v87
	v_mul_f32_e32 v26, v14, v12
	v_and_b32_e32 v12, 0xffff0000, v87
	v_mul_f32_e32 v15, v15, v12
	v_cvt_pk_bf16_f32 v12, v20, v21
	v_cvt_pk_bf16_f32 v13, v22, v23
	v_cvt_pk_bf16_f32 v14, v24, v25
	v_cvt_pk_bf16_f32 v15, v26, v15
	global_store_dwordx4 v[28:29], v[12:15], off offset:256
	s_nop 1
	s_waitcnt vmcnt(7)
	v_lshlrev_b32_e32 v14, 16, v88
	v_mul_f32_e32 v14, v16, v14
	v_lshlrev_b32_e32 v16, 16, v89
	v_and_b32_e32 v15, 0xffff0000, v88
	v_mul_f32_e32 v16, v18, v16
	v_lshlrev_b32_e32 v18, 16, v90
	v_mul_f32_e32 v15, v17, v15
	v_and_b32_e32 v17, 0xffff0000, v89
	v_mul_f32_e32 v18, v8, v18
	v_and_b32_e32 v8, 0xffff0000, v90
	v_lshlrev_b64 v[12:13], 11, v[102:103]
	v_mul_f32_e32 v17, v19, v17
	v_mul_f32_e32 v19, v9, v8
	v_lshlrev_b32_e32 v8, 16, v91
	v_mul_f32_e32 v20, v10, v8
	v_and_b32_e32 v8, 0xffff0000, v91
	v_lshl_add_u64 v[12:13], s[2:3], 0, v[12:13]
	v_mul_f32_e32 v11, v11, v8
	v_cvt_pk_bf16_f32 v8, v14, v15
	v_lshl_add_u64 v[12:13], v[12:13], 0, v[144:145]
	v_cvt_pk_bf16_f32 v9, v16, v17
	v_cvt_pk_bf16_f32 v10, v18, v19
	v_cvt_pk_bf16_f32 v11, v20, v11
	global_store_dwordx4 v[12:13], v[8:11], off
	s_nop 1
	s_waitcnt vmcnt(7)
	v_lshlrev_b32_e32 v8, 16, v92
	v_mul_f32_e32 v4, v4, v8
	v_and_b32_e32 v8, 0xffff0000, v92
	v_mul_f32_e32 v5, v5, v8
	v_lshlrev_b32_e32 v8, 16, v93
	v_mul_f32_e32 v6, v6, v8
	v_and_b32_e32 v8, 0xffff0000, v93
	v_mul_f32_e32 v7, v7, v8
	v_lshlrev_b32_e32 v8, 16, v94
	v_mul_f32_e32 v8, v0, v8
	v_and_b32_e32 v0, 0xffff0000, v94
	v_mul_f32_e32 v9, v1, v0
	v_lshlrev_b32_e32 v0, 16, v95
	v_mul_f32_e32 v10, v2, v0
	v_and_b32_e32 v0, 0xffff0000, v95
	v_mul_f32_e32 v3, v3, v0
	v_cvt_pk_bf16_f32 v0, v4, v5
	v_cvt_pk_bf16_f32 v1, v6, v7
	v_cvt_pk_bf16_f32 v2, v8, v9
	v_cvt_pk_bf16_f32 v3, v10, v3
	global_store_dwordx4 v[12:13], v[0:3], off offset:256
	s_cbranch_vccz .LBB0_570
	s_waitcnt vmcnt(0)
	s_cmpk_gt_u32 s26, 0xff
	s_cbranch_scc1 .LBB0_581
	s_barrier

; #define PG8_STAGE(bufoff, gbase, voff) do { _Pragma("unroll") for (int _i = 0; _i < 2; ++_i) \
;         __builtin_amdgcn_global_load_lds((const unsigned*)((const char*)(gbase) + (voff)[_i]), (LAS unsigned*)(lds + (bufoff) + ldsw + _i * 8192), 16, 0, 0); } while (0)
; #define PG8_LDA(dst, b, h) do { _Pragma("unroll") for (int m = 0; m < 4; ++m) _Pragma("unroll") for (int k = 0; k < 2; ++k) dst[m][k] = *(const LAS bf16x8*)(lds + PG8_SA(b, h) + aoff + m * 2048 + k * 1024); } while (0)
; #define PG8_WAIT_V(n) asm volatile("s_waitcnt vmcnt(" #n ")" ::: "memory")
; template <class Epi, class Sched>
; __device__ __forceinline__ void gemm_phase(const int wv, LAS unsigned char* lds, const Gemm g, const Sched& S, const Epi& E) {
;     ...
;         for (int t = 0; t < nt; t += 2) {
;             const bool last = (t == nt - 2);
;             const char* a1 = cA + (size_t)(t + 1) * kstepA;
;             const char* a2 = last ? nA : cA + (size_t)(t + 2) * kstepA; const char* b2 = last ? nB : cB + (size_t)(t + 2) * kstep;
;             const char* a3 = a2 + kstepA; const char* b3 = b2 + kstep;
;             if (last && has_next) S.a_ready(nxt);
;             PG8_LDB(B0, 0, 0); PG8_SCHED; PG8_LDA(At, 0, 0); PG8_STAGE(PG8_SA(1, 1), a1 + hstepA, voffA);
;             PG8_WAIT_L(8); PG8_BAR; PG8_WAIT_L(0); PG8_MMA(0, 0, At, B0); PG8_BAR; PG8_SCHED;
;             PG8_LDB(B1, 0, 1); PG8_STAGE(PG8_SB(0, 0), b2, voffB);
;             PG8_BAR; PG8_WAIT_L(0); PG8_MMA(0, 1, At, B1); PG8_BAR;
;             PG8_LDA(At, 0, 1); PG8_STAGE(PG8_SA(0, 0), a2, voffA);
;             PG8_BAR; PG8_WAIT_L(0); PG8_MMA(1, 0, At, B0); PG8_BAR; PG8_SCHED;
;             PG8_STAGE(PG8_SB(0, 1), b2 + hstepB, voffB);
;             PG8_WAIT_V(6); PG8_BAR; PG8_MMA(1, 1, At, B1); PG8_BAR;
;             PG8_LDB(B0, 1, 0); PG8_SCHED; PG8_LDA(At, 1, 0); PG8_STAGE(PG8_SA(0, 1), a2 + hstepA, voffA);
;             PG8_WAIT_L(8); PG8_BAR; PG8_WAIT_L(0); PG8_MMA(0, 0, At, B0); PG8_BAR; PG8_SCHED;
;             PG8_LDB(B1, 1, 1); PG8_STAGE(PG8_SB(1, 0), b3, voffB);
;             PG8_BAR; PG8_WAIT_L(0); PG8_MMA(0, 1, At, B1); PG8_BAR;
;             PG8_LDA(At, 1, 1); PG8_STAGE(PG8_SA(1, 0), a3, voffA);
;             PG8_BAR; PG8_WAIT_L(0); PG8_MMA(1, 0, At, B0); PG8_BAR; PG8_SCHED;
;             PG8_STAGE(PG8_SB(1, 1), b3 + hstepB, voffB);
;             PG8_WAIT_V(6); PG8_BAR; PG8_MMA(1, 1, At, B1); PG8_BAR;
.LBB0_597:
	ds_read_b128 v[128:131], v175
	ds_read_b128 v[132:135], v175 offset:1024
	ds_read_b128 v[136:139], v175 offset:2048
	ds_read_b128 v[140:143], v175 offset:3072
	s_add_u32 s20, s18, 0xfff80080
	s_addc_u32 s21, s19, -1
	s_cmp_eq_u32 s44, 28
	s_cselect_b32 s23, s11, s21
	s_cselect_b32 s22, s40, s20
	s_cselect_b32 s21, s9, s43
	s_cselect_b32 s20, s41, s42
	v_lshl_add_u64 v[200:201], s[18:19], 0, v[156:157]
	s_add_i32 m0, s17, 0xc000
	ds_read_b128 v[144:147], v176
	ds_read_b128 v[164:167], v176 offset:1024
	ds_read_b128 v[168:171], v176 offset:2048
	ds_read_b128 v[180:183], v176 offset:3072
	ds_read_b128 v[184:187], v176 offset:4096
	ds_read_b128 v[188:191], v176 offset:5120
	ds_read_b128 v[192:195], v176 offset:6144
	ds_read_b128 v[196:199], v176 offset:7168
	global_load_lds_dwordx4 v[200:201], off
	s_add_i32 m0, s17, 0xe000
	v_lshl_add_u64 v[200:201], s[18:19], 0, v[158:159]
	global_load_lds_dwordx4 v[200:201], off
	s_waitcnt lgkmcnt(8)
	s_barrier
	s_waitcnt lgkmcnt(0)
	v_mfma_f32_16x16x32_bf16 v[124:127], v[128:131], v[144:147], v[124:127]
	v_mfma_f32_16x16x32_bf16 v[120:123], v[136:139], v[144:147], v[120:123]
	v_mfma_f32_16x16x32_bf16 v[108:111], v[128:131], v[168:171], v[108:111]
	v_mfma_f32_16x16x32_bf16 v[104:107], v[136:139], v[168:171], v[104:107]
	v_mfma_f32_16x16x32_bf16 v[92:95], v[128:131], v[184:187], v[92:95]
	v_mfma_f32_16x16x32_bf16 v[88:91], v[136:139], v[184:187], v[88:91]
	v_mfma_f32_16x16x32_bf16 v[76:79], v[128:131], v[192:195], v[76:79]
	v_mfma_f32_16x16x32_bf16 v[72:75], v[136:139], v[192:195], v[72:75]
	v_mfma_f32_16x16x32_bf16 v[124:127], v[132:135], v[164:167], v[124:127]
	v_mfma_f32_16x16x32_bf16 v[120:123], v[140:143], v[164:167], v[120:123]
	v_mfma_f32_16x16x32_bf16 v[108:111], v[132:135], v[180:183], v[108:111]
	v_mfma_f32_16x16x32_bf16 v[104:107], v[140:143], v[180:183], v[104:107]
	v_mfma_f32_16x16x32_bf16 v[92:95], v[132:135], v[188:191], v[92:95]
	v_mfma_f32_16x16x32_bf16 v[88:91], v[140:143], v[188:191], v[88:91]
	v_mfma_f32_16x16x32_bf16 v[76:79], v[132:135], v[196:199], v[76:79]
	v_mfma_f32_16x16x32_bf16 v[72:75], v[140:143], v[196:199], v[72:75]
	s_barrier
	s_add_i32 s45, s37, s29
	v_lshl_add_u64 v[216:217], s[20:21], 0, v[150:151]
	s_mov_b32 m0, s45
	ds_read_b128 v[200:203], v177
	ds_read_b128 v[204:207], v177 offset:1024
	ds_read_b128 v[208:211], v177 offset:2048
	ds_read_b128 v[212:215], v177 offset:3072
	global_load_lds_dwordx4 v[216:217], off
	s_add_i32 m0, s45, 0x2000
	v_lshl_add_u64 v[218:219], s[20:21], 0, v[154:155]
	global_load_lds_dwordx4 v[218:219], off
	s_barrier
	s_waitcnt lgkmcnt(0)
	v_mfma_f32_16x16x32_bf16 v[116:119], v[200:203], v[144:147], v[116:119]
	v_mfma_f32_16x16x32_bf16 v[112:115], v[208:211], v[144:147], v[112:115]
	v_mfma_f32_16x16x32_bf16 v[100:103], v[200:203], v[168:171], v[100:103]
	v_mfma_f32_16x16x32_bf16 v[96:99], v[208:211], v[168:171], v[96:99]
	v_mfma_f32_16x16x32_bf16 v[84:87], v[200:203], v[184:187], v[84:87]
	v_mfma_f32_16x16x32_bf16 v[80:83], v[208:211], v[184:187], v[80:83]
	v_mfma_f32_16x16x32_bf16 v[68:71], v[200:203], v[192:195], v[68:71]
	v_mfma_f32_16x16x32_bf16 v[64:67], v[208:211], v[192:195], v[64:67]
	v_mfma_f32_16x16x32_bf16 v[116:119], v[204:207], v[164:167], v[116:119]
	v_mfma_f32_16x16x32_bf16 v[112:115], v[212:215], v[164:167], v[112:115]
	v_mfma_f32_16x16x32_bf16 v[100:103], v[204:207], v[180:183], v[100:103]
	v_mfma_f32_16x16x32_bf16 v[96:99], v[212:215], v[180:183], v[96:99]
	v_mfma_f32_16x16x32_bf16 v[84:87], v[204:207], v[188:191], v[84:87]
	v_mfma_f32_16x16x32_bf16 v[80:83], v[212:215], v[188:191], v[80:83]
	v_mfma_f32_16x16x32_bf16 v[68:71], v[204:207], v[196:199], v[68:71]
	v_mfma_f32_16x16x32_bf16 v[64:67], v[212:215], v[196:199], v[64:67]
	s_mov_b32 m0, s17
	v_lshl_add_u64 v[220:221], s[22:23], 0, v[148:149]
	s_barrier
	ds_read_b128 v[144:147], v176 offset:16384
	ds_read_b128 v[164:167], v176 offset:17408
	ds_read_b128 v[168:171], v176 offset:18432
	ds_read_b128 v[180:183], v176 offset:19456
	ds_read_b128 v[184:187], v176 offset:20480
	ds_read_b128 v[188:191], v176 offset:21504
	ds_read_b128 v[192:195], v176 offset:22528
	ds_read_b128 v[196:199], v176 offset:23552
	global_load_lds_dwordx4 v[220:221], off
	s_mov_b32 m0, s30
	v_lshl_add_u64 v[222:223], s[22:23], 0, v[152:153]
	global_load_lds_dwordx4 v[222:223], off
	s_barrier
	s_waitcnt lgkmcnt(0)
	v_mfma_f32_16x16x32_bf16 v[60:63], v[128:131], v[144:147], v[60:63]
	v_mfma_f32_16x16x32_bf16 v[56:59], v[136:139], v[144:147], v[56:59]
	v_mfma_f32_16x16x32_bf16 v[44:47], v[128:131], v[168:171], v[44:47]
	v_mfma_f32_16x16x32_bf16 v[40:43], v[136:139], v[168:171], v[40:43]
	v_mfma_f32_16x16x32_bf16 v[28:31], v[128:131], v[184:187], v[28:31]
	v_mfma_f32_16x16x32_bf16 v[24:27], v[136:139], v[184:187], v[24:27]
	v_mfma_f32_16x16x32_bf16 v[12:15], v[128:131], v[192:195], v[12:15]
	v_mfma_f32_16x16x32_bf16 v[8:11], v[136:139], v[192:195], v[8:11]
	v_mfma_f32_16x16x32_bf16 v[60:63], v[132:135], v[164:167], v[60:63]
	v_mfma_f32_16x16x32_bf16 v[56:59], v[140:143], v[164:167], v[56:59]
	v_mfma_f32_16x16x32_bf16 v[44:47], v[132:135], v[180:183], v[44:47]
	v_mfma_f32_16x16x32_bf16 v[40:43], v[140:143], v[180:183], v[40:43]
	v_mfma_f32_16x16x32_bf16 v[28:31], v[132:135], v[188:191], v[28:31]
	v_mfma_f32_16x16x32_bf16 v[24:27], v[140:143], v[188:191], v[24:27]
	v_mfma_f32_16x16x32_bf16 v[12:15], v[132:135], v[196:199], v[12:15]
	v_mfma_f32_16x16x32_bf16 v[8:11], v[140:143], v[196:199], v[8:11]
	s_barrier
	s_add_u32 s46, s20, 0x80000
	s_addc_u32 s47, s21, 0
	s_add_i32 s45, s38, s29
	s_mov_b32 m0, s45
	v_lshl_add_u64 v[128:129], s[46:47], 0, v[150:151]
	global_load_lds_dwordx4 v[128:129], off
	s_add_i32 m0, s45, 0x2000
	v_lshl_add_u64 v[128:129], s[46:47], 0, v[154:155]
	global_load_lds_dwordx4 v[128:129], off
	s_waitcnt vmcnt(6)
	s_barrier
; #define PG8_STAGE(bufoff, gbase, voff) do { _Pragma("unroll") for (int _i = 0; _i < 2; ++_i) \
;         __builtin_amdgcn_global_load_lds((const unsigned*)((const char*)(gbase) + (voff)[_i]), (LAS unsigned*)(lds + (bufoff) + ldsw + _i * 8192), 16, 0, 0); } while (0)
; #define PG8_LDA(dst, b, h) do { _Pragma("unroll") for (int m = 0; m < 4; ++m) _Pragma("unroll") for (int k = 0; k < 2; ++k) dst[m][k] = *(const LAS bf16x8*)(lds + PG8_SA(b, h) + aoff + m * 2048 + k * 1024); } while (0)
; #define PG8_LDB(dst, b, h) do { _Pragma("unroll") for (int n = 0; n < 2; ++n) _Pragma("unroll") for (int k = 0; k < 2; ++k) dst[n][k] = *(const LAS bf16x8*)(lds + PG8_SB(b, h) + boff + n * 2048 + k * 1024); } while (0)
; #define PG8_WAIT_V(n) asm volatile("s_waitcnt vmcnt(" #n ")" ::: "memory")
; #define PG8_WAIT_L(n) asm volatile("s_waitcnt lgkmcnt(" #n ")" ::: "memory")
; #define PG8_BAR __builtin_amdgcn_s_barrier()
; #define PG8_SCHED __builtin_amdgcn_sched_barrier(0)
; template <class Epi, class Sched>
; __device__ __forceinline__ void gemm_phase(const int wv, LAS unsigned char* lds, const Gemm g, const Sched& S, const Epi& E) {
;     ...
;             PG8_LDB(B0, 0, 0); PG8_SCHED; PG8_LDA(At, 0, 0); PG8_STAGE(PG8_SA(1, 1), a1 + hstepA, voffA);
;             PG8_WAIT_L(8); PG8_BAR; PG8_WAIT_L(0); PG8_MMA(0, 0, At, B0); PG8_BAR; PG8_SCHED;
;             PG8_LDB(B1, 0, 1); PG8_STAGE(PG8_SB(0, 0), b2, voffB);
;             PG8_BAR; PG8_WAIT_L(0); PG8_MMA(0, 1, At, B1); PG8_BAR;
;             PG8_LDA(At, 0, 1); PG8_STAGE(PG8_SA(0, 0), a2, voffA);
;             PG8_BAR; PG8_WAIT_L(0); PG8_MMA(1, 0, At, B0); PG8_BAR; PG8_SCHED;
;             PG8_STAGE(PG8_SB(0, 1), b2 + hstepB, voffB);
;             PG8_WAIT_V(6); PG8_BAR; PG8_MMA(1, 1, At, B1); PG8_BAR;
;             PG8_LDB(B0, 1, 0); PG8_SCHED; PG8_LDA(At, 1, 0); PG8_STAGE(PG8_SA(0, 1), a2 + hstepA, voffA);
;             PG8_WAIT_L(8); PG8_BAR; PG8_WAIT_L(0); PG8_MMA(0, 0, At, B0); PG8_BAR; PG8_SCHED;
;             PG8_LDB(B1, 1, 1); PG8_STAGE(PG8_SB(1, 0), b3, voffB);
;             PG8_BAR; PG8_WAIT_L(0); PG8_MMA(0, 1, At, B1); PG8_BAR;
;             PG8_LDA(At, 1, 1); PG8_STAGE(PG8_SA(1, 0), a3, voffA);
;             PG8_BAR; PG8_WAIT_L(0); PG8_MMA(1, 0, At, B0); PG8_BAR; PG8_SCHED;
;             PG8_STAGE(PG8_SB(1, 1), b3 + hstepB, voffB);
;             PG8_WAIT_V(6); PG8_BAR; PG8_MMA(1, 1, At, B1); PG8_BAR;
	v_mfma_f32_16x16x32_bf16 v[52:55], v[200:203], v[144:147], v[52:55]
	v_mfma_f32_16x16x32_bf16 v[48:51], v[208:211], v[144:147], v[48:51]
	v_mfma_f32_16x16x32_bf16 v[36:39], v[200:203], v[168:171], v[36:39]
	v_mfma_f32_16x16x32_bf16 v[32:35], v[208:211], v[168:171], v[32:35]
	v_mfma_f32_16x16x32_bf16 v[20:23], v[200:203], v[184:187], v[20:23]
	v_mfma_f32_16x16x32_bf16 v[16:19], v[208:211], v[184:187], v[16:19]
	v_mfma_f32_16x16x32_bf16 v[4:7], v[200:203], v[192:195], v[4:7]
	v_mfma_f32_16x16x32_bf16 v[0:3], v[208:211], v[192:195], v[0:3]
	v_mfma_f32_16x16x32_bf16 v[52:55], v[204:207], v[164:167], v[52:55]
	v_mfma_f32_16x16x32_bf16 v[48:51], v[212:215], v[164:167], v[48:51]
	v_mfma_f32_16x16x32_bf16 v[36:39], v[204:207], v[180:183], v[36:39]
	v_mfma_f32_16x16x32_bf16 v[32:35], v[212:215], v[180:183], v[32:35]
	v_mfma_f32_16x16x32_bf16 v[20:23], v[204:207], v[188:191], v[20:23]
	v_mfma_f32_16x16x32_bf16 v[16:19], v[212:215], v[188:191], v[16:19]
	v_mfma_f32_16x16x32_bf16 v[4:7], v[204:207], v[196:199], v[4:7]
	v_mfma_f32_16x16x32_bf16 v[0:3], v[212:215], v[196:199], v[0:3]
	s_add_i32 s45, 0, 0x18000
	v_add_u32_e32 v140, s45, v173
	s_barrier
	ds_read_b128 v[128:131], v140
	ds_read_b128 v[132:135], v140 offset:1024
	ds_read_b128 v[136:139], v140 offset:2048
	ds_read_b128 v[140:143], v140 offset:3072
	s_add_u32 s22, s22, 0x80000
	s_addc_u32 s23, s23, 0
	s_mov_b32 m0, s31
	v_lshl_add_u64 v[200:201], s[22:23], 0, v[148:149]
	ds_read_b128 v[144:147], v176 offset:32768
	ds_read_b128 v[164:167], v176 offset:33792
	ds_read_b128 v[168:171], v176 offset:34816
	ds_read_b128 v[180:183], v176 offset:35840
	ds_read_b128 v[184:187], v176 offset:36864
	ds_read_b128 v[188:191], v176 offset:37888
	ds_read_b128 v[192:195], v176 offset:38912
	ds_read_b128 v[196:199], v176 offset:39936
	global_load_lds_dwordx4 v[200:201], off
	s_mov_b32 m0, s33
	v_lshl_add_u64 v[200:201], s[22:23], 0, v[152:153]
	global_load_lds_dwordx4 v[200:201], off
	s_waitcnt lgkmcnt(8)
	s_barrier
	s_waitcnt lgkmcnt(0)
	v_mfma_f32_16x16x32_bf16 v[124:127], v[128:131], v[144:147], v[124:127]
	v_mfma_f32_16x16x32_bf16 v[120:123], v[136:139], v[144:147], v[120:123]
	v_mfma_f32_16x16x32_bf16 v[108:111], v[128:131], v[168:171], v[108:111]
	v_mfma_f32_16x16x32_bf16 v[104:107], v[136:139], v[168:171], v[104:107]
	v_mfma_f32_16x16x32_bf16 v[92:95], v[128:131], v[184:187], v[92:95]
	v_mfma_f32_16x16x32_bf16 v[88:91], v[136:139], v[184:187], v[88:91]
	v_mfma_f32_16x16x32_bf16 v[76:79], v[128:131], v[192:195], v[76:79]
	v_mfma_f32_16x16x32_bf16 v[72:75], v[136:139], v[192:195], v[72:75]
	v_mfma_f32_16x16x32_bf16 v[124:127], v[132:135], v[164:167], v[124:127]
	v_mfma_f32_16x16x32_bf16 v[120:123], v[140:143], v[164:167], v[120:123]
	v_mfma_f32_16x16x32_bf16 v[108:111], v[132:135], v[180:183], v[108:111]
	v_mfma_f32_16x16x32_bf16 v[104:107], v[140:143], v[180:183], v[104:107]
	v_mfma_f32_16x16x32_bf16 v[92:95], v[132:135], v[188:191], v[92:95]
	v_mfma_f32_16x16x32_bf16 v[88:91], v[140:143], v[188:191], v[88:91]
	v_mfma_f32_16x16x32_bf16 v[76:79], v[132:135], v[196:199], v[76:79]
	v_mfma_f32_16x16x32_bf16 v[72:75], v[140:143], v[196:199], v[72:75]
	s_barrier
	s_add_i32 s22, 0, 0x1c000
	s_add_i32 s23, s45, s29
	v_add_u32_e32 v212, s22, v173
	v_lshl_add_u64 v[216:217], v[216:217], 0, s[6:7]
	s_mov_b32 m0, s23
	ds_read_b128 v[200:203], v212
	ds_read_b128 v[204:207], v212 offset:1024
	ds_read_b128 v[208:211], v212 offset:2048
	ds_read_b128 v[212:215], v212 offset:3072
	global_load_lds_dwordx4 v[216:217], off
	s_add_i32 m0, s23, 0x2000
	v_lshl_add_u64 v[216:217], v[218:219], 0, s[6:7]
	global_load_lds_dwordx4 v[216:217], off
	s_barrier
	s_waitcnt lgkmcnt(0)
	v_mfma_f32_16x16x32_bf16 v[116:119], v[200:203], v[144:147], v[116:119]
	v_mfma_f32_16x16x32_bf16 v[112:115], v[208:211], v[144:147], v[112:115]
	v_mfma_f32_16x16x32_bf16 v[100:103], v[200:203], v[168:171], v[100:103]
	v_mfma_f32_16x16x32_bf16 v[96:99], v[208:211], v[168:171], v[96:99]
	v_mfma_f32_16x16x32_bf16 v[84:87], v[200:203], v[184:187], v[84:87]
	v_mfma_f32_16x16x32_bf16 v[80:83], v[208:211], v[184:187], v[80:83]
	v_mfma_f32_16x16x32_bf16 v[68:71], v[200:203], v[192:195], v[68:71]
	v_mfma_f32_16x16x32_bf16 v[64:67], v[208:211], v[192:195], v[64:67]
	v_mfma_f32_16x16x32_bf16 v[116:119], v[204:207], v[164:167], v[116:119]
	v_mfma_f32_16x16x32_bf16 v[112:115], v[212:215], v[164:167], v[112:115]
	v_mfma_f32_16x16x32_bf16 v[100:103], v[204:207], v[180:183], v[100:103]
	v_mfma_f32_16x16x32_bf16 v[96:99], v[212:215], v[180:183], v[96:99]
	v_mfma_f32_16x16x32_bf16 v[84:87], v[204:207], v[188:191], v[84:87]
	v_mfma_f32_16x16x32_bf16 v[80:83], v[212:215], v[188:191], v[80:83]
	v_mfma_f32_16x16x32_bf16 v[68:71], v[204:207], v[196:199], v[68:71]
	v_mfma_f32_16x16x32_bf16 v[64:67], v[212:215], v[196:199], v[64:67]
	s_mov_b32 m0, s35
	v_lshl_add_u64 v[216:217], v[220:221], 0, s[6:7]
	s_barrier
	ds_read_b128 v[144:147], v176 offset:49152
	ds_read_b128 v[164:167], v176 offset:50176
	ds_read_b128 v[168:171], v176 offset:51200
	ds_read_b128 v[180:183], v176 offset:52224
	ds_read_b128 v[184:187], v176 offset:53248
	ds_read_b128 v[188:191], v176 offset:54272
	ds_read_b128 v[192:195], v176 offset:55296
	ds_read_b128 v[196:199], v176 offset:56320
	global_load_lds_dwordx4 v[216:217], off
	s_mov_b32 m0, s36
	v_lshl_add_u64 v[216:217], v[222:223], 0, s[6:7]
	global_load_lds_dwordx4 v[216:217], off
	s_barrier
; #define PG8_WAIT_V(n) asm volatile("s_waitcnt vmcnt(" #n ")" ::: "memory")
; #define PG8_WAIT_L(n) asm volatile("s_waitcnt lgkmcnt(" #n ")" ::: "memory")
; #define PG8_BAR __builtin_amdgcn_s_barrier()
; template <class Epi, class Sched>
; __device__ __forceinline__ void gemm_phase(const int wv, LAS unsigned char* lds, const Gemm g, const Sched& S, const Epi& E) {
;     ...
;             PG8_LDB(B0, 0, 0); PG8_SCHED; PG8_LDA(At, 0, 0); PG8_STAGE(PG8_SA(1, 1), a1 + hstepA, voffA);
;             PG8_WAIT_L(8); PG8_BAR; PG8_WAIT_L(0); PG8_MMA(0, 0, At, B0); PG8_BAR; PG8_SCHED;
;             PG8_LDB(B1, 0, 1); PG8_STAGE(PG8_SB(0, 0), b2, voffB);
;             PG8_BAR; PG8_WAIT_L(0); PG8_MMA(0, 1, At, B1); PG8_BAR;
;             PG8_LDA(At, 0, 1); PG8_STAGE(PG8_SA(0, 0), a2, voffA);
;             PG8_BAR; PG8_WAIT_L(0); PG8_MMA(1, 0, At, B0); PG8_BAR; PG8_SCHED;
;             PG8_STAGE(PG8_SB(0, 1), b2 + hstepB, voffB);
;             PG8_WAIT_V(6); PG8_BAR; PG8_MMA(1, 1, At, B1); PG8_BAR;
;             PG8_LDB(B0, 1, 0); PG8_SCHED; PG8_LDA(At, 1, 0); PG8_STAGE(PG8_SA(0, 1), a2 + hstepA, voffA);
;             PG8_WAIT_L(8); PG8_BAR; PG8_WAIT_L(0); PG8_MMA(0, 0, At, B0); PG8_BAR; PG8_SCHED;
;             PG8_LDB(B1, 1, 1); PG8_STAGE(PG8_SB(1, 0), b3, voffB);
;             PG8_BAR; PG8_WAIT_L(0); PG8_MMA(0, 1, At, B1); PG8_BAR;
;             PG8_LDA(At, 1, 1); PG8_STAGE(PG8_SA(1, 0), a3, voffA);
;             PG8_BAR; PG8_WAIT_L(0); PG8_MMA(1, 0, At, B0); PG8_BAR; PG8_SCHED;
;             PG8_STAGE(PG8_SB(1, 1), b3 + hstepB, voffB);
;             PG8_WAIT_V(6); PG8_BAR; PG8_MMA(1, 1, At, B1); PG8_BAR;
;         }
;     __device__ __forceinline__ void operator()(const f32x4 (&acc)[2][2][4][2], const Unit& u, int wr, int wc, int fr, int fq) const {
;         const int row0 = u.pm * 256 + wr * 64 + fr; const int col0 = u.pn * 256 + wc * 32 + 8 * fq;
; #pragma unroll
;         for (int ai = 0; ai < 2; ++ai) {
;             u32x4 gv[4][2], yv[4][2];
; #pragma unroll
;             for (int m = 0; m < 4; ++m)
; #pragma unroll
;                 for (int bj = 0; bj < 2; ++bj) {
;                     const int row = row0 + ai * 128 + m * 16, col = col0 + bj * 128;
;                     gv[m][bj] = *(const u32x4*)(gates + (size_t)row * 2048 + SECOND * 1024 + col);
;                     if (SECOND) yv[m][bj] = *(const u32x4*)(Y + (size_t)row * 1024 + col);
;                 }
	s_waitcnt lgkmcnt(0)
	v_mfma_f32_16x16x32_bf16 v[60:63], v[128:131], v[144:147], v[60:63]
	v_mfma_f32_16x16x32_bf16 v[56:59], v[136:139], v[144:147], v[56:59]
	v_mfma_f32_16x16x32_bf16 v[44:47], v[128:131], v[168:171], v[44:47]
	v_mfma_f32_16x16x32_bf16 v[40:43], v[136:139], v[168:171], v[40:43]
	v_mfma_f32_16x16x32_bf16 v[28:31], v[128:131], v[184:187], v[28:31]
	v_mfma_f32_16x16x32_bf16 v[24:27], v[136:139], v[184:187], v[24:27]
	v_mfma_f32_16x16x32_bf16 v[12:15], v[128:131], v[192:195], v[12:15]
	v_mfma_f32_16x16x32_bf16 v[8:11], v[136:139], v[192:195], v[8:11]
	v_mfma_f32_16x16x32_bf16 v[60:63], v[132:135], v[164:167], v[60:63]
	v_mfma_f32_16x16x32_bf16 v[56:59], v[140:143], v[164:167], v[56:59]
	v_mfma_f32_16x16x32_bf16 v[44:47], v[132:135], v[180:183], v[44:47]
	v_mfma_f32_16x16x32_bf16 v[40:43], v[140:143], v[180:183], v[40:43]
	v_mfma_f32_16x16x32_bf16 v[28:31], v[132:135], v[188:191], v[28:31]
	v_mfma_f32_16x16x32_bf16 v[24:27], v[140:143], v[188:191], v[24:27]
	v_mfma_f32_16x16x32_bf16 v[12:15], v[132:135], v[196:199], v[12:15]
	v_mfma_f32_16x16x32_bf16 v[8:11], v[140:143], v[196:199], v[8:11]
	s_barrier
	s_add_u32 s20, s20, 0x80080
	s_addc_u32 s21, s21, 0
	s_add_i32 s22, s22, s29
	s_mov_b32 m0, s22
	v_lshl_add_u64 v[128:129], s[20:21], 0, v[150:151]
	global_load_lds_dwordx4 v[128:129], off
	s_add_i32 m0, s22, 0x2000
	v_lshl_add_u64 v[128:129], s[20:21], 0, v[154:155]
	global_load_lds_dwordx4 v[128:129], off
	s_waitcnt vmcnt(6)
	s_barrier
	v_mfma_f32_16x16x32_bf16 v[52:55], v[200:203], v[144:147], v[52:55]
	v_mfma_f32_16x16x32_bf16 v[48:51], v[208:211], v[144:147], v[48:51]
	v_mfma_f32_16x16x32_bf16 v[36:39], v[200:203], v[168:171], v[36:39]
	v_mfma_f32_16x16x32_bf16 v[32:35], v[208:211], v[168:171], v[32:35]
	v_mfma_f32_16x16x32_bf16 v[20:23], v[200:203], v[184:187], v[20:23]
	v_mfma_f32_16x16x32_bf16 v[16:19], v[208:211], v[184:187], v[16:19]
	v_mfma_f32_16x16x32_bf16 v[4:7], v[200:203], v[192:195], v[4:7]
	v_mfma_f32_16x16x32_bf16 v[0:3], v[208:211], v[192:195], v[0:3]
	v_mfma_f32_16x16x32_bf16 v[52:55], v[204:207], v[164:167], v[52:55]
	v_mfma_f32_16x16x32_bf16 v[48:51], v[212:215], v[164:167], v[48:51]
	v_mfma_f32_16x16x32_bf16 v[36:39], v[204:207], v[180:183], v[36:39]
	v_mfma_f32_16x16x32_bf16 v[32:35], v[212:215], v[180:183], v[32:35]
	v_mfma_f32_16x16x32_bf16 v[20:23], v[204:207], v[188:191], v[20:23]
	v_mfma_f32_16x16x32_bf16 v[16:19], v[212:215], v[188:191], v[16:19]
	v_mfma_f32_16x16x32_bf16 v[4:7], v[204:207], v[196:199], v[4:7]
	v_mfma_f32_16x16x32_bf16 v[0:3], v[212:215], v[196:199], v[0:3]
	s_add_i32 s44, s44, 2
	s_add_u32 s18, s18, 0x100
	s_addc_u32 s19, s19, 0
	s_add_u32 s42, s42, 0x100
	s_addc_u32 s43, s43, 0
	s_cmp_gt_u32 s44, 29
	s_barrier
	s_cbranch_scc0 .LBB0_597
	v_lshl_add_u32 v164, s16, 8, v172
	v_lshl_or_b32 v128, s39, 8, v174
	v_ashrrev_i32_e32 v165, 31, v164
	v_ashrrev_i32_e32 v129, 31, v128
	v_lshlrev_b64 v[130:131], 12, v[164:165]
	v_lshl_add_u64 v[130:131], s[4:5], 0, v[130:131]
	v_lshlrev_b64 v[166:167], 1, v[128:129]
	v_lshl_add_u64 v[128:129], v[130:131], 0, v[166:167]
	v_lshlrev_b64 v[130:131], 11, v[164:165]
	v_lshl_add_u64 v[130:131], s[2:3], 0, v[130:131]
	v_lshl_add_u64 v[224:225], v[130:131], 0, v[166:167]
	global_load_dwordx4 v[180:183], v[128:129], off offset:2048
	global_load_dwordx4 v[184:187], v[224:225], off
	global_load_dwordx4 v[188:191], v[128:129], off offset:2304
	global_load_dwordx4 v[192:195], v[224:225], off offset:256
	v_or_b32_e32 v128, 16, v164
	v_ashrrev_i32_e32 v129, 31, v128
	v_lshlrev_b64 v[134:135], 12, v[128:129]
	v_lshlrev_b64 v[128:129], 11, v[128:129]
	v_lshl_add_u64 v[134:135], s[4:5], 0, v[134:135]
	v_lshl_add_u64 v[128:129], s[2:3], 0, v[128:129]
	v_lshl_add_u64 v[134:135], v[134:135], 0, v[166:167]
	v_lshl_add_u64 v[226:227], v[128:129], 0, v[166:167]
	global_load_dwordx4 v[196:199], v[134:135], off offset:2048
	global_load_dwordx4 v[200:203], v[226:227], off
	v_or_b32_e32 v130, 32, v164
	v_or_b32_e32 v132, 48, v164
	v_ashrrev_i32_e32 v131, 31, v130
	v_ashrrev_i32_e32 v133, 31, v132
	v_lshlrev_b64 v[136:137], 12, v[130:131]
	v_lshlrev_b64 v[130:131], 11, v[130:131]
	v_lshlrev_b64 v[138:139], 12, v[132:133]
	v_lshlrev_b64 v[132:133], 11, v[132:133]
	v_lshl_add_u64 v[136:137], s[4:5], 0, v[136:137]
	v_lshl_add_u64 v[130:131], s[2:3], 0, v[130:131]
	v_lshl_add_u64 v[138:139], s[4:5], 0, v[138:139]
	v_lshl_add_u64 v[132:133], s[2:3], 0, v[132:133]
	v_lshl_add_u64 v[128:129], v[136:137], 0, v[166:167]
	v_lshl_add_u64 v[170:171], v[130:131], 0, v[166:167]
	v_lshl_add_u64 v[130:131], v[138:139], 0, v[166:167]
	v_lshl_add_u64 v[168:169], v[132:133], 0, v[166:167]
	global_load_dwordx4 v[204:207], v[134:135], off offset:2304
	global_load_dwordx4 v[208:211], v[226:227], off offset:256
	global_load_dwordx4 v[212:215], v[128:129], off offset:2048
	global_load_dwordx4 v[216:219], v[128:129], off offset:2304
	global_load_dwordx4 v[220:223], v[170:171], off
	global_load_dwordx4 v[144:147], v[170:171], off offset:256
	global_load_dwordx4 v[140:143], v[130:131], off offset:2048
	global_load_dwordx4 v[132:135], v[130:131], off offset:2304
	global_load_dwordx4 v[136:139], v[168:169], off
	s_nop 0
	global_load_dwordx4 v[128:131], v[168:169], off offset:256
	s_and_b64 vcc, exec, s[0:1]
	s_mov_b32 s39, s8
	s_mov_b32 s16, s10
	s_mov_b64 s[20:21], s[14:15]
	s_mov_b64 s[18:19], s[12:13]
	s_waitcnt vmcnt(14)
	v_lshlrev_b32_e32 v231, 16, v184
	s_waitcnt vmcnt(13)
	v_lshlrev_b32_e32 v235, 16, v188
	s_waitcnt vmcnt(12)
; __device__ __forceinline__ unsigned cvt_pk_bf16(float lo, float hi) { unsigned r; asm volatile("v_cvt_pk_bf16_f32 %0, %1, %2" : "=v"(r) : "v"(lo), "v"(hi)); return r; }
; __device__ __forceinline__ float bflo(unsigned u) { return __uint_as_float(u << 16); }
; __device__ __forceinline__ float bfhi(unsigned u) { return __uint_as_float(u & 0xffff0000u); }
;     __device__ __forceinline__ void operator()(const f32x4 (&acc)[2][2][4][2], const Unit& u, int wr, int wc, int fr, int fq) const {
;     ...
; #pragma unroll
;             for (int m = 0; m < 4; ++m)
; #pragma unroll
;                 for (int bj = 0; bj < 2; ++bj) {
;                     const int row = row0 + ai * 128 + m * 16, col = col0 + bj * 128;
;                     const u32x4 g = gv[m][bj];
;                     const f32x4 a0 = acc[ai][bj][m][0], a1 = acc[ai][bj][m][1];
;                     float r[8] = {a0[0] * bflo(g.x), a0[1] * bfhi(g.x), a0[2] * bflo(g.y), a0[3] * bfhi(g.y), a1[0] * bflo(g.z), a1[1] * bfhi(g.z), a1[2] * bflo(g.w), a1[3] * bfhi(g.w)};
;                     if (SECOND) { const u32x4 y = yv[m][bj];
;                         r[0] += bflo(y.x); r[1] += bfhi(y.x); r[2] += bflo(y.y); r[3] += bfhi(y.y); r[4] += bflo(y.z); r[5] += bfhi(y.z); r[6] += bflo(y.w); r[7] += bfhi(y.w); }
;                     u32x4 w; w.x = cvt_pk_bf16(r[0], r[1]); w.y = cvt_pk_bf16(r[2], r[3]); w.z = cvt_pk_bf16(r[4], r[5]); w.w = cvt_pk_bf16(r[6], r[7]);
;                     *(u32x4*)(Y + (size_t)row * 1024 + col) = w;
	v_lshlrev_b32_e32 v239, 16, v192
	v_and_b32_e32 v188, 0xffff0000, v188
	v_fmac_f32_e32 v239, v116, v235
	v_and_b32_e32 v116, 0xffff0000, v192
	v_lshlrev_b32_e32 v165, 16, v180
	v_and_b32_e32 v180, 0xffff0000, v180
	v_lshlrev_b32_e32 v229, 16, v182
	v_and_b32_e32 v184, 0xffff0000, v184
	v_lshlrev_b32_e32 v233, 16, v186
	v_lshlrev_b32_e32 v236, 16, v189
	v_fmac_f32_e32 v116, v117, v188
	v_lshlrev_b32_e32 v117, 16, v193
	v_lshlrev_b32_e32 v228, 16, v181
	v_and_b32_e32 v181, 0xffff0000, v181
	v_and_b32_e32 v182, 0xffff0000, v182
	v_lshlrev_b32_e32 v230, 16, v183
	v_and_b32_e32 v183, 0xffff0000, v183
	v_lshlrev_b32_e32 v232, 16, v185
	v_and_b32_e32 v185, 0xffff0000, v185
	v_and_b32_e32 v186, 0xffff0000, v186
	v_lshlrev_b32_e32 v234, 16, v187
	v_and_b32_e32 v187, 0xffff0000, v187
	v_and_b32_e32 v189, 0xffff0000, v189
	v_fmac_f32_e32 v231, v124, v165
	v_fmac_f32_e32 v184, v125, v180
	v_fmac_f32_e32 v233, v120, v229
	v_cvt_pk_bf16_f32 v120, v231, v184
	v_fmac_f32_e32 v117, v118, v236
	v_and_b32_e32 v118, 0xffff0000, v193
	v_lshlrev_b32_e32 v237, 16, v190
	v_and_b32_e32 v190, 0xffff0000, v190
	v_fmac_f32_e32 v232, v126, v228
	v_fmac_f32_e32 v185, v127, v181
	v_fmac_f32_e32 v186, v121, v182
	v_fmac_f32_e32 v234, v122, v230
	v_fmac_f32_e32 v187, v123, v183
	v_cvt_pk_bf16_f32 v121, v232, v185
	v_cvt_pk_bf16_f32 v122, v233, v186
	v_cvt_pk_bf16_f32 v123, v234, v187
	global_store_dwordx4 v[224:225], v[120:123], off
	v_fmac_f32_e32 v118, v119, v189
	v_lshlrev_b32_e32 v119, 16, v194
	v_and_b32_e32 v120, 0xffff0000, v194
	v_lshlrev_b32_e32 v238, 16, v191
	v_and_b32_e32 v191, 0xffff0000, v191
	v_fmac_f32_e32 v119, v112, v237
	v_fmac_f32_e32 v120, v113, v190
	v_lshlrev_b32_e32 v121, 16, v195
	v_and_b32_e32 v122, 0xffff0000, v195
	v_cvt_pk_bf16_f32 v112, v239, v116
	v_fmac_f32_e32 v121, v114, v238
	v_fmac_f32_e32 v122, v115, v191
	v_cvt_pk_bf16_f32 v113, v117, v118
	v_cvt_pk_bf16_f32 v114, v119, v120
	v_cvt_pk_bf16_f32 v115, v121, v122
	global_store_dwordx4 v[224:225], v[112:115], off offset:256
	s_waitcnt vmcnt(12)
	v_lshlrev_b32_e32 v120, 16, v200
	v_lshlrev_b32_e32 v116, 16, v198
	v_lshlrev_b32_e32 v112, 16, v196
	v_and_b32_e32 v113, 0xffff0000, v196
	v_fmac_f32_e32 v120, v108, v112
	v_and_b32_e32 v108, 0xffff0000, v200
	v_lshlrev_b32_e32 v114, 16, v197
	v_fmac_f32_e32 v108, v109, v113
	v_lshlrev_b32_e32 v109, 16, v201
	v_and_b32_e32 v115, 0xffff0000, v197
	v_fmac_f32_e32 v109, v110, v114
	v_and_b32_e32 v110, 0xffff0000, v201
	v_and_b32_e32 v117, 0xffff0000, v198
	v_fmac_f32_e32 v110, v111, v115
	v_lshlrev_b32_e32 v111, 16, v202
	v_and_b32_e32 v112, 0xffff0000, v202
	v_lshlrev_b32_e32 v118, 16, v199
	v_and_b32_e32 v119, 0xffff0000, v199
	v_fmac_f32_e32 v111, v104, v116
	v_fmac_f32_e32 v112, v105, v117
	v_lshlrev_b32_e32 v113, 16, v203
	v_and_b32_e32 v114, 0xffff0000, v203
	v_cvt_pk_bf16_f32 v104, v120, v108
	v_fmac_f32_e32 v113, v106, v118
	v_fmac_f32_e32 v114, v107, v119
	v_cvt_pk_bf16_f32 v105, v109, v110
	v_cvt_pk_bf16_f32 v106, v111, v112
	v_cvt_pk_bf16_f32 v107, v113, v114
	global_store_dwordx4 v[226:227], v[104:107], off
	s_waitcnt vmcnt(11)
	v_lshlrev_b32_e32 v112, 16, v208
	v_lshlrev_b32_e32 v108, 16, v206
	v_lshlrev_b32_e32 v104, 16, v204
	v_and_b32_e32 v105, 0xffff0000, v204
	v_fmac_f32_e32 v112, v100, v104
	v_and_b32_e32 v100, 0xffff0000, v208
	v_lshlrev_b32_e32 v106, 16, v205
	v_fmac_f32_e32 v100, v101, v105
	v_lshlrev_b32_e32 v101, 16, v209
	v_and_b32_e32 v107, 0xffff0000, v205
	v_fmac_f32_e32 v101, v102, v106
	v_and_b32_e32 v102, 0xffff0000, v209
	v_and_b32_e32 v109, 0xffff0000, v206
	v_fmac_f32_e32 v102, v103, v107
	v_lshlrev_b32_e32 v103, 16, v210
	v_and_b32_e32 v104, 0xffff0000, v210
	v_lshlrev_b32_e32 v110, 16, v207
	v_and_b32_e32 v111, 0xffff0000, v207
	v_fmac_f32_e32 v103, v96, v108
	v_fmac_f32_e32 v104, v97, v109
	v_lshlrev_b32_e32 v105, 16, v211
	v_and_b32_e32 v106, 0xffff0000, v211
	v_cvt_pk_bf16_f32 v96, v112, v100
	v_fmac_f32_e32 v105, v98, v110
	v_fmac_f32_e32 v106, v99, v111
	v_cvt_pk_bf16_f32 v97, v101, v102
	v_cvt_pk_bf16_f32 v98, v103, v104
	v_cvt_pk_bf16_f32 v99, v105, v106
	global_store_dwordx4 v[226:227], v[96:99], off offset:256
	s_waitcnt vmcnt(9)
	v_lshlrev_b32_e32 v104, 16, v220
	v_lshlrev_b32_e32 v100, 16, v214
	v_lshlrev_b32_e32 v96, 16, v212
	v_and_b32_e32 v97, 0xffff0000, v212
	v_fmac_f32_e32 v104, v92, v96
	v_and_b32_e32 v92, 0xffff0000, v220
	v_lshlrev_b32_e32 v98, 16, v213
	v_fmac_f32_e32 v92, v93, v97
	v_lshlrev_b32_e32 v93, 16, v221
	v_and_b32_e32 v99, 0xffff0000, v213
	v_fmac_f32_e32 v93, v94, v98
	v_and_b32_e32 v94, 0xffff0000, v221
	v_and_b32_e32 v101, 0xffff0000, v214
	v_fmac_f32_e32 v94, v95, v99
	v_lshlrev_b32_e32 v95, 16, v222
	v_and_b32_e32 v96, 0xffff0000, v222
	v_lshlrev_b32_e32 v102, 16, v215
	v_and_b32_e32 v103, 0xffff0000, v215
	v_fmac_f32_e32 v95, v88, v100
	v_fmac_f32_e32 v96, v89, v101
	v_lshlrev_b32_e32 v97, 16, v223
	v_and_b32_e32 v98, 0xffff0000, v223
	v_cvt_pk_bf16_f32 v88, v104, v92
	v_fmac_f32_e32 v97, v90, v102
	v_fmac_f32_e32 v98, v91, v103
	v_cvt_pk_bf16_f32 v89, v93, v94
	v_cvt_pk_bf16_f32 v90, v95, v96
	v_cvt_pk_bf16_f32 v91, v97, v98
	global_store_dwordx4 v[170:171], v[88:91], off
	s_waitcnt vmcnt(9)
; __device__ __forceinline__ unsigned cvt_pk_bf16(float lo, float hi) { unsigned r; asm volatile("v_cvt_pk_bf16_f32 %0, %1, %2" : "=v"(r) : "v"(lo), "v"(hi)); return r; }
; __device__ __forceinline__ float bflo(unsigned u) { return __uint_as_float(u << 16); }
; __device__ __forceinline__ float bfhi(unsigned u) { return __uint_as_float(u & 0xffff0000u); }
;     __device__ __forceinline__ void operator()(const f32x4 (&acc)[2][2][4][2], const Unit& u, int wr, int wc, int fr, int fq) const {
;     ...
;         for (int ai = 0; ai < 2; ++ai) {
;             u32x4 gv[4][2], yv[4][2];
; #pragma unroll
;             for (int m = 0; m < 4; ++m)
; #pragma unroll
;                 for (int bj = 0; bj < 2; ++bj) {
;                     const int row = row0 + ai * 128 + m * 16, col = col0 + bj * 128;
;                     gv[m][bj] = *(const u32x4*)(gates + (size_t)row * 2048 + SECOND * 1024 + col);
;                     if (SECOND) yv[m][bj] = *(const u32x4*)(Y + (size_t)row * 1024 + col);
;                 }
; #pragma unroll
;             for (int m = 0; m < 4; ++m)
; #pragma unroll
;                 for (int bj = 0; bj < 2; ++bj) {
;                     const int row = row0 + ai * 128 + m * 16, col = col0 + bj * 128;
;                     const u32x4 g = gv[m][bj];
;                     const f32x4 a0 = acc[ai][bj][m][0], a1 = acc[ai][bj][m][1];
;                     float r[8] = {a0[0] * bflo(g.x), a0[1] * bfhi(g.x), a0[2] * bflo(g.y), a0[3] * bfhi(g.y), a1[0] * bflo(g.z), a1[1] * bfhi(g.z), a1[2] * bflo(g.w), a1[3] * bfhi(g.w)};
;                     if (SECOND) { const u32x4 y = yv[m][bj];
;                         r[0] += bflo(y.x); r[1] += bfhi(y.x); r[2] += bflo(y.y); r[3] += bfhi(y.y); r[4] += bflo(y.z); r[5] += bfhi(y.z); r[6] += bflo(y.w); r[7] += bfhi(y.w); }
;                     u32x4 w; w.x = cvt_pk_bf16(r[0], r[1]); w.y = cvt_pk_bf16(r[2], r[3]); w.z = cvt_pk_bf16(r[4], r[5]); w.w = cvt_pk_bf16(r[6], r[7]);
;                     *(u32x4*)(Y + (size_t)row * 1024 + col) = w;
	v_lshlrev_b32_e32 v96, 16, v144
	v_lshlrev_b32_e32 v92, 16, v218
	v_lshlrev_b32_e32 v88, 16, v216
	v_and_b32_e32 v89, 0xffff0000, v216
	v_fmac_f32_e32 v96, v84, v88
	v_and_b32_e32 v84, 0xffff0000, v144
	v_lshlrev_b32_e32 v90, 16, v217
	v_fmac_f32_e32 v84, v85, v89
	v_lshlrev_b32_e32 v85, 16, v145
	v_and_b32_e32 v91, 0xffff0000, v217
	v_fmac_f32_e32 v85, v86, v90
	v_and_b32_e32 v86, 0xffff0000, v145
	v_and_b32_e32 v93, 0xffff0000, v218
	v_fmac_f32_e32 v86, v87, v91
	v_lshlrev_b32_e32 v87, 16, v146
	v_and_b32_e32 v88, 0xffff0000, v146
	v_lshlrev_b32_e32 v94, 16, v219
	v_and_b32_e32 v95, 0xffff0000, v219
	v_fmac_f32_e32 v87, v80, v92
	v_fmac_f32_e32 v88, v81, v93
	v_lshlrev_b32_e32 v89, 16, v147
	v_and_b32_e32 v90, 0xffff0000, v147
	v_cvt_pk_bf16_f32 v80, v96, v84
	v_fmac_f32_e32 v89, v82, v94
	v_fmac_f32_e32 v90, v83, v95
	v_cvt_pk_bf16_f32 v81, v85, v86
	v_cvt_pk_bf16_f32 v82, v87, v88
	v_cvt_pk_bf16_f32 v83, v89, v90
	global_store_dwordx4 v[170:171], v[80:83], off offset:256
	s_waitcnt vmcnt(7)
	v_lshlrev_b32_e32 v88, 16, v136
	v_lshlrev_b32_e32 v84, 16, v142
	v_lshlrev_b32_e32 v80, 16, v140
	v_and_b32_e32 v81, 0xffff0000, v140
	v_fmac_f32_e32 v88, v76, v80
	v_and_b32_e32 v76, 0xffff0000, v136
	v_lshlrev_b32_e32 v82, 16, v141
	v_fmac_f32_e32 v76, v77, v81
	v_lshlrev_b32_e32 v77, 16, v137
	v_and_b32_e32 v83, 0xffff0000, v141
	v_fmac_f32_e32 v77, v78, v82
	v_and_b32_e32 v78, 0xffff0000, v137
	v_and_b32_e32 v85, 0xffff0000, v142
	v_fmac_f32_e32 v78, v79, v83
	v_lshlrev_b32_e32 v79, 16, v138
	v_and_b32_e32 v80, 0xffff0000, v138
	v_lshlrev_b32_e32 v86, 16, v143
	v_and_b32_e32 v87, 0xffff0000, v143
	v_fmac_f32_e32 v79, v72, v84
	v_fmac_f32_e32 v80, v73, v85
	v_lshlrev_b32_e32 v81, 16, v139
	v_and_b32_e32 v82, 0xffff0000, v139
	v_cvt_pk_bf16_f32 v72, v88, v76
	v_fmac_f32_e32 v81, v74, v86
	v_fmac_f32_e32 v82, v75, v87
	v_cvt_pk_bf16_f32 v73, v77, v78
	v_cvt_pk_bf16_f32 v74, v79, v80
	v_cvt_pk_bf16_f32 v75, v81, v82
	global_store_dwordx4 v[168:169], v[72:75], off
	s_waitcnt vmcnt(7)
	v_lshlrev_b32_e32 v80, 16, v128
	v_lshlrev_b32_e32 v76, 16, v134
	v_lshlrev_b32_e32 v72, 16, v132
	v_and_b32_e32 v73, 0xffff0000, v132
	v_fmac_f32_e32 v80, v68, v72
	v_and_b32_e32 v68, 0xffff0000, v128
	v_lshlrev_b32_e32 v74, 16, v133
	v_fmac_f32_e32 v68, v69, v73
	v_lshlrev_b32_e32 v69, 16, v129
	v_and_b32_e32 v75, 0xffff0000, v133
	v_fmac_f32_e32 v69, v70, v74
	v_and_b32_e32 v70, 0xffff0000, v129
	v_fmac_f32_e32 v70, v71, v75
	v_lshlrev_b32_e32 v71, 16, v130
	v_and_b32_e32 v77, 0xffff0000, v134
	v_lshlrev_b32_e32 v78, 16, v135
	v_and_b32_e32 v79, 0xffff0000, v135
	v_fmac_f32_e32 v71, v64, v76
	v_and_b32_e32 v72, 0xffff0000, v130
	v_lshlrev_b32_e32 v73, 16, v131
	v_and_b32_e32 v74, 0xffff0000, v131
	v_cvt_pk_bf16_f32 v64, v80, v68
	v_fmac_f32_e32 v72, v65, v77
	v_fmac_f32_e32 v73, v66, v78
	v_fmac_f32_e32 v74, v67, v79
	v_cvt_pk_bf16_f32 v65, v69, v70
	v_cvt_pk_bf16_f32 v66, v71, v72
	v_cvt_pk_bf16_f32 v67, v73, v74
	global_store_dwordx4 v[168:169], v[64:67], off offset:256
	s_nop 1
	v_add_u32_e32 v64, 0x80, v164
	v_ashrrev_i32_e32 v65, 31, v64
	v_lshlrev_b64 v[66:67], 12, v[64:65]
	v_lshl_add_u64 v[66:67], s[4:5], 0, v[66:67]
	v_lshl_add_u64 v[66:67], v[66:67], 0, v[166:167]
	v_lshlrev_b64 v[64:65], 11, v[64:65]
	global_load_dwordx4 v[88:91], v[66:67], off offset:2048
	v_lshl_add_u64 v[64:65], s[2:3], 0, v[64:65]
	v_lshl_add_u64 v[132:133], v[64:65], 0, v[166:167]
	global_load_dwordx4 v[92:95], v[132:133], off
	global_load_dwordx4 v[96:99], v[66:67], off offset:2304
	global_load_dwordx4 v[100:103], v[132:133], off offset:256
	v_add_u32_e32 v64, 0x90, v164
	v_ashrrev_i32_e32 v65, 31, v64
	v_lshlrev_b64 v[66:67], 12, v[64:65]
	v_lshl_add_u64 v[66:67], s[4:5], 0, v[66:67]
	v_lshlrev_b64 v[64:65], 11, v[64:65]
	v_lshl_add_u64 v[64:65], s[2:3], 0, v[64:65]
	v_lshl_add_u64 v[66:67], v[66:67], 0, v[166:167]
	v_lshl_add_u64 v[134:135], v[64:65], 0, v[166:167]
	global_load_dwordx4 v[104:107], v[66:67], off offset:2048
	global_load_dwordx4 v[108:111], v[66:67], off offset:2304
	global_load_dwordx4 v[112:115], v[134:135], off
	global_load_dwordx4 v[116:119], v[134:135], off offset:256
	v_add_u32_e32 v64, 0xa0, v164
	v_ashrrev_i32_e32 v65, 31, v64
	v_lshlrev_b64 v[66:67], 12, v[64:65]
	v_lshl_add_u64 v[66:67], s[4:5], 0, v[66:67]
	v_lshlrev_b64 v[64:65], 11, v[64:65]
	v_lshl_add_u64 v[64:65], s[2:3], 0, v[64:65]
	v_lshl_add_u64 v[66:67], v[66:67], 0, v[166:167]
	v_lshl_add_u64 v[86:87], v[64:65], 0, v[166:167]
	global_load_dwordx4 v[120:123], v[66:67], off offset:2048
	global_load_dwordx4 v[124:127], v[66:67], off offset:2304
	global_load_dwordx4 v[128:131], v[86:87], off
	global_load_dwordx4 v[80:83], v[86:87], off offset:256
	v_add_u32_e32 v64, 0xb0, v164
	v_ashrrev_i32_e32 v65, 31, v64
	v_lshlrev_b64 v[66:67], 12, v[64:65]
	v_lshl_add_u64 v[66:67], s[4:5], 0, v[66:67]
	v_lshlrev_b64 v[64:65], 11, v[64:65]
	v_lshl_add_u64 v[64:65], s[2:3], 0, v[64:65]
	v_lshl_add_u64 v[66:67], v[66:67], 0, v[166:167]
	v_lshl_add_u64 v[84:85], v[64:65], 0, v[166:167]
	global_load_dwordx4 v[76:79], v[66:67], off offset:2048
	global_load_dwordx4 v[68:71], v[66:67], off offset:2304
	global_load_dwordx4 v[72:75], v[84:85], off
	s_nop 0
	global_load_dwordx4 v[64:67], v[84:85], off offset:256
	s_waitcnt vmcnt(15)
	v_lshlrev_b32_e32 v136, 16, v88
	s_waitcnt vmcnt(14)
; __device__ __forceinline__ unsigned cvt_pk_bf16(float lo, float hi) { unsigned r; asm volatile("v_cvt_pk_bf16_f32 %0, %1, %2" : "=v"(r) : "v"(lo), "v"(hi)); return r; }
; __device__ __forceinline__ float bflo(unsigned u) { return __uint_as_float(u << 16); }
; __device__ __forceinline__ float bfhi(unsigned u) { return __uint_as_float(u & 0xffff0000u); }
;     __device__ __forceinline__ void operator()(const f32x4 (&acc)[2][2][4][2], const Unit& u, int wr, int wc, int fr, int fq) const {
;     ...
;             for (int m = 0; m < 4; ++m)
; #pragma unroll
;                 for (int bj = 0; bj < 2; ++bj) {
;                     const int row = row0 + ai * 128 + m * 16, col = col0 + bj * 128;
;                     const u32x4 g = gv[m][bj];
;                     const f32x4 a0 = acc[ai][bj][m][0], a1 = acc[ai][bj][m][1];
;                     float r[8] = {a0[0] * bflo(g.x), a0[1] * bfhi(g.x), a0[2] * bflo(g.y), a0[3] * bfhi(g.y), a1[0] * bflo(g.z), a1[1] * bfhi(g.z), a1[2] * bflo(g.w), a1[3] * bfhi(g.w)};
;                     if (SECOND) { const u32x4 y = yv[m][bj];
;                         r[0] += bflo(y.x); r[1] += bfhi(y.x); r[2] += bflo(y.y); r[3] += bfhi(y.y); r[4] += bflo(y.z); r[5] += bfhi(y.z); r[6] += bflo(y.w); r[7] += bfhi(y.w); }
;                     u32x4 w; w.x = cvt_pk_bf16(r[0], r[1]); w.y = cvt_pk_bf16(r[2], r[3]); w.z = cvt_pk_bf16(r[4], r[5]); w.w = cvt_pk_bf16(r[6], r[7]);
;                     *(u32x4*)(Y + (size_t)row * 1024 + col) = w;
	v_lshlrev_b32_e32 v140, 16, v92
	v_and_b32_e32 v88, 0xffff0000, v88
	v_fmac_f32_e32 v140, v60, v136
	v_and_b32_e32 v60, 0xffff0000, v92
	v_lshlrev_b32_e32 v137, 16, v89
	v_fmac_f32_e32 v60, v61, v88
	v_lshlrev_b32_e32 v61, 16, v93
	v_and_b32_e32 v89, 0xffff0000, v89
	v_fmac_f32_e32 v61, v62, v137
	v_and_b32_e32 v62, 0xffff0000, v93
	v_lshlrev_b32_e32 v138, 16, v90
	v_and_b32_e32 v90, 0xffff0000, v90
	v_fmac_f32_e32 v62, v63, v89
	v_lshlrev_b32_e32 v63, 16, v94
	v_and_b32_e32 v88, 0xffff0000, v94
	v_lshlrev_b32_e32 v139, 16, v91
	v_and_b32_e32 v91, 0xffff0000, v91
	v_fmac_f32_e32 v63, v56, v138
	v_fmac_f32_e32 v88, v57, v90
	v_lshlrev_b32_e32 v89, 16, v95
	v_and_b32_e32 v90, 0xffff0000, v95
	v_cvt_pk_bf16_f32 v56, v140, v60
	v_fmac_f32_e32 v89, v58, v139
	v_fmac_f32_e32 v90, v59, v91
	v_cvt_pk_bf16_f32 v57, v61, v62
	v_cvt_pk_bf16_f32 v58, v63, v88
	v_cvt_pk_bf16_f32 v59, v89, v90
	global_store_dwordx4 v[132:133], v[56:59], off
	s_waitcnt vmcnt(13)
	v_lshlrev_b32_e32 v88, 16, v100
	v_lshlrev_b32_e32 v60, 16, v98
	v_lshlrev_b32_e32 v56, 16, v96
	v_and_b32_e32 v57, 0xffff0000, v96
	v_fmac_f32_e32 v88, v52, v56
	v_and_b32_e32 v52, 0xffff0000, v100
	v_lshlrev_b32_e32 v58, 16, v97
	v_fmac_f32_e32 v52, v53, v57
	v_lshlrev_b32_e32 v53, 16, v101
	v_and_b32_e32 v59, 0xffff0000, v97
	v_fmac_f32_e32 v53, v54, v58
	v_and_b32_e32 v54, 0xffff0000, v101
	v_and_b32_e32 v61, 0xffff0000, v98
	v_fmac_f32_e32 v54, v55, v59
	v_lshlrev_b32_e32 v55, 16, v102
	v_and_b32_e32 v56, 0xffff0000, v102
	v_lshlrev_b32_e32 v62, 16, v99
	v_and_b32_e32 v63, 0xffff0000, v99
	v_fmac_f32_e32 v55, v48, v60
	v_fmac_f32_e32 v56, v49, v61
	v_lshlrev_b32_e32 v57, 16, v103
	v_and_b32_e32 v58, 0xffff0000, v103
	v_cvt_pk_bf16_f32 v48, v88, v52
	v_fmac_f32_e32 v57, v50, v62
	v_fmac_f32_e32 v58, v51, v63
	v_cvt_pk_bf16_f32 v49, v53, v54
	v_cvt_pk_bf16_f32 v50, v55, v56
	v_cvt_pk_bf16_f32 v51, v57, v58
	global_store_dwordx4 v[132:133], v[48:51], off offset:256
	s_waitcnt vmcnt(11)
	v_lshlrev_b32_e32 v56, 16, v112
	v_lshlrev_b32_e32 v52, 16, v106
	v_lshlrev_b32_e32 v48, 16, v104
	v_and_b32_e32 v49, 0xffff0000, v104
	v_fmac_f32_e32 v56, v44, v48
	v_and_b32_e32 v44, 0xffff0000, v112
	v_lshlrev_b32_e32 v50, 16, v105
	v_fmac_f32_e32 v44, v45, v49
	v_lshlrev_b32_e32 v45, 16, v113
	v_and_b32_e32 v51, 0xffff0000, v105
	v_fmac_f32_e32 v45, v46, v50
	v_and_b32_e32 v46, 0xffff0000, v113
	v_and_b32_e32 v53, 0xffff0000, v106
	v_fmac_f32_e32 v46, v47, v51
	v_lshlrev_b32_e32 v47, 16, v114
	v_and_b32_e32 v48, 0xffff0000, v114
	v_lshlrev_b32_e32 v54, 16, v107
	v_and_b32_e32 v55, 0xffff0000, v107
	v_fmac_f32_e32 v47, v40, v52
	v_fmac_f32_e32 v48, v41, v53
	v_lshlrev_b32_e32 v49, 16, v115
	v_and_b32_e32 v50, 0xffff0000, v115
	v_cvt_pk_bf16_f32 v40, v56, v44
	v_fmac_f32_e32 v49, v42, v54
	v_fmac_f32_e32 v50, v43, v55
	v_cvt_pk_bf16_f32 v41, v45, v46
	v_cvt_pk_bf16_f32 v42, v47, v48
	v_cvt_pk_bf16_f32 v43, v49, v50
	global_store_dwordx4 v[134:135], v[40:43], off
	s_waitcnt vmcnt(11)
	v_lshlrev_b32_e32 v48, 16, v116
	v_lshlrev_b32_e32 v44, 16, v110
	v_lshlrev_b32_e32 v40, 16, v108
	v_and_b32_e32 v41, 0xffff0000, v108
	v_fmac_f32_e32 v48, v36, v40
	v_and_b32_e32 v36, 0xffff0000, v116
	v_lshlrev_b32_e32 v42, 16, v109
	v_fmac_f32_e32 v36, v37, v41
	v_lshlrev_b32_e32 v37, 16, v117
	v_and_b32_e32 v43, 0xffff0000, v109
	v_fmac_f32_e32 v37, v38, v42
	v_and_b32_e32 v38, 0xffff0000, v117
	v_and_b32_e32 v45, 0xffff0000, v110
	v_fmac_f32_e32 v38, v39, v43
	v_lshlrev_b32_e32 v39, 16, v118
	v_and_b32_e32 v40, 0xffff0000, v118
	v_lshlrev_b32_e32 v46, 16, v111
	v_and_b32_e32 v47, 0xffff0000, v111
	v_fmac_f32_e32 v39, v32, v44
	v_fmac_f32_e32 v40, v33, v45
	v_lshlrev_b32_e32 v41, 16, v119
	v_and_b32_e32 v42, 0xffff0000, v119
	v_cvt_pk_bf16_f32 v32, v48, v36
	v_fmac_f32_e32 v41, v34, v46
	v_fmac_f32_e32 v42, v35, v47
	v_cvt_pk_bf16_f32 v33, v37, v38
	v_cvt_pk_bf16_f32 v34, v39, v40
	v_cvt_pk_bf16_f32 v35, v41, v42
	global_store_dwordx4 v[134:135], v[32:35], off offset:256
	s_waitcnt vmcnt(9)
; __device__ __forceinline__ unsigned cvt_pk_bf16(float lo, float hi) { unsigned r; asm volatile("v_cvt_pk_bf16_f32 %0, %1, %2" : "=v"(r) : "v"(lo), "v"(hi)); return r; }
; __device__ __forceinline__ float bflo(unsigned u) { return __uint_as_float(u << 16); }
; __device__ __forceinline__ float bfhi(unsigned u) { return __uint_as_float(u & 0xffff0000u); }
; #define PG8_WAIT_V(n) asm volatile("s_waitcnt vmcnt(" #n ")" ::: "memory")
; #define PG8_BAR __builtin_amdgcn_s_barrier()
; template <class Epi, class Sched>
; __device__ __forceinline__ void gemm_phase(const int wv, LAS unsigned char* lds, const Gemm g, const Sched& S, const Epi& E) {
;     ...
;     PG8_WAIT_V(0);
;     if (wr == 0) PG8_BAR;
;     PG8_BAR;
;     __device__ __forceinline__ void operator()(const f32x4 (&acc)[2][2][4][2], const Unit& u, int wr, int wc, int fr, int fq) const {
;     ...
;             for (int m = 0; m < 4; ++m)
; #pragma unroll
;                 for (int bj = 0; bj < 2; ++bj) {
;                     const int row = row0 + ai * 128 + m * 16, col = col0 + bj * 128;
;                     const u32x4 g = gv[m][bj];
;                     const f32x4 a0 = acc[ai][bj][m][0], a1 = acc[ai][bj][m][1];
;                     float r[8] = {a0[0] * bflo(g.x), a0[1] * bfhi(g.x), a0[2] * bflo(g.y), a0[3] * bfhi(g.y), a1[0] * bflo(g.z), a1[1] * bfhi(g.z), a1[2] * bflo(g.w), a1[3] * bfhi(g.w)};
;                     if (SECOND) { const u32x4 y = yv[m][bj];
;                         r[0] += bflo(y.x); r[1] += bfhi(y.x); r[2] += bflo(y.y); r[3] += bfhi(y.y); r[4] += bflo(y.z); r[5] += bfhi(y.z); r[6] += bflo(y.w); r[7] += bfhi(y.w); }
;                     u32x4 w; w.x = cvt_pk_bf16(r[0], r[1]); w.y = cvt_pk_bf16(r[2], r[3]); w.z = cvt_pk_bf16(r[4], r[5]); w.w = cvt_pk_bf16(r[6], r[7]);
;                     *(u32x4*)(Y + (size_t)row * 1024 + col) = w;
	v_lshlrev_b32_e32 v40, 16, v128
	v_lshlrev_b32_e32 v36, 16, v122
	v_lshlrev_b32_e32 v32, 16, v120
	v_and_b32_e32 v33, 0xffff0000, v120
	v_fmac_f32_e32 v40, v28, v32
	v_and_b32_e32 v28, 0xffff0000, v128
	v_lshlrev_b32_e32 v34, 16, v121
	v_fmac_f32_e32 v28, v29, v33
	v_lshlrev_b32_e32 v29, 16, v129
	v_and_b32_e32 v35, 0xffff0000, v121
	v_fmac_f32_e32 v29, v30, v34
	v_and_b32_e32 v30, 0xffff0000, v129
	v_and_b32_e32 v37, 0xffff0000, v122
	v_fmac_f32_e32 v30, v31, v35
	v_lshlrev_b32_e32 v31, 16, v130
	v_and_b32_e32 v32, 0xffff0000, v130
	v_lshlrev_b32_e32 v38, 16, v123
	v_and_b32_e32 v39, 0xffff0000, v123
	v_fmac_f32_e32 v31, v24, v36
	v_fmac_f32_e32 v32, v25, v37
	v_lshlrev_b32_e32 v33, 16, v131
	v_and_b32_e32 v34, 0xffff0000, v131
	v_cvt_pk_bf16_f32 v24, v40, v28
	v_fmac_f32_e32 v33, v26, v38
	v_fmac_f32_e32 v34, v27, v39
	v_cvt_pk_bf16_f32 v25, v29, v30
	v_cvt_pk_bf16_f32 v26, v31, v32
	v_cvt_pk_bf16_f32 v27, v33, v34
	global_store_dwordx4 v[86:87], v[24:27], off
	s_waitcnt vmcnt(9)
	v_lshlrev_b32_e32 v32, 16, v80
	v_lshlrev_b32_e32 v28, 16, v126
	v_lshlrev_b32_e32 v24, 16, v124
	v_and_b32_e32 v25, 0xffff0000, v124
	v_fmac_f32_e32 v32, v20, v24
	v_and_b32_e32 v20, 0xffff0000, v80
	v_lshlrev_b32_e32 v26, 16, v125
	v_fmac_f32_e32 v20, v21, v25
	v_lshlrev_b32_e32 v21, 16, v81
	v_and_b32_e32 v27, 0xffff0000, v125
	v_fmac_f32_e32 v21, v22, v26
	v_and_b32_e32 v22, 0xffff0000, v81
	v_and_b32_e32 v29, 0xffff0000, v126
	v_fmac_f32_e32 v22, v23, v27
	v_lshlrev_b32_e32 v23, 16, v82
	v_and_b32_e32 v24, 0xffff0000, v82
	v_lshlrev_b32_e32 v30, 16, v127
	v_and_b32_e32 v31, 0xffff0000, v127
	v_fmac_f32_e32 v23, v16, v28
	v_fmac_f32_e32 v24, v17, v29
	v_lshlrev_b32_e32 v25, 16, v83
	v_and_b32_e32 v26, 0xffff0000, v83
	v_cvt_pk_bf16_f32 v16, v32, v20
	v_fmac_f32_e32 v25, v18, v30
	v_fmac_f32_e32 v26, v19, v31
	v_cvt_pk_bf16_f32 v17, v21, v22
	v_cvt_pk_bf16_f32 v18, v23, v24
	v_cvt_pk_bf16_f32 v19, v25, v26
	global_store_dwordx4 v[86:87], v[16:19], off offset:256
	s_waitcnt vmcnt(7)
	v_lshlrev_b32_e32 v24, 16, v72
	v_lshlrev_b32_e32 v20, 16, v78
	v_lshlrev_b32_e32 v16, 16, v76
	v_and_b32_e32 v17, 0xffff0000, v76
	v_fmac_f32_e32 v24, v12, v16
	v_and_b32_e32 v12, 0xffff0000, v72
	v_lshlrev_b32_e32 v18, 16, v77
	v_fmac_f32_e32 v12, v13, v17
	v_lshlrev_b32_e32 v13, 16, v73
	v_and_b32_e32 v19, 0xffff0000, v77
	v_fmac_f32_e32 v13, v14, v18
	v_and_b32_e32 v14, 0xffff0000, v73
	v_and_b32_e32 v21, 0xffff0000, v78
	v_fmac_f32_e32 v14, v15, v19
	v_lshlrev_b32_e32 v15, 16, v74
	v_and_b32_e32 v16, 0xffff0000, v74
	v_lshlrev_b32_e32 v22, 16, v79
	v_and_b32_e32 v23, 0xffff0000, v79
	v_fmac_f32_e32 v15, v8, v20
	v_fmac_f32_e32 v16, v9, v21
	v_lshlrev_b32_e32 v17, 16, v75
	v_and_b32_e32 v18, 0xffff0000, v75
	v_cvt_pk_bf16_f32 v8, v24, v12
	v_fmac_f32_e32 v17, v10, v22
	v_fmac_f32_e32 v18, v11, v23
	v_cvt_pk_bf16_f32 v9, v13, v14
	v_cvt_pk_bf16_f32 v10, v15, v16
	v_cvt_pk_bf16_f32 v11, v17, v18
	global_store_dwordx4 v[84:85], v[8:11], off
	s_waitcnt vmcnt(7)
	v_lshlrev_b32_e32 v16, 16, v64
	v_lshlrev_b32_e32 v12, 16, v70
	v_lshlrev_b32_e32 v8, 16, v68
	v_and_b32_e32 v9, 0xffff0000, v68
	v_fmac_f32_e32 v16, v4, v8
	v_and_b32_e32 v4, 0xffff0000, v64
	v_lshlrev_b32_e32 v10, 16, v69
	v_fmac_f32_e32 v4, v5, v9
	v_lshlrev_b32_e32 v5, 16, v65
	v_and_b32_e32 v11, 0xffff0000, v69
	v_fmac_f32_e32 v5, v6, v10
	v_and_b32_e32 v6, 0xffff0000, v65
	v_and_b32_e32 v13, 0xffff0000, v70
	v_lshlrev_b32_e32 v14, 16, v71
	v_and_b32_e32 v15, 0xffff0000, v71
	v_fmac_f32_e32 v6, v7, v11
	v_lshlrev_b32_e32 v7, 16, v66
	v_and_b32_e32 v8, 0xffff0000, v66
	v_lshlrev_b32_e32 v9, 16, v67
	v_and_b32_e32 v10, 0xffff0000, v67
	v_fmac_f32_e32 v7, v0, v12
	v_fmac_f32_e32 v8, v1, v13
	v_fmac_f32_e32 v9, v2, v14
	v_fmac_f32_e32 v10, v3, v15
	v_cvt_pk_bf16_f32 v0, v16, v4
	v_cvt_pk_bf16_f32 v1, v5, v6
	v_cvt_pk_bf16_f32 v2, v7, v8
	v_cvt_pk_bf16_f32 v3, v9, v10
	global_store_dwordx4 v[84:85], v[0:3], off offset:256
	s_cbranch_vccz .LBB0_590
	s_waitcnt vmcnt(0)
	s_cmpk_gt_u32 s24, 0xff
	s_cbranch_scc1 .LBB0_601
	s_barrier

; #define PG8_STAGE(bufoff, gbase, voff) do { _Pragma("unroll") for (int _i = 0; _i < 2; ++_i) \
;         __builtin_amdgcn_global_load_lds((const unsigned*)((const char*)(gbase) + (voff)[_i]), (LAS unsigned*)(lds + (bufoff) + ldsw + _i * 8192), 16, 0, 0); } while (0)
; #define PG8_LDA(dst, b, h) do { _Pragma("unroll") for (int m = 0; m < 4; ++m) _Pragma("unroll") for (int k = 0; k < 2; ++k) dst[m][k] = *(const LAS bf16x8*)(lds + PG8_SA(b, h) + aoff + m * 2048 + k * 1024); } while (0)
; #define PG8_LDB(dst, b, h) do { _Pragma("unroll") for (int n = 0; n < 2; ++n) _Pragma("unroll") for (int k = 0; k < 2; ++k) dst[n][k] = *(const LAS bf16x8*)(lds + PG8_SB(b, h) + boff + n * 2048 + k * 1024); } while (0)
; #define PG8_MMA(ai, bj, At, Bt) do { __builtin_amdgcn_s_setprio(1); _Pragma("unroll") for (int m = 0; m < 4; ++m) _Pragma("unroll") for (int n = 0; n < 2; ++n) _Pragma("unroll") for (int k = 0; k < 2; ++k) \
;         acc[ai][bj][m][n] = __builtin_amdgcn_mfma_f32_16x16x32_bf16(Bt[n][k], At[m][k], acc[ai][bj][m][n], 0, 0, 0); __builtin_amdgcn_s_setprio(0); } while (0)
; #define PG8_WAIT_V(n) asm volatile("s_waitcnt vmcnt(" #n ")" ::: "memory")
; #define PG8_WAIT_L(n) asm volatile("s_waitcnt lgkmcnt(" #n ")" ::: "memory")
; #define PG8_BAR __builtin_amdgcn_s_barrier()
; #define PG8_SCHED __builtin_amdgcn_sched_barrier(0)
; template <class Epi, class Sched>
; __device__ __forceinline__ void gemm_phase(const int wv, LAS unsigned char* lds, const Gemm g, const Sched& S, const Epi& E) {
;     ...
;             PG8_LDB(B0, 0, 0); PG8_SCHED; PG8_LDA(At, 0, 0); PG8_STAGE(PG8_SA(1, 1), a1 + hstepA, voffA);
;             PG8_WAIT_L(8); PG8_BAR; PG8_WAIT_L(0); PG8_MMA(0, 0, At, B0); PG8_BAR; PG8_SCHED;
;             PG8_LDB(B1, 0, 1); PG8_STAGE(PG8_SB(0, 0), b2, voffB);
;             PG8_BAR; PG8_WAIT_L(0); PG8_MMA(0, 1, At, B1); PG8_BAR;
;             PG8_LDA(At, 0, 1); PG8_STAGE(PG8_SA(0, 0), a2, voffA);
;             PG8_BAR; PG8_WAIT_L(0); PG8_MMA(1, 0, At, B0); PG8_BAR; PG8_SCHED;
;             PG8_STAGE(PG8_SB(0, 1), b2 + hstepB, voffB);
;             PG8_WAIT_V(6); PG8_BAR; PG8_MMA(1, 1, At, B1); PG8_BAR;
;             PG8_LDB(B0, 1, 0); PG8_SCHED; PG8_LDA(At, 1, 0); PG8_STAGE(PG8_SA(0, 1), a2 + hstepA, voffA);
;             PG8_WAIT_L(8); PG8_BAR; PG8_WAIT_L(0); PG8_MMA(0, 0, At, B0); PG8_BAR; PG8_SCHED;
.LBB0_661:
	ds_read_b128 v[128:131], v177
	ds_read_b128 v[132:135], v177 offset:1024
	ds_read_b128 v[136:139], v177 offset:2048
	ds_read_b128 v[140:143], v177 offset:3072
	s_add_u32 s24, s22, 0xfffc0080
	s_addc_u32 s25, s23, -1
	s_cmp_eq_u32 s48, 12
	s_cselect_b32 s27, s15, s25
	s_cselect_b32 s26, s44, s24
	s_cselect_b32 s25, s13, s47
	s_cselect_b32 s24, s45, s46
	v_lshl_add_u64 v[202:203], s[22:23], 0, v[152:153]
	s_add_i32 m0, s35, 0xc000
	ds_read_b128 v[160:163], v180
	ds_read_b128 v[164:167], v180 offset:1024
	ds_read_b128 v[168:171], v180 offset:2048
	ds_read_b128 v[182:185], v180 offset:3072
	ds_read_b128 v[186:189], v180 offset:4096
	ds_read_b128 v[190:193], v180 offset:5120
	ds_read_b128 v[194:197], v180 offset:6144
	ds_read_b128 v[198:201], v180 offset:7168
	global_load_lds_dwordx4 v[202:203], off
	s_add_i32 m0, s35, 0xe000
	v_lshl_add_u64 v[202:203], s[22:23], 0, v[154:155]
	global_load_lds_dwordx4 v[202:203], off
	s_waitcnt lgkmcnt(8)
	s_barrier
	s_waitcnt lgkmcnt(0)
	v_mfma_f32_16x16x32_bf16 v[124:127], v[128:131], v[160:163], v[124:127]
	v_mfma_f32_16x16x32_bf16 v[120:123], v[136:139], v[160:163], v[120:123]
	v_mfma_f32_16x16x32_bf16 v[116:119], v[128:131], v[168:171], v[116:119]
	v_mfma_f32_16x16x32_bf16 v[104:107], v[136:139], v[168:171], v[104:107]
	v_mfma_f32_16x16x32_bf16 v[92:95], v[128:131], v[186:189], v[92:95]
	v_mfma_f32_16x16x32_bf16 v[88:91], v[136:139], v[186:189], v[88:91]
	v_mfma_f32_16x16x32_bf16 v[76:79], v[128:131], v[194:197], v[76:79]
	v_mfma_f32_16x16x32_bf16 v[72:75], v[136:139], v[194:197], v[72:75]
	v_mfma_f32_16x16x32_bf16 v[124:127], v[132:135], v[164:167], v[124:127]
	v_mfma_f32_16x16x32_bf16 v[120:123], v[140:143], v[164:167], v[120:123]
	v_mfma_f32_16x16x32_bf16 v[116:119], v[132:135], v[182:185], v[116:119]
	v_mfma_f32_16x16x32_bf16 v[104:107], v[140:143], v[182:185], v[104:107]
	v_mfma_f32_16x16x32_bf16 v[92:95], v[132:135], v[190:193], v[92:95]
	v_mfma_f32_16x16x32_bf16 v[88:91], v[140:143], v[190:193], v[88:91]
	v_mfma_f32_16x16x32_bf16 v[76:79], v[132:135], v[198:201], v[76:79]
	v_mfma_f32_16x16x32_bf16 v[72:75], v[140:143], v[198:201], v[72:75]
	s_barrier
	s_add_i32 s49, s41, s34
	v_lshl_add_u64 v[218:219], s[24:25], 0, v[146:147]
	s_mov_b32 m0, s49
	ds_read_b128 v[202:205], v181
	ds_read_b128 v[206:209], v181 offset:1024
	ds_read_b128 v[210:213], v181 offset:2048
	ds_read_b128 v[214:217], v181 offset:3072
	global_load_lds_dwordx4 v[218:219], off
	s_add_i32 m0, s49, 0x2000
	v_lshl_add_u64 v[220:221], s[24:25], 0, v[150:151]
	global_load_lds_dwordx4 v[220:221], off
	s_barrier
	s_waitcnt lgkmcnt(0)
	v_mfma_f32_16x16x32_bf16 v[112:115], v[202:205], v[160:163], v[112:115]
	v_mfma_f32_16x16x32_bf16 v[108:111], v[210:213], v[160:163], v[108:111]
	v_mfma_f32_16x16x32_bf16 v[100:103], v[202:205], v[168:171], v[100:103]
	v_mfma_f32_16x16x32_bf16 v[96:99], v[210:213], v[168:171], v[96:99]
	v_mfma_f32_16x16x32_bf16 v[84:87], v[202:205], v[186:189], v[84:87]
	v_mfma_f32_16x16x32_bf16 v[80:83], v[210:213], v[186:189], v[80:83]
	v_mfma_f32_16x16x32_bf16 v[68:71], v[202:205], v[194:197], v[68:71]
	v_mfma_f32_16x16x32_bf16 v[64:67], v[210:213], v[194:197], v[64:67]
	v_mfma_f32_16x16x32_bf16 v[112:115], v[206:209], v[164:167], v[112:115]
	v_mfma_f32_16x16x32_bf16 v[108:111], v[214:217], v[164:167], v[108:111]
	v_mfma_f32_16x16x32_bf16 v[100:103], v[206:209], v[182:185], v[100:103]
	v_mfma_f32_16x16x32_bf16 v[96:99], v[214:217], v[182:185], v[96:99]
	v_mfma_f32_16x16x32_bf16 v[84:87], v[206:209], v[190:193], v[84:87]
	v_mfma_f32_16x16x32_bf16 v[80:83], v[214:217], v[190:193], v[80:83]
	v_mfma_f32_16x16x32_bf16 v[68:71], v[206:209], v[198:201], v[68:71]
	v_mfma_f32_16x16x32_bf16 v[64:67], v[214:217], v[198:201], v[64:67]
	s_mov_b32 m0, s35
	v_lshl_add_u64 v[222:223], s[26:27], 0, v[144:145]
	s_barrier
	ds_read_b128 v[160:163], v180 offset:16384
	ds_read_b128 v[164:167], v180 offset:17408
	ds_read_b128 v[168:171], v180 offset:18432
	ds_read_b128 v[182:185], v180 offset:19456
	ds_read_b128 v[186:189], v180 offset:20480
	ds_read_b128 v[190:193], v180 offset:21504
	ds_read_b128 v[194:197], v180 offset:22528
	ds_read_b128 v[198:201], v180 offset:23552
	global_load_lds_dwordx4 v[222:223], off
	s_mov_b32 m0, s36
	v_lshl_add_u64 v[224:225], s[26:27], 0, v[148:149]
	global_load_lds_dwordx4 v[224:225], off
	s_barrier
	s_waitcnt lgkmcnt(0)
	v_mfma_f32_16x16x32_bf16 v[60:63], v[128:131], v[160:163], v[60:63]
	v_mfma_f32_16x16x32_bf16 v[56:59], v[136:139], v[160:163], v[56:59]
	v_mfma_f32_16x16x32_bf16 v[44:47], v[128:131], v[168:171], v[44:47]
	v_mfma_f32_16x16x32_bf16 v[40:43], v[136:139], v[168:171], v[40:43]
	v_mfma_f32_16x16x32_bf16 v[28:31], v[128:131], v[186:189], v[28:31]
	v_mfma_f32_16x16x32_bf16 v[24:27], v[136:139], v[186:189], v[24:27]
	v_mfma_f32_16x16x32_bf16 v[12:15], v[128:131], v[194:197], v[12:15]
	v_mfma_f32_16x16x32_bf16 v[8:11], v[136:139], v[194:197], v[8:11]
	v_mfma_f32_16x16x32_bf16 v[60:63], v[132:135], v[164:167], v[60:63]
	v_mfma_f32_16x16x32_bf16 v[56:59], v[140:143], v[164:167], v[56:59]
	v_mfma_f32_16x16x32_bf16 v[44:47], v[132:135], v[182:185], v[44:47]
	v_mfma_f32_16x16x32_bf16 v[40:43], v[140:143], v[182:185], v[40:43]
	v_mfma_f32_16x16x32_bf16 v[28:31], v[132:135], v[190:193], v[28:31]
	v_mfma_f32_16x16x32_bf16 v[24:27], v[140:143], v[190:193], v[24:27]
	v_mfma_f32_16x16x32_bf16 v[12:15], v[132:135], v[198:201], v[12:15]
	v_mfma_f32_16x16x32_bf16 v[8:11], v[140:143], v[198:201], v[8:11]
	s_barrier
	s_add_u32 s50, s24, 0x40000
	s_addc_u32 s51, s25, 0
	s_add_i32 s49, s42, s34
	s_mov_b32 m0, s49
	v_lshl_add_u64 v[128:129], s[50:51], 0, v[146:147]
	global_load_lds_dwordx4 v[128:129], off
	s_add_i32 m0, s49, 0x2000
	v_lshl_add_u64 v[128:129], s[50:51], 0, v[150:151]
	global_load_lds_dwordx4 v[128:129], off
	s_waitcnt vmcnt(6)
	s_barrier
; #define PG8_STAGE(bufoff, gbase, voff) do { _Pragma("unroll") for (int _i = 0; _i < 2; ++_i) \
;         __builtin_amdgcn_global_load_lds((const unsigned*)((const char*)(gbase) + (voff)[_i]), (LAS unsigned*)(lds + (bufoff) + ldsw + _i * 8192), 16, 0, 0); } while (0)
; #define PG8_LDA(dst, b, h) do { _Pragma("unroll") for (int m = 0; m < 4; ++m) _Pragma("unroll") for (int k = 0; k < 2; ++k) dst[m][k] = *(const LAS bf16x8*)(lds + PG8_SA(b, h) + aoff + m * 2048 + k * 1024); } while (0)
; #define PG8_LDB(dst, b, h) do { _Pragma("unroll") for (int n = 0; n < 2; ++n) _Pragma("unroll") for (int k = 0; k < 2; ++k) dst[n][k] = *(const LAS bf16x8*)(lds + PG8_SB(b, h) + boff + n * 2048 + k * 1024); } while (0)
; #define PG8_MMA(ai, bj, At, Bt) do { __builtin_amdgcn_s_setprio(1); _Pragma("unroll") for (int m = 0; m < 4; ++m) _Pragma("unroll") for (int n = 0; n < 2; ++n) _Pragma("unroll") for (int k = 0; k < 2; ++k) \
;         acc[ai][bj][m][n] = __builtin_amdgcn_mfma_f32_16x16x32_bf16(Bt[n][k], At[m][k], acc[ai][bj][m][n], 0, 0, 0); __builtin_amdgcn_s_setprio(0); } while (0)
; #define PG8_WAIT_V(n) asm volatile("s_waitcnt vmcnt(" #n ")" ::: "memory")
; #define PG8_WAIT_L(n) asm volatile("s_waitcnt lgkmcnt(" #n ")" ::: "memory")
; #define PG8_BAR __builtin_amdgcn_s_barrier()
; #define PG8_SCHED __builtin_amdgcn_sched_barrier(0)
; template <class Epi, class Sched>
; __device__ __forceinline__ void gemm_phase(const int wv, LAS unsigned char* lds, const Gemm g, const Sched& S, const Epi& E) {
;     ...
;             PG8_STAGE(PG8_SB(0, 1), b2 + hstepB, voffB);
;             PG8_WAIT_V(6); PG8_BAR; PG8_MMA(1, 1, At, B1); PG8_BAR;
;             PG8_LDB(B0, 1, 0); PG8_SCHED; PG8_LDA(At, 1, 0); PG8_STAGE(PG8_SA(0, 1), a2 + hstepA, voffA);
;             PG8_WAIT_L(8); PG8_BAR; PG8_WAIT_L(0); PG8_MMA(0, 0, At, B0); PG8_BAR; PG8_SCHED;
;             PG8_LDB(B1, 1, 1); PG8_STAGE(PG8_SB(1, 0), b3, voffB);
;             PG8_BAR; PG8_WAIT_L(0); PG8_MMA(0, 1, At, B1); PG8_BAR;
;             PG8_LDA(At, 1, 1); PG8_STAGE(PG8_SA(1, 0), a3, voffA);
;             PG8_BAR; PG8_WAIT_L(0); PG8_MMA(1, 0, At, B0); PG8_BAR; PG8_SCHED;
	v_mfma_f32_16x16x32_bf16 v[52:55], v[202:205], v[160:163], v[52:55]
	v_mfma_f32_16x16x32_bf16 v[48:51], v[210:213], v[160:163], v[48:51]
	v_mfma_f32_16x16x32_bf16 v[36:39], v[202:205], v[168:171], v[36:39]
	v_mfma_f32_16x16x32_bf16 v[32:35], v[210:213], v[168:171], v[32:35]
	v_mfma_f32_16x16x32_bf16 v[20:23], v[202:205], v[186:189], v[20:23]
	v_mfma_f32_16x16x32_bf16 v[16:19], v[210:213], v[186:189], v[16:19]
	v_mfma_f32_16x16x32_bf16 v[4:7], v[202:205], v[194:197], v[4:7]
	v_mfma_f32_16x16x32_bf16 v[0:3], v[210:213], v[194:197], v[0:3]
	v_mfma_f32_16x16x32_bf16 v[52:55], v[206:209], v[164:167], v[52:55]
	v_mfma_f32_16x16x32_bf16 v[48:51], v[214:217], v[164:167], v[48:51]
	v_mfma_f32_16x16x32_bf16 v[36:39], v[206:209], v[182:185], v[36:39]
	v_mfma_f32_16x16x32_bf16 v[32:35], v[214:217], v[182:185], v[32:35]
	v_mfma_f32_16x16x32_bf16 v[20:23], v[206:209], v[190:193], v[20:23]
	v_mfma_f32_16x16x32_bf16 v[16:19], v[214:217], v[190:193], v[16:19]
	v_mfma_f32_16x16x32_bf16 v[4:7], v[206:209], v[198:201], v[4:7]
	v_mfma_f32_16x16x32_bf16 v[0:3], v[214:217], v[198:201], v[0:3]
	s_add_i32 s49, 0, 0x18000
	v_add_u32_e32 v140, s49, v173
	s_barrier
	ds_read_b128 v[128:131], v140
	ds_read_b128 v[132:135], v140 offset:1024
	ds_read_b128 v[136:139], v140 offset:2048
	ds_read_b128 v[140:143], v140 offset:3072
	s_add_u32 s26, s26, 0x40000
	s_addc_u32 s27, s27, 0
	s_mov_b32 m0, s37
	v_lshl_add_u64 v[202:203], s[26:27], 0, v[144:145]
	ds_read_b128 v[160:163], v180 offset:32768
	ds_read_b128 v[164:167], v180 offset:33792
	ds_read_b128 v[168:171], v180 offset:34816
	ds_read_b128 v[182:185], v180 offset:35840
	ds_read_b128 v[186:189], v180 offset:36864
	ds_read_b128 v[190:193], v180 offset:37888
	ds_read_b128 v[194:197], v180 offset:38912
	ds_read_b128 v[198:201], v180 offset:39936
	global_load_lds_dwordx4 v[202:203], off
	s_mov_b32 m0, s38
	v_lshl_add_u64 v[202:203], s[26:27], 0, v[148:149]
	global_load_lds_dwordx4 v[202:203], off
	s_waitcnt lgkmcnt(8)
	s_barrier
	s_waitcnt lgkmcnt(0)
	v_mfma_f32_16x16x32_bf16 v[124:127], v[128:131], v[160:163], v[124:127]
	v_mfma_f32_16x16x32_bf16 v[120:123], v[136:139], v[160:163], v[120:123]
	v_mfma_f32_16x16x32_bf16 v[116:119], v[128:131], v[168:171], v[116:119]
	v_mfma_f32_16x16x32_bf16 v[104:107], v[136:139], v[168:171], v[104:107]
	v_mfma_f32_16x16x32_bf16 v[92:95], v[128:131], v[186:189], v[92:95]
	v_mfma_f32_16x16x32_bf16 v[88:91], v[136:139], v[186:189], v[88:91]
	v_mfma_f32_16x16x32_bf16 v[76:79], v[128:131], v[194:197], v[76:79]
	v_mfma_f32_16x16x32_bf16 v[72:75], v[136:139], v[194:197], v[72:75]
	v_mfma_f32_16x16x32_bf16 v[124:127], v[132:135], v[164:167], v[124:127]
	v_mfma_f32_16x16x32_bf16 v[120:123], v[140:143], v[164:167], v[120:123]
	v_mfma_f32_16x16x32_bf16 v[116:119], v[132:135], v[182:185], v[116:119]
	v_mfma_f32_16x16x32_bf16 v[104:107], v[140:143], v[182:185], v[104:107]
	v_mfma_f32_16x16x32_bf16 v[92:95], v[132:135], v[190:193], v[92:95]
	v_mfma_f32_16x16x32_bf16 v[88:91], v[140:143], v[190:193], v[88:91]
	v_mfma_f32_16x16x32_bf16 v[76:79], v[132:135], v[198:201], v[76:79]
	v_mfma_f32_16x16x32_bf16 v[72:75], v[140:143], v[198:201], v[72:75]
	s_barrier
	s_add_i32 s26, 0, 0x1c000
	s_add_i32 s27, s49, s34
	v_add_u32_e32 v214, s26, v173
	v_lshl_add_u64 v[218:219], v[218:219], 0, s[10:11]
	s_mov_b32 m0, s27
	ds_read_b128 v[202:205], v214
	ds_read_b128 v[206:209], v214 offset:1024
	ds_read_b128 v[210:213], v214 offset:2048
	ds_read_b128 v[214:217], v214 offset:3072
	global_load_lds_dwordx4 v[218:219], off
	s_add_i32 m0, s27, 0x2000
	v_lshl_add_u64 v[218:219], v[220:221], 0, s[10:11]
	global_load_lds_dwordx4 v[218:219], off
	s_barrier
	s_waitcnt lgkmcnt(0)
	v_mfma_f32_16x16x32_bf16 v[112:115], v[202:205], v[160:163], v[112:115]
	v_mfma_f32_16x16x32_bf16 v[108:111], v[210:213], v[160:163], v[108:111]
	v_mfma_f32_16x16x32_bf16 v[100:103], v[202:205], v[168:171], v[100:103]
	v_mfma_f32_16x16x32_bf16 v[96:99], v[210:213], v[168:171], v[96:99]
	v_mfma_f32_16x16x32_bf16 v[84:87], v[202:205], v[186:189], v[84:87]
	v_mfma_f32_16x16x32_bf16 v[80:83], v[210:213], v[186:189], v[80:83]
	v_mfma_f32_16x16x32_bf16 v[68:71], v[202:205], v[194:197], v[68:71]
	v_mfma_f32_16x16x32_bf16 v[64:67], v[210:213], v[194:197], v[64:67]
	v_mfma_f32_16x16x32_bf16 v[112:115], v[206:209], v[164:167], v[112:115]
	v_mfma_f32_16x16x32_bf16 v[108:111], v[214:217], v[164:167], v[108:111]
	v_mfma_f32_16x16x32_bf16 v[100:103], v[206:209], v[182:185], v[100:103]
	v_mfma_f32_16x16x32_bf16 v[96:99], v[214:217], v[182:185], v[96:99]
	v_mfma_f32_16x16x32_bf16 v[84:87], v[206:209], v[190:193], v[84:87]
	v_mfma_f32_16x16x32_bf16 v[80:83], v[214:217], v[190:193], v[80:83]
	v_mfma_f32_16x16x32_bf16 v[68:71], v[206:209], v[198:201], v[68:71]
	v_mfma_f32_16x16x32_bf16 v[64:67], v[214:217], v[198:201], v[64:67]
	s_mov_b32 m0, s39
	v_lshl_add_u64 v[218:219], v[222:223], 0, s[10:11]
	s_barrier
	ds_read_b128 v[160:163], v180 offset:49152
	ds_read_b128 v[164:167], v180 offset:50176
	ds_read_b128 v[168:171], v180 offset:51200
	ds_read_b128 v[182:185], v180 offset:52224
	ds_read_b128 v[186:189], v180 offset:53248
	ds_read_b128 v[190:193], v180 offset:54272
	ds_read_b128 v[194:197], v180 offset:55296
	ds_read_b128 v[198:201], v180 offset:56320
	global_load_lds_dwordx4 v[218:219], off
	s_mov_b32 m0, s40
	v_lshl_add_u64 v[218:219], v[224:225], 0, s[10:11]
	global_load_lds_dwordx4 v[218:219], off
	s_barrier
; __device__ __forceinline__ unsigned cvt_pk_bf16(float lo, float hi) { unsigned r; asm volatile("v_cvt_pk_bf16_f32 %0, %1, %2" : "=v"(r) : "v"(lo), "v"(hi)); return r; }
; #define PG8_STAGE(bufoff, gbase, voff) do { _Pragma("unroll") for (int _i = 0; _i < 2; ++_i) \
;         __builtin_amdgcn_global_load_lds((const unsigned*)((const char*)(gbase) + (voff)[_i]), (LAS unsigned*)(lds + (bufoff) + ldsw + _i * 8192), 16, 0, 0); } while (0)
; #define PG8_MMA(ai, bj, At, Bt) do { __builtin_amdgcn_s_setprio(1); _Pragma("unroll") for (int m = 0; m < 4; ++m) _Pragma("unroll") for (int n = 0; n < 2; ++n) _Pragma("unroll") for (int k = 0; k < 2; ++k) \
;         acc[ai][bj][m][n] = __builtin_amdgcn_mfma_f32_16x16x32_bf16(Bt[n][k], At[m][k], acc[ai][bj][m][n], 0, 0, 0); __builtin_amdgcn_s_setprio(0); } while (0)
; template <class Epi, class Sched>
; __device__ __forceinline__ void gemm_phase(const int wv, LAS unsigned char* lds, const Gemm g, const Sched& S, const Epi& E) {
;     ...
;             PG8_STAGE(PG8_SB(1, 1), b3 + hstepB, voffB);
;             PG8_WAIT_V(6); PG8_BAR; PG8_MMA(1, 1, At, B1); PG8_BAR;
;         }
;     __device__ __forceinline__ void operator()(const f32x4 (&acc)[2][2][4][2], const Unit& u, int wr, int wc, int fr, int fq) const {
;     ...
;             for (int m = 0; m < 4; ++m)
; #pragma unroll
;                 for (int bj = 0; bj < 2; ++bj) {
;                     const size_t o = (size_t)(row0 + ai * 128 + m * 16) * 1024 + col0 + bj * 128;
;                     xv[m][bj][0] = *(const f32x4*)(x + o); xv[m][bj][1] = *(const f32x4*)(x + o + 4);
;                 }
; #pragma unroll
;             for (int m = 0; m < 4; ++m) {
;                 const int row = row0 + ai * 128 + m * 16; float ss = 0.f;
; #pragma unroll
;                 for (int bj = 0; bj < 2; ++bj) {
;                     const size_t o = (size_t)row * 1024 + col0 + bj * 128;
;                     const f32x4 v0 = xv[m][bj][0] + acc[ai][bj][m][0], v1 = xv[m][bj][1] + acc[ai][bj][m][1];
;                     ss += (v0[0] * v0[0] + v0[1] * v0[1]) + (v0[2] * v0[2] + v0[3] * v0[3]) + (v1[0] * v1[0] + v1[1] * v1[1]) + (v1[2] * v1[2] + v1[3] * v1[3]);
;                     u32x4 w; w.x = cvt_pk_bf16(v0[0], v0[1]); w.y = cvt_pk_bf16(v0[2], v0[3]); w.z = cvt_pk_bf16(v1[0], v1[1]); w.w = cvt_pk_bf16(v1[2], v1[3]);
;                     *(u32x4*)(x1b + o) = w;
	s_waitcnt lgkmcnt(0)
	v_mfma_f32_16x16x32_bf16 v[60:63], v[128:131], v[160:163], v[60:63]
	v_mfma_f32_16x16x32_bf16 v[56:59], v[136:139], v[160:163], v[56:59]
	v_mfma_f32_16x16x32_bf16 v[44:47], v[128:131], v[168:171], v[44:47]
	v_mfma_f32_16x16x32_bf16 v[40:43], v[136:139], v[168:171], v[40:43]
	v_mfma_f32_16x16x32_bf16 v[28:31], v[128:131], v[186:189], v[28:31]
	v_mfma_f32_16x16x32_bf16 v[24:27], v[136:139], v[186:189], v[24:27]
	v_mfma_f32_16x16x32_bf16 v[12:15], v[128:131], v[194:197], v[12:15]
	v_mfma_f32_16x16x32_bf16 v[8:11], v[136:139], v[194:197], v[8:11]
	v_mfma_f32_16x16x32_bf16 v[60:63], v[132:135], v[164:167], v[60:63]
	v_mfma_f32_16x16x32_bf16 v[56:59], v[140:143], v[164:167], v[56:59]
	v_mfma_f32_16x16x32_bf16 v[44:47], v[132:135], v[182:185], v[44:47]
	v_mfma_f32_16x16x32_bf16 v[40:43], v[140:143], v[182:185], v[40:43]
	v_mfma_f32_16x16x32_bf16 v[28:31], v[132:135], v[190:193], v[28:31]
	v_mfma_f32_16x16x32_bf16 v[24:27], v[140:143], v[190:193], v[24:27]
	v_mfma_f32_16x16x32_bf16 v[12:15], v[132:135], v[198:201], v[12:15]
	v_mfma_f32_16x16x32_bf16 v[8:11], v[140:143], v[198:201], v[8:11]
	s_barrier
	s_add_u32 s24, s24, 0x40080
	s_addc_u32 s25, s25, 0
	s_add_i32 s26, s26, s34
	s_mov_b32 m0, s26
	v_lshl_add_u64 v[128:129], s[24:25], 0, v[146:147]
	global_load_lds_dwordx4 v[128:129], off
	s_add_i32 m0, s26, 0x2000
	v_lshl_add_u64 v[128:129], s[24:25], 0, v[150:151]
	global_load_lds_dwordx4 v[128:129], off
	s_waitcnt vmcnt(6)
	s_barrier
	v_mfma_f32_16x16x32_bf16 v[52:55], v[202:205], v[160:163], v[52:55]
	v_mfma_f32_16x16x32_bf16 v[48:51], v[210:213], v[160:163], v[48:51]
	v_mfma_f32_16x16x32_bf16 v[36:39], v[202:205], v[168:171], v[36:39]
	v_mfma_f32_16x16x32_bf16 v[32:35], v[210:213], v[168:171], v[32:35]
	v_mfma_f32_16x16x32_bf16 v[20:23], v[202:205], v[186:189], v[20:23]
	v_mfma_f32_16x16x32_bf16 v[16:19], v[210:213], v[186:189], v[16:19]
	v_mfma_f32_16x16x32_bf16 v[4:7], v[202:205], v[194:197], v[4:7]
	v_mfma_f32_16x16x32_bf16 v[0:3], v[210:213], v[194:197], v[0:3]
	v_mfma_f32_16x16x32_bf16 v[52:55], v[206:209], v[164:167], v[52:55]
	v_mfma_f32_16x16x32_bf16 v[48:51], v[214:217], v[164:167], v[48:51]
	v_mfma_f32_16x16x32_bf16 v[36:39], v[206:209], v[182:185], v[36:39]
	v_mfma_f32_16x16x32_bf16 v[32:35], v[214:217], v[182:185], v[32:35]
	v_mfma_f32_16x16x32_bf16 v[20:23], v[206:209], v[190:193], v[20:23]
	v_mfma_f32_16x16x32_bf16 v[16:19], v[214:217], v[190:193], v[16:19]
	v_mfma_f32_16x16x32_bf16 v[4:7], v[206:209], v[198:201], v[4:7]
	v_mfma_f32_16x16x32_bf16 v[0:3], v[214:217], v[198:201], v[0:3]
	s_add_i32 s48, s48, 2
	s_add_u32 s22, s22, 0x100
	s_addc_u32 s23, s23, 0
	s_add_u32 s46, s46, 0x100
	s_addc_u32 s47, s47, 0
	s_cmp_gt_u32 s48, 13
	s_barrier
	s_cbranch_scc0 .LBB0_661
	v_lshl_add_u32 v162, s20, 8, v172
	v_lshl_or_b32 v128, s21, 8, v174
	v_ashrrev_i32_e32 v129, 31, v128
	v_ashrrev_i32_e32 v163, 31, v162
	v_lshl_add_u64 v[164:165], v[128:129], 2, s[2:3]
	v_lshlrev_b64 v[130:131], 12, v[162:163]
	v_lshl_add_u64 v[130:131], v[164:165], 0, v[130:131]
	global_load_dwordx4 v[182:185], v[130:131], off
	global_load_dwordx4 v[186:189], v[130:131], off offset:16
	global_load_dwordx4 v[190:193], v[130:131], off offset:512
	global_load_dwordx4 v[194:197], v[130:131], off offset:528
	v_or_b32_e32 v170, 16, v162
	v_ashrrev_i32_e32 v171, 31, v170
	v_lshlrev_b64 v[130:131], 12, v[170:171]
	v_lshl_add_u64 v[130:131], v[164:165], 0, v[130:131]
	global_load_dwordx4 v[198:201], v[130:131], off
	global_load_dwordx4 v[202:205], v[130:131], off offset:16
	global_load_dwordx4 v[206:209], v[130:131], off offset:528
	global_load_dwordx4 v[210:213], v[130:131], off offset:512
	v_or_b32_e32 v168, 32, v162
	v_or_b32_e32 v166, 48, v162
	s_lshl_b32 s20, s21, 2
	v_ashrrev_i32_e32 v169, 31, v168
	v_ashrrev_i32_e32 v167, 31, v166
	s_ashr_i32 s21, s20, 31
	v_lshlrev_b64 v[132:133], 11, v[162:163]
	v_lshlrev_b64 v[160:161], 1, v[128:129]
	v_lshlrev_b64 v[128:129], 6, v[162:163]
	v_lshlrev_b64 v[134:135], 12, v[168:169]
	v_lshlrev_b64 v[136:137], 12, v[166:167]
	s_lshl_b64 s[20:21], s[20:21], 2
	v_lshl_add_u64 v[132:133], s[6:7], 0, v[132:133]
	v_lshl_add_u64 v[128:129], s[8:9], 0, v[128:129]
	v_lshl_add_u64 v[130:131], v[164:165], 0, v[134:135]
	v_lshl_add_u64 v[134:135], v[164:165], 0, v[136:137]
	v_lshl_add_u64 v[232:233], v[132:133], 0, v[160:161]
	v_lshl_add_u64 v[234:235], v[128:129], 0, s[20:21]
	global_load_dwordx4 v[214:217], v[130:131], off offset:16
	global_load_dwordx4 v[218:221], v[130:131], off
	global_load_dwordx4 v[222:225], v[130:131], off offset:528
	global_load_dwordx4 v[226:229], v[130:131], off offset:512
	global_load_dwordx4 v[136:139], v[134:135], off offset:16
	global_load_dwordx4 v[140:143], v[134:135], off
	s_nop 0
	global_load_dwordx4 v[128:131], v[134:135], off offset:528
	s_nop 0
	global_load_dwordx4 v[132:135], v[134:135], off offset:512
	v_lshl_add_u64 v[234:235], v[234:235], 0, s[4:5]
	v_lshlrev_b64 v[230:231], 11, v[170:171]
	s_and_b64 vcc, exec, s[0:1]
	s_mov_b64 s[24:25], s[18:19]
	s_mov_b64 s[22:23], s[16:17]
	s_waitcnt vmcnt(15)
	v_pk_add_f32 v[126:127], v[126:127], v[184:185]
	v_pk_add_f32 v[124:125], v[124:125], v[182:183]
	s_waitcnt vmcnt(14)
	v_pk_add_f32 v[122:123], v[122:123], v[188:189]
	v_pk_add_f32 v[120:121], v[120:121], v[186:187]
	s_waitcnt vmcnt(13)
	v_pk_add_f32 v[114:115], v[114:115], v[192:193]
	v_pk_add_f32 v[112:113], v[112:113], v[190:191]
	s_waitcnt vmcnt(12)
; __device__ __forceinline__ float shx(float v, int lane, int mask) { return __int_as_float(__builtin_amdgcn_ds_bpermute((lane ^ mask) << 2, __float_as_int(v))); }
; __device__ __forceinline__ unsigned cvt_pk_bf16(float lo, float hi) { unsigned r; asm volatile("v_cvt_pk_bf16_f32 %0, %1, %2" : "=v"(r) : "v"(lo), "v"(hi)); return r; }
;     __device__ __forceinline__ void operator()(const f32x4 (&acc)[2][2][4][2], const Unit& u, int wr, int wc, int fr, int fq) const {
;     ...
; #pragma unroll
;             for (int m = 0; m < 4; ++m) {
;                 const int row = row0 + ai * 128 + m * 16; float ss = 0.f;
; #pragma unroll
;                 for (int bj = 0; bj < 2; ++bj) {
;                     const size_t o = (size_t)row * 1024 + col0 + bj * 128;
;                     const f32x4 v0 = xv[m][bj][0] + acc[ai][bj][m][0], v1 = xv[m][bj][1] + acc[ai][bj][m][1];
;                     ss += (v0[0] * v0[0] + v0[1] * v0[1]) + (v0[2] * v0[2] + v0[3] * v0[3]) + (v1[0] * v1[0] + v1[1] * v1[1]) + (v1[2] * v1[2] + v1[3] * v1[3]);
;                     u32x4 w; w.x = cvt_pk_bf16(v0[0], v0[1]); w.y = cvt_pk_bf16(v0[2], v0[3]); w.z = cvt_pk_bf16(v1[0], v1[1]); w.w = cvt_pk_bf16(v1[2], v1[3]);
;                     *(u32x4*)(x1b + o) = w;
;                 }
;                 ss += shx(ss, fq * 16 + fr, 16); ss += shx(ss, fq * 16 + fr, 32);
;                 ss2[(size_t)row * 16 + u.pn * 4 + wc] = ss;
	v_pk_add_f32 v[182:183], v[110:111], v[196:197]
	v_pk_add_f32 v[184:185], v[108:109], v[194:195]
	v_mul_f32_e32 v163, v125, v125
	v_mul_f32_e32 v190, v127, v127
	v_mul_f32_e32 v191, v121, v121
	v_mul_f32_e32 v192, v123, v123
	v_cvt_pk_bf16_f32 v108, v124, v125
	v_cvt_pk_bf16_f32 v109, v126, v127
	v_cvt_pk_bf16_f32 v110, v120, v121
	v_cvt_pk_bf16_f32 v111, v122, v123
	v_mul_f32_e32 v121, v113, v113
	v_mul_f32_e32 v123, v115, v115
	v_mul_f32_e32 v125, v185, v185
	v_fmac_f32_e32 v163, v124, v124
	v_fmac_f32_e32 v190, v126, v126
	v_fmac_f32_e32 v121, v112, v112
	v_fmac_f32_e32 v123, v114, v114
	v_mul_f32_e32 v127, v183, v183
	v_fmac_f32_e32 v191, v120, v120
	global_store_dwordx4 v[232:233], v[108:111], off
	v_fmac_f32_e32 v125, v184, v184
	v_fmac_f32_e32 v192, v122, v122
	v_add_f32_e32 v108, v163, v190
	v_add_f32_e32 v109, v121, v123
	v_fmac_f32_e32 v127, v182, v182
	v_add_f32_e32 v108, v108, v191
	v_add_f32_e32 v109, v109, v125
	v_add_f32_e32 v108, v192, v108
	v_add_f32_e32 v109, v127, v109
	v_add_f32_e32 v108, v108, v109
	ds_bpermute_b32 v109, v175, v108
	s_waitcnt vmcnt(11)
	v_pk_add_f32 v[188:189], v[104:105], v[202:203]
	v_cvt_pk_bf16_f32 v104, v112, v113
	v_pk_add_f32 v[186:187], v[106:107], v[204:205]
	v_cvt_pk_bf16_f32 v105, v114, v115
	v_cvt_pk_bf16_f32 v106, v184, v185
	v_cvt_pk_bf16_f32 v107, v182, v183
	global_store_dwordx4 v[232:233], v[104:107], off offset:256
	s_waitcnt vmcnt(10)
	v_pk_add_f32 v[102:103], v[102:103], v[212:213]
	v_pk_add_f32 v[100:101], v[100:101], v[210:211]
	s_waitcnt lgkmcnt(0)
	v_add_f32_e32 v104, v108, v109
	ds_bpermute_b32 v105, v176, v104
	v_pk_add_f32 v[108:109], v[98:99], v[208:209]
	v_pk_add_f32 v[98:99], v[96:97], v[206:207]
	v_mul_f32_e32 v96, v101, v101
	v_mul_f32_e32 v97, v103, v103
	v_pk_add_f32 v[118:119], v[118:119], v[200:201]
	v_pk_add_f32 v[116:117], v[116:117], v[198:199]
	v_fmac_f32_e32 v96, v100, v100
	v_fmac_f32_e32 v97, v102, v102
	v_mul_f32_e32 v110, v117, v117
	v_mul_f32_e32 v111, v119, v119
	v_add_f32_e32 v96, v96, v97
	v_mul_f32_e32 v97, v99, v99
	v_mul_f32_e32 v112, v189, v189
	v_fmac_f32_e32 v110, v116, v116
	v_fmac_f32_e32 v111, v118, v118
	v_fmac_f32_e32 v97, v98, v98
	v_fmac_f32_e32 v112, v188, v188
	v_add_f32_e32 v106, v110, v111
	s_waitcnt lgkmcnt(0)
	v_add_f32_e32 v104, v104, v105
	v_mul_f32_e32 v105, v187, v187
	v_add_f32_e32 v96, v96, v97
	v_mul_f32_e32 v97, v109, v109
	global_store_dword v[234:235], v104, off
	v_add_f32_e32 v104, v106, v112
	v_fmac_f32_e32 v105, v186, v186
	v_fmac_f32_e32 v97, v108, v108
	v_add_f32_e32 v110, v105, v104
	v_add_f32_e32 v96, v97, v96
	v_add_f32_e32 v112, v110, v96
	ds_bpermute_b32 v113, v175, v112
	v_lshl_add_u64 v[96:97], s[6:7], 0, v[230:231]
	v_lshl_add_u64 v[110:111], v[96:97], 0, v[160:161]
	v_cvt_pk_bf16_f32 v104, v116, v117
	v_cvt_pk_bf16_f32 v105, v118, v119
	v_cvt_pk_bf16_f32 v106, v188, v189
	v_cvt_pk_bf16_f32 v107, v186, v187
	global_store_dwordx4 v[110:111], v[104:107], off
	v_cvt_pk_bf16_f32 v96, v100, v101
	s_waitcnt lgkmcnt(0)
	v_add_f32_e32 v100, v112, v113
	ds_bpermute_b32 v101, v176, v100
	v_cvt_pk_bf16_f32 v97, v102, v103
	v_cvt_pk_bf16_f32 v98, v98, v99
	v_cvt_pk_bf16_f32 v99, v108, v109
	global_store_dwordx4 v[110:111], v[96:99], off offset:256
	s_waitcnt vmcnt(11)
	v_pk_add_f32 v[94:95], v[94:95], v[220:221]
	v_pk_add_f32 v[92:93], v[92:93], v[218:219]
	v_lshlrev_b64 v[96:97], 6, v[170:171]
	v_lshl_add_u64 v[96:97], s[8:9], 0, v[96:97]
	v_lshl_add_u64 v[96:97], v[96:97], 0, s[20:21]
	s_waitcnt lgkmcnt(0)
	v_add_f32_e32 v98, v100, v101
	v_lshl_add_u64 v[96:97], v[96:97], 0, s[4:5]
	global_store_dword v[96:97], v98, off
	v_pk_add_f32 v[98:99], v[90:91], v[216:217]
	v_pk_add_f32 v[90:91], v[88:89], v[214:215]
	v_mul_f32_e32 v88, v93, v93
	v_mul_f32_e32 v89, v95, v95
	v_fmac_f32_e32 v88, v92, v92
	v_fmac_f32_e32 v89, v94, v94
	v_add_f32_e32 v88, v88, v89
	v_mul_f32_e32 v89, v91, v91
	v_fmac_f32_e32 v89, v90, v90
	v_add_f32_e32 v88, v88, v89
	v_mul_f32_e32 v89, v99, v99
	v_fmac_f32_e32 v89, v98, v98
	s_waitcnt vmcnt(10)
	v_pk_add_f32 v[86:87], v[86:87], v[228:229]
	v_pk_add_f32 v[84:85], v[84:85], v[226:227]
	v_add_f32_e32 v100, v89, v88
	v_cvt_pk_bf16_f32 v88, v92, v93
	v_pk_add_f32 v[92:93], v[82:83], v[224:225]
	v_pk_add_f32 v[82:83], v[80:81], v[222:223]
	v_mul_f32_e32 v80, v85, v85
	v_mul_f32_e32 v81, v87, v87
	v_fmac_f32_e32 v80, v84, v84
	v_fmac_f32_e32 v81, v86, v86
	v_add_f32_e32 v80, v80, v81
	v_mul_f32_e32 v81, v83, v83
	v_fmac_f32_e32 v81, v82, v82
	v_add_f32_e32 v80, v80, v81
	v_mul_f32_e32 v81, v93, v93
	v_fmac_f32_e32 v81, v92, v92
	v_add_f32_e32 v80, v81, v80
	v_cvt_pk_bf16_f32 v89, v94, v95
	v_cvt_pk_bf16_f32 v90, v90, v91
	v_cvt_pk_bf16_f32 v91, v98, v99
	v_add_f32_e32 v98, v100, v80
	ds_bpermute_b32 v99, v175, v98
	v_lshlrev_b64 v[96:97], 11, v[168:169]
	v_lshl_add_u64 v[80:81], s[6:7], 0, v[96:97]
	v_lshl_add_u64 v[94:95], v[80:81], 0, v[160:161]
	global_store_dwordx4 v[94:95], v[88:91], off
	v_cvt_pk_bf16_f32 v80, v84, v85
	s_waitcnt lgkmcnt(0)
	v_add_f32_e32 v84, v98, v99
	ds_bpermute_b32 v85, v176, v84
	v_cvt_pk_bf16_f32 v81, v86, v87
	v_cvt_pk_bf16_f32 v82, v82, v83
	v_cvt_pk_bf16_f32 v83, v92, v93
	global_store_dwordx4 v[94:95], v[80:83], off offset:256
	s_waitcnt vmcnt(10)
	v_pk_add_f32 v[78:79], v[78:79], v[142:143]
	v_pk_add_f32 v[76:77], v[76:77], v[140:141]
	v_lshlrev_b64 v[80:81], 6, v[168:169]
	v_lshl_add_u64 v[80:81], s[8:9], 0, v[80:81]
	v_lshl_add_u64 v[80:81], v[80:81], 0, s[20:21]
	s_waitcnt lgkmcnt(0)
; __device__ __forceinline__ float shx(float v, int lane, int mask) { return __int_as_float(__builtin_amdgcn_ds_bpermute((lane ^ mask) << 2, __float_as_int(v))); }
; __device__ __forceinline__ unsigned cvt_pk_bf16(float lo, float hi) { unsigned r; asm volatile("v_cvt_pk_bf16_f32 %0, %1, %2" : "=v"(r) : "v"(lo), "v"(hi)); return r; }
;     __device__ __forceinline__ void operator()(const f32x4 (&acc)[2][2][4][2], const Unit& u, int wr, int wc, int fr, int fq) const {
;     ...
;         for (int ai = 0; ai < 2; ++ai) {
;             f32x4 xv[4][2][2];
; #pragma unroll
;             for (int m = 0; m < 4; ++m)
; #pragma unroll
;                 for (int bj = 0; bj < 2; ++bj) {
;                     const size_t o = (size_t)(row0 + ai * 128 + m * 16) * 1024 + col0 + bj * 128;
;                     xv[m][bj][0] = *(const f32x4*)(x + o); xv[m][bj][1] = *(const f32x4*)(x + o + 4);
;                 }
; #pragma unroll
;             for (int m = 0; m < 4; ++m) {
;                 const int row = row0 + ai * 128 + m * 16; float ss = 0.f;
; #pragma unroll
;                 for (int bj = 0; bj < 2; ++bj) {
;                     const size_t o = (size_t)row * 1024 + col0 + bj * 128;
;                     const f32x4 v0 = xv[m][bj][0] + acc[ai][bj][m][0], v1 = xv[m][bj][1] + acc[ai][bj][m][1];
;                     ss += (v0[0] * v0[0] + v0[1] * v0[1]) + (v0[2] * v0[2] + v0[3] * v0[3]) + (v1[0] * v1[0] + v1[1] * v1[1]) + (v1[2] * v1[2] + v1[3] * v1[3]);
;                     u32x4 w; w.x = cvt_pk_bf16(v0[0], v0[1]); w.y = cvt_pk_bf16(v0[2], v0[3]); w.z = cvt_pk_bf16(v1[0], v1[1]); w.w = cvt_pk_bf16(v1[2], v1[3]);
;                     *(u32x4*)(x1b + o) = w;
;                 }
;                 ss += shx(ss, fq * 16 + fr, 16); ss += shx(ss, fq * 16 + fr, 32);
;                 ss2[(size_t)row * 16 + u.pn * 4 + wc] = ss;
;             }
	v_add_f32_e32 v82, v84, v85
	v_lshl_add_u64 v[80:81], v[80:81], 0, s[4:5]
	global_store_dword v[80:81], v82, off
	v_pk_add_f32 v[82:83], v[74:75], v[138:139]
	v_pk_add_f32 v[74:75], v[72:73], v[136:137]
	v_mul_f32_e32 v72, v77, v77
	v_mul_f32_e32 v73, v79, v79
	v_fmac_f32_e32 v72, v76, v76
	v_fmac_f32_e32 v73, v78, v78
	v_add_f32_e32 v72, v72, v73
	v_mul_f32_e32 v73, v75, v75
	v_fmac_f32_e32 v73, v74, v74
	v_add_f32_e32 v72, v72, v73
	v_mul_f32_e32 v73, v83, v83
	v_fmac_f32_e32 v73, v82, v82
	s_waitcnt vmcnt(9)
	v_pk_add_f32 v[70:71], v[70:71], v[134:135]
	v_pk_add_f32 v[68:69], v[68:69], v[132:133]
	v_add_f32_e32 v84, v73, v72
	v_cvt_pk_bf16_f32 v72, v76, v77
	v_pk_add_f32 v[76:77], v[66:67], v[130:131]
	v_pk_add_f32 v[66:67], v[64:65], v[128:129]
	v_mul_f32_e32 v64, v69, v69
	v_mul_f32_e32 v65, v71, v71
	v_fmac_f32_e32 v64, v68, v68
	v_fmac_f32_e32 v65, v70, v70
	v_add_f32_e32 v64, v64, v65
	v_mul_f32_e32 v65, v67, v67
	v_fmac_f32_e32 v65, v66, v66
	v_add_f32_e32 v64, v64, v65
	v_mul_f32_e32 v65, v77, v77
	v_fmac_f32_e32 v65, v76, v76
	v_add_f32_e32 v64, v65, v64
	v_cvt_pk_bf16_f32 v73, v78, v79
	v_cvt_pk_bf16_f32 v74, v74, v75
	v_cvt_pk_bf16_f32 v75, v82, v83
	v_add_f32_e32 v82, v84, v64
	ds_bpermute_b32 v83, v175, v82
	v_lshlrev_b64 v[80:81], 11, v[166:167]
	v_lshl_add_u64 v[64:65], s[6:7], 0, v[80:81]
	v_lshl_add_u64 v[78:79], v[64:65], 0, v[160:161]
	global_store_dwordx4 v[78:79], v[72:75], off
	v_cvt_pk_bf16_f32 v64, v68, v69
	s_waitcnt lgkmcnt(0)
	v_add_f32_e32 v68, v82, v83
	ds_bpermute_b32 v69, v176, v68
	v_cvt_pk_bf16_f32 v65, v70, v71
	v_cvt_pk_bf16_f32 v66, v66, v67
	v_cvt_pk_bf16_f32 v67, v76, v77
	global_store_dwordx4 v[78:79], v[64:67], off offset:256
	v_add_u32_e32 v132, 0x80, v162
	v_ashrrev_i32_e32 v133, 31, v132
	v_lshlrev_b64 v[64:65], 6, v[166:167]
	v_lshl_add_u64 v[64:65], s[8:9], 0, v[64:65]
	v_lshl_add_u64 v[64:65], v[64:65], 0, s[20:21]
	s_waitcnt lgkmcnt(0)
	v_add_f32_e32 v66, v68, v69
	v_lshl_add_u64 v[64:65], v[64:65], 0, s[4:5]
	global_store_dword v[64:65], v66, off
	v_lshlrev_b64 v[64:65], 12, v[132:133]
	v_lshl_add_u64 v[64:65], v[164:165], 0, v[64:65]
	global_load_dwordx4 v[92:95], v[64:65], off
	global_load_dwordx4 v[96:99], v[64:65], off offset:16
	global_load_dwordx4 v[100:103], v[64:65], off offset:512
	global_load_dwordx4 v[104:107], v[64:65], off offset:528
	v_add_u32_e32 v134, 0x90, v162
	v_ashrrev_i32_e32 v135, 31, v134
	v_lshlrev_b64 v[64:65], 12, v[134:135]
	v_lshl_add_u64 v[64:65], v[164:165], 0, v[64:65]
	global_load_dwordx4 v[108:111], v[64:65], off
	global_load_dwordx4 v[112:115], v[64:65], off offset:16
	global_load_dwordx4 v[116:119], v[64:65], off offset:528
	global_load_dwordx4 v[120:123], v[64:65], off offset:512
	v_add_u32_e32 v90, 0xa0, v162
	v_ashrrev_i32_e32 v91, 31, v90
	v_lshlrev_b64 v[64:65], 12, v[90:91]
	v_lshl_add_u64 v[64:65], v[164:165], 0, v[64:65]
	global_load_dwordx4 v[124:127], v[64:65], off offset:16
	global_load_dwordx4 v[128:131], v[64:65], off
	global_load_dwordx4 v[80:83], v[64:65], off offset:528
	global_load_dwordx4 v[84:87], v[64:65], off offset:512
	v_add_u32_e32 v88, 0xb0, v162
	v_ashrrev_i32_e32 v89, 31, v88
	v_lshlrev_b64 v[64:65], 12, v[88:89]
	v_lshl_add_u64 v[68:69], v[164:165], 0, v[64:65]
	global_load_dwordx4 v[72:75], v[68:69], off offset:16
	global_load_dwordx4 v[76:79], v[68:69], off
	global_load_dwordx4 v[64:67], v[68:69], off offset:528
	s_nop 0
	global_load_dwordx4 v[68:71], v[68:69], off offset:512
	v_lshlrev_b64 v[136:137], 11, v[132:133]
	s_waitcnt vmcnt(15)
	v_pk_add_f32 v[62:63], v[62:63], v[94:95]
	v_pk_add_f32 v[60:61], v[60:61], v[92:93]
	s_waitcnt vmcnt(14)
	v_pk_add_f32 v[92:93], v[58:59], v[98:99]
	v_pk_add_f32 v[58:59], v[56:57], v[96:97]
	v_mul_f32_e32 v56, v61, v61
	v_mul_f32_e32 v57, v63, v63
	v_fmac_f32_e32 v56, v60, v60
	v_fmac_f32_e32 v57, v62, v62
	v_add_f32_e32 v56, v56, v57
	v_mul_f32_e32 v57, v59, v59
	v_fmac_f32_e32 v57, v58, v58
	v_add_f32_e32 v56, v56, v57
	v_mul_f32_e32 v57, v93, v93
	v_fmac_f32_e32 v57, v92, v92
	s_waitcnt vmcnt(13)
	v_pk_add_f32 v[54:55], v[54:55], v[102:103]
	v_pk_add_f32 v[52:53], v[52:53], v[100:101]
	v_add_f32_e32 v94, v57, v56
	v_cvt_pk_bf16_f32 v56, v60, v61
	s_waitcnt vmcnt(12)
	v_pk_add_f32 v[60:61], v[50:51], v[106:107]
	v_pk_add_f32 v[50:51], v[48:49], v[104:105]
	v_mul_f32_e32 v48, v53, v53
	v_mul_f32_e32 v49, v55, v55
	v_fmac_f32_e32 v48, v52, v52
	v_fmac_f32_e32 v49, v54, v54
	v_add_f32_e32 v48, v48, v49
	v_mul_f32_e32 v49, v51, v51
	v_fmac_f32_e32 v49, v50, v50
	v_add_f32_e32 v48, v48, v49
	v_mul_f32_e32 v49, v61, v61
	v_fmac_f32_e32 v49, v60, v60
	v_add_f32_e32 v48, v49, v48
	v_cvt_pk_bf16_f32 v57, v62, v63
	v_cvt_pk_bf16_f32 v58, v58, v59
	v_cvt_pk_bf16_f32 v59, v92, v93
	v_add_f32_e32 v92, v94, v48
	ds_bpermute_b32 v93, v175, v92
	v_lshl_add_u64 v[48:49], s[6:7], 0, v[136:137]
	v_lshl_add_u64 v[62:63], v[48:49], 0, v[160:161]
	global_store_dwordx4 v[62:63], v[56:59], off
	v_cvt_pk_bf16_f32 v48, v52, v53
	s_waitcnt lgkmcnt(0)
	v_add_f32_e32 v52, v92, v93
	ds_bpermute_b32 v53, v176, v52
	v_cvt_pk_bf16_f32 v49, v54, v55
	v_cvt_pk_bf16_f32 v50, v50, v51
	v_cvt_pk_bf16_f32 v51, v60, v61
	global_store_dwordx4 v[62:63], v[48:51], off offset:256
	s_waitcnt vmcnt(13)
	v_pk_add_f32 v[46:47], v[46:47], v[110:111]
	v_pk_add_f32 v[44:45], v[44:45], v[108:109]
	v_lshlrev_b64 v[48:49], 6, v[132:133]
	v_lshl_add_u64 v[48:49], s[8:9], 0, v[48:49]
	v_lshl_add_u64 v[48:49], v[48:49], 0, s[20:21]
	s_waitcnt lgkmcnt(0)
	v_add_f32_e32 v50, v52, v53
	v_lshl_add_u64 v[48:49], v[48:49], 0, s[4:5]
	global_store_dword v[48:49], v50, off
	s_waitcnt vmcnt(13)
; __device__ __forceinline__ float shx(float v, int lane, int mask) { return __int_as_float(__builtin_amdgcn_ds_bpermute((lane ^ mask) << 2, __float_as_int(v))); }
; __device__ __forceinline__ unsigned cvt_pk_bf16(float lo, float hi) { unsigned r; asm volatile("v_cvt_pk_bf16_f32 %0, %1, %2" : "=v"(r) : "v"(lo), "v"(hi)); return r; }
; #define PG8_WAIT_V(n) asm volatile("s_waitcnt vmcnt(" #n ")" ::: "memory")
; #define PG8_BAR __builtin_amdgcn_s_barrier()
; template <class Epi, class Sched>
; __device__ __forceinline__ void gemm_phase(const int wv, LAS unsigned char* lds, const Gemm g, const Sched& S, const Epi& E) {
;     ...
;     PG8_WAIT_V(0);
;     if (wr == 0) PG8_BAR;
;     PG8_BAR;
;     __device__ __forceinline__ void operator()(const f32x4 (&acc)[2][2][4][2], const Unit& u, int wr, int wc, int fr, int fq) const {
;     ...
;             for (int m = 0; m < 4; ++m) {
;                 const int row = row0 + ai * 128 + m * 16; float ss = 0.f;
; #pragma unroll
;                 for (int bj = 0; bj < 2; ++bj) {
;                     const size_t o = (size_t)row * 1024 + col0 + bj * 128;
;                     const f32x4 v0 = xv[m][bj][0] + acc[ai][bj][m][0], v1 = xv[m][bj][1] + acc[ai][bj][m][1];
;                     ss += (v0[0] * v0[0] + v0[1] * v0[1]) + (v0[2] * v0[2] + v0[3] * v0[3]) + (v1[0] * v1[0] + v1[1] * v1[1]) + (v1[2] * v1[2] + v1[3] * v1[3]);
;                     u32x4 w; w.x = cvt_pk_bf16(v0[0], v0[1]); w.y = cvt_pk_bf16(v0[2], v0[3]); w.z = cvt_pk_bf16(v1[0], v1[1]); w.w = cvt_pk_bf16(v1[2], v1[3]);
;                     *(u32x4*)(x1b + o) = w;
;                 }
;                 ss += shx(ss, fq * 16 + fr, 16); ss += shx(ss, fq * 16 + fr, 32);
;                 ss2[(size_t)row * 16 + u.pn * 4 + wc] = ss;
;             }
	v_pk_add_f32 v[50:51], v[42:43], v[114:115]
	v_pk_add_f32 v[42:43], v[40:41], v[112:113]
	v_mul_f32_e32 v40, v45, v45
	v_mul_f32_e32 v41, v47, v47
	v_fmac_f32_e32 v40, v44, v44
	v_fmac_f32_e32 v41, v46, v46
	v_add_f32_e32 v40, v40, v41
	v_mul_f32_e32 v41, v43, v43
	v_fmac_f32_e32 v41, v42, v42
	v_add_f32_e32 v40, v40, v41
	v_mul_f32_e32 v41, v51, v51
	v_fmac_f32_e32 v41, v50, v50
	s_waitcnt vmcnt(11)
	v_pk_add_f32 v[38:39], v[38:39], v[122:123]
	v_pk_add_f32 v[36:37], v[36:37], v[120:121]
	v_add_f32_e32 v52, v41, v40
	v_cvt_pk_bf16_f32 v40, v44, v45
	v_pk_add_f32 v[44:45], v[34:35], v[118:119]
	v_pk_add_f32 v[34:35], v[32:33], v[116:117]
	v_mul_f32_e32 v32, v37, v37
	v_mul_f32_e32 v33, v39, v39
	v_fmac_f32_e32 v32, v36, v36
	v_fmac_f32_e32 v33, v38, v38
	v_add_f32_e32 v32, v32, v33
	v_mul_f32_e32 v33, v35, v35
	v_fmac_f32_e32 v33, v34, v34
	v_add_f32_e32 v32, v32, v33
	v_mul_f32_e32 v33, v45, v45
	v_fmac_f32_e32 v33, v44, v44
	v_add_f32_e32 v32, v33, v32
	v_cvt_pk_bf16_f32 v41, v46, v47
	v_cvt_pk_bf16_f32 v42, v42, v43
	v_cvt_pk_bf16_f32 v43, v50, v51
	v_add_f32_e32 v50, v52, v32
	ds_bpermute_b32 v51, v175, v50
	v_lshlrev_b64 v[48:49], 11, v[134:135]
	v_lshl_add_u64 v[32:33], s[6:7], 0, v[48:49]
	v_lshl_add_u64 v[46:47], v[32:33], 0, v[160:161]
	global_store_dwordx4 v[46:47], v[40:43], off
	v_cvt_pk_bf16_f32 v32, v36, v37
	s_waitcnt lgkmcnt(0)
	v_add_f32_e32 v36, v50, v51
	ds_bpermute_b32 v37, v176, v36
	v_cvt_pk_bf16_f32 v33, v38, v39
	v_cvt_pk_bf16_f32 v34, v34, v35
	v_cvt_pk_bf16_f32 v35, v44, v45
	global_store_dwordx4 v[46:47], v[32:35], off offset:256
	s_waitcnt vmcnt(11)
	v_pk_add_f32 v[30:31], v[30:31], v[130:131]
	v_pk_add_f32 v[28:29], v[28:29], v[128:129]
	v_lshlrev_b64 v[32:33], 6, v[134:135]
	v_lshl_add_u64 v[32:33], s[8:9], 0, v[32:33]
	v_lshl_add_u64 v[32:33], v[32:33], 0, s[20:21]
	s_waitcnt lgkmcnt(0)
	v_add_f32_e32 v34, v36, v37
	v_lshl_add_u64 v[32:33], v[32:33], 0, s[4:5]
	global_store_dword v[32:33], v34, off
	v_pk_add_f32 v[34:35], v[26:27], v[126:127]
	v_pk_add_f32 v[26:27], v[24:25], v[124:125]
	v_mul_f32_e32 v24, v29, v29
	v_mul_f32_e32 v25, v31, v31
	v_fmac_f32_e32 v24, v28, v28
	v_fmac_f32_e32 v25, v30, v30
	v_add_f32_e32 v24, v24, v25
	v_mul_f32_e32 v25, v27, v27
	v_fmac_f32_e32 v25, v26, v26
	v_add_f32_e32 v24, v24, v25
	v_mul_f32_e32 v25, v35, v35
	v_fmac_f32_e32 v25, v34, v34
	s_waitcnt vmcnt(10)
	v_pk_add_f32 v[22:23], v[22:23], v[86:87]
	v_pk_add_f32 v[20:21], v[20:21], v[84:85]
	v_add_f32_e32 v36, v25, v24
	v_cvt_pk_bf16_f32 v24, v28, v29
	v_pk_add_f32 v[28:29], v[18:19], v[82:83]
	v_pk_add_f32 v[18:19], v[16:17], v[80:81]
	v_mul_f32_e32 v16, v21, v21
	v_mul_f32_e32 v17, v23, v23
	v_fmac_f32_e32 v16, v20, v20
	v_fmac_f32_e32 v17, v22, v22
	v_add_f32_e32 v16, v16, v17
	v_mul_f32_e32 v17, v19, v19
	v_fmac_f32_e32 v17, v18, v18
	v_add_f32_e32 v16, v16, v17
	v_mul_f32_e32 v17, v29, v29
	v_fmac_f32_e32 v17, v28, v28
	v_add_f32_e32 v16, v17, v16
	v_cvt_pk_bf16_f32 v25, v30, v31
	v_cvt_pk_bf16_f32 v26, v26, v27
	v_cvt_pk_bf16_f32 v27, v34, v35
	v_add_f32_e32 v34, v36, v16
	ds_bpermute_b32 v35, v175, v34
	v_lshlrev_b64 v[32:33], 11, v[90:91]
	v_lshl_add_u64 v[16:17], s[6:7], 0, v[32:33]
	v_lshl_add_u64 v[30:31], v[16:17], 0, v[160:161]
	global_store_dwordx4 v[30:31], v[24:27], off
	v_cvt_pk_bf16_f32 v16, v20, v21
	s_waitcnt lgkmcnt(0)
	v_add_f32_e32 v20, v34, v35
	ds_bpermute_b32 v21, v176, v20
	v_cvt_pk_bf16_f32 v17, v22, v23
	v_cvt_pk_bf16_f32 v18, v18, v19
	v_cvt_pk_bf16_f32 v19, v28, v29
	global_store_dwordx4 v[30:31], v[16:19], off offset:256
	s_waitcnt vmcnt(10)
	v_pk_add_f32 v[14:15], v[14:15], v[78:79]
	v_pk_add_f32 v[12:13], v[12:13], v[76:77]
	v_lshlrev_b64 v[16:17], 6, v[90:91]
	v_lshl_add_u64 v[16:17], s[8:9], 0, v[16:17]
	v_lshl_add_u64 v[16:17], v[16:17], 0, s[20:21]
	s_waitcnt lgkmcnt(0)
	v_add_f32_e32 v18, v20, v21
	v_lshl_add_u64 v[16:17], v[16:17], 0, s[4:5]
	global_store_dword v[16:17], v18, off
	v_pk_add_f32 v[18:19], v[10:11], v[74:75]
	v_pk_add_f32 v[10:11], v[8:9], v[72:73]
	v_mul_f32_e32 v8, v13, v13
	v_mul_f32_e32 v9, v15, v15
	v_fmac_f32_e32 v8, v12, v12
	v_fmac_f32_e32 v9, v14, v14
	v_add_f32_e32 v8, v8, v9
	v_mul_f32_e32 v9, v11, v11
	v_fmac_f32_e32 v9, v10, v10
	v_add_f32_e32 v8, v8, v9
	v_mul_f32_e32 v9, v19, v19
	v_fmac_f32_e32 v9, v18, v18
	s_waitcnt vmcnt(9)
	v_pk_add_f32 v[6:7], v[6:7], v[70:71]
	v_pk_add_f32 v[4:5], v[4:5], v[68:69]
	v_add_f32_e32 v20, v9, v8
	v_cvt_pk_bf16_f32 v8, v12, v13
	v_pk_add_f32 v[12:13], v[2:3], v[66:67]
	v_pk_add_f32 v[2:3], v[0:1], v[64:65]
	v_mul_f32_e32 v0, v5, v5
	v_mul_f32_e32 v1, v7, v7
	v_fmac_f32_e32 v0, v4, v4
	v_fmac_f32_e32 v1, v6, v6
	v_add_f32_e32 v0, v0, v1
	v_mul_f32_e32 v1, v3, v3
	v_fmac_f32_e32 v1, v2, v2
	v_add_f32_e32 v0, v0, v1
	v_mul_f32_e32 v1, v13, v13
	v_fmac_f32_e32 v1, v12, v12
	v_add_f32_e32 v0, v1, v0
	v_cvt_pk_bf16_f32 v9, v14, v15
	v_cvt_pk_bf16_f32 v10, v10, v11
	v_cvt_pk_bf16_f32 v11, v18, v19
	v_add_f32_e32 v18, v20, v0
	ds_bpermute_b32 v19, v175, v18
	v_lshlrev_b64 v[16:17], 11, v[88:89]
	v_lshl_add_u64 v[0:1], s[6:7], 0, v[16:17]
	v_lshl_add_u64 v[14:15], v[0:1], 0, v[160:161]
	global_store_dwordx4 v[14:15], v[8:11], off
	v_cvt_pk_bf16_f32 v0, v4, v5
	s_waitcnt lgkmcnt(0)
	v_add_f32_e32 v4, v18, v19
	ds_bpermute_b32 v5, v176, v4
	v_cvt_pk_bf16_f32 v1, v6, v7
	v_cvt_pk_bf16_f32 v2, v2, v3
	v_cvt_pk_bf16_f32 v3, v12, v13
	global_store_dwordx4 v[14:15], v[0:3], off offset:256
	s_nop 1
	v_lshlrev_b64 v[0:1], 6, v[88:89]
	v_lshl_add_u64 v[0:1], s[8:9], 0, v[0:1]
	v_lshl_add_u64 v[0:1], v[0:1], 0, s[20:21]
	s_waitcnt lgkmcnt(0)
	v_add_f32_e32 v2, v4, v5
	v_lshl_add_u64 v[0:1], v[0:1], 0, s[4:5]
	s_mov_b32 s21, s12
	s_mov_b32 s20, s14
	global_store_dword v[0:1], v2, off
	s_cbranch_vccz .LBB0_654
	s_waitcnt vmcnt(0)
	s_cmpk_gt_u32 s28, 0xff
	s_cbranch_scc1 .LBB0_665
	s_barrier

; #define PG8_STAGE(bufoff, gbase, voff) do { _Pragma("unroll") for (int _i = 0; _i < 2; ++_i) \
;         __builtin_amdgcn_global_load_lds((const unsigned*)((const char*)(gbase) + (voff)[_i]), (LAS unsigned*)(lds + (bufoff) + ldsw + _i * 8192), 16, 0, 0); } while (0)
; #define PG8_LDA(dst, b, h) do { _Pragma("unroll") for (int m = 0; m < 4; ++m) _Pragma("unroll") for (int k = 0; k < 2; ++k) dst[m][k] = *(const LAS bf16x8*)(lds + PG8_SA(b, h) + aoff + m * 2048 + k * 1024); } while (0)
; #define PG8_LDB(dst, b, h) do { _Pragma("unroll") for (int n = 0; n < 2; ++n) _Pragma("unroll") for (int k = 0; k < 2; ++k) dst[n][k] = *(const LAS bf16x8*)(lds + PG8_SB(b, h) + boff + n * 2048 + k * 1024); } while (0)
; #define PG8_MMA(ai, bj, At, Bt) do { __builtin_amdgcn_s_setprio(1); _Pragma("unroll") for (int m = 0; m < 4; ++m) _Pragma("unroll") for (int n = 0; n < 2; ++n) _Pragma("unroll") for (int k = 0; k < 2; ++k) \
;         acc[ai][bj][m][n] = __builtin_amdgcn_mfma_f32_16x16x32_bf16(Bt[n][k], At[m][k], acc[ai][bj][m][n], 0, 0, 0); __builtin_amdgcn_s_setprio(0); } while (0)
; #define PG8_WAIT_V(n) asm volatile("s_waitcnt vmcnt(" #n ")" ::: "memory")
; #define PG8_WAIT_L(n) asm volatile("s_waitcnt lgkmcnt(" #n ")" ::: "memory")
; #define PG8_BAR __builtin_amdgcn_s_barrier()
; #define PG8_SCHED __builtin_amdgcn_sched_barrier(0)
; template <class Epi, class Sched>
; __device__ __forceinline__ void gemm_phase(const int wv, LAS unsigned char* lds, const Gemm g, const Sched& S, const Epi& E) {
;     ...
;             PG8_LDB(B0, 0, 0); PG8_SCHED; PG8_LDA(At, 0, 0); PG8_STAGE(PG8_SA(1, 1), a1 + hstepA, voffA);
;             PG8_WAIT_L(8); PG8_BAR; PG8_WAIT_L(0); PG8_MMA(0, 0, At, B0); PG8_BAR; PG8_SCHED;
;             PG8_LDB(B1, 0, 1); PG8_STAGE(PG8_SB(0, 0), b2, voffB);
;             PG8_BAR; PG8_WAIT_L(0); PG8_MMA(0, 1, At, B1); PG8_BAR;
;             PG8_LDA(At, 0, 1); PG8_STAGE(PG8_SA(0, 0), a2, voffA);
;             PG8_BAR; PG8_WAIT_L(0); PG8_MMA(1, 0, At, B0); PG8_BAR; PG8_SCHED;
;             PG8_STAGE(PG8_SB(0, 1), b2 + hstepB, voffB);
;             PG8_WAIT_V(6); PG8_BAR; PG8_MMA(1, 1, At, B1); PG8_BAR;
;             PG8_LDB(B0, 1, 0); PG8_SCHED; PG8_LDA(At, 1, 0); PG8_STAGE(PG8_SA(0, 1), a2 + hstepA, voffA);
;             PG8_WAIT_L(8); PG8_BAR; PG8_WAIT_L(0); PG8_MMA(0, 0, At, B0); PG8_BAR; PG8_SCHED;
.LBB0_789:
	ds_read_b128 v[144:147], v199
	ds_read_b128 v[148:151], v199 offset:1024
	ds_read_b128 v[152:155], v199 offset:2048
	ds_read_b128 v[156:159], v199 offset:3072
	s_add_u32 s20, s18, 0x4000
	s_addc_u32 s21, s19, 0
	s_cmp_eq_u32 s46, 60
	s_cselect_b32 s24, s42, s20
	s_cselect_b32 s25, s11, s21
	s_cselect_b32 s20, s43, s44
	s_cselect_b32 s21, s9, s45
	s_add_u32 s22, s24, 0x8000
	s_addc_u32 s23, s25, 0
	v_lshl_add_u64 v[192:193], s[18:19], 0, v[136:137]
	s_add_i32 m0, s17, 0xc000
	ds_read_b128 v[160:163], v200
	ds_read_b128 v[164:167], v200 offset:1024
	ds_read_b128 v[168:171], v200 offset:2048
	ds_read_b128 v[172:175], v200 offset:3072
	ds_read_b128 v[176:179], v200 offset:4096
	ds_read_b128 v[180:183], v200 offset:5120
	ds_read_b128 v[184:187], v200 offset:6144
	ds_read_b128 v[188:191], v200 offset:7168
	global_load_lds_dwordx4 v[192:193], off
	s_add_i32 m0, s17, 0xe000
	v_lshl_add_u64 v[192:193], s[18:19], 0, v[138:139]
	global_load_lds_dwordx4 v[192:193], off
	s_waitcnt lgkmcnt(8)
	s_barrier
	s_waitcnt lgkmcnt(0)
	v_mfma_f32_16x16x32_bf16 v[124:127], v[144:147], v[160:163], v[124:127]
	v_mfma_f32_16x16x32_bf16 v[120:123], v[152:155], v[160:163], v[120:123]
	v_mfma_f32_16x16x32_bf16 v[112:115], v[144:147], v[168:171], v[112:115]
	v_mfma_f32_16x16x32_bf16 v[104:107], v[152:155], v[168:171], v[104:107]
	v_mfma_f32_16x16x32_bf16 v[96:99], v[144:147], v[176:179], v[96:99]
	v_mfma_f32_16x16x32_bf16 v[88:91], v[152:155], v[176:179], v[88:91]
	v_mfma_f32_16x16x32_bf16 v[80:83], v[144:147], v[184:187], v[80:83]
	v_mfma_f32_16x16x32_bf16 v[72:75], v[152:155], v[184:187], v[72:75]
	v_mfma_f32_16x16x32_bf16 v[124:127], v[148:151], v[164:167], v[124:127]
	v_mfma_f32_16x16x32_bf16 v[120:123], v[156:159], v[164:167], v[120:123]
	v_mfma_f32_16x16x32_bf16 v[112:115], v[148:151], v[172:175], v[112:115]
	v_mfma_f32_16x16x32_bf16 v[104:107], v[156:159], v[172:175], v[104:107]
	v_mfma_f32_16x16x32_bf16 v[96:99], v[148:151], v[180:183], v[96:99]
	v_mfma_f32_16x16x32_bf16 v[88:91], v[156:159], v[180:183], v[88:91]
	v_mfma_f32_16x16x32_bf16 v[80:83], v[148:151], v[188:191], v[80:83]
	v_mfma_f32_16x16x32_bf16 v[72:75], v[156:159], v[188:191], v[72:75]
	s_barrier
	s_add_i32 s47, s39, s31
	v_lshl_add_u64 v[214:215], s[20:21], 0, v[130:131]
	s_mov_b32 m0, s47
	ds_read_b128 v[192:195], v201
	ds_read_b128 v[202:205], v201 offset:1024
	ds_read_b128 v[206:209], v201 offset:2048
	ds_read_b128 v[210:213], v201 offset:3072
	global_load_lds_dwordx4 v[214:215], off
	s_add_i32 m0, s47, 0x2000
	v_lshl_add_u64 v[216:217], s[20:21], 0, v[134:135]
	global_load_lds_dwordx4 v[216:217], off
	s_barrier
	s_waitcnt lgkmcnt(0)
	v_mfma_f32_16x16x32_bf16 v[116:119], v[192:195], v[160:163], v[116:119]
	v_mfma_f32_16x16x32_bf16 v[108:111], v[206:209], v[160:163], v[108:111]
	v_mfma_f32_16x16x32_bf16 v[100:103], v[192:195], v[168:171], v[100:103]
	v_mfma_f32_16x16x32_bf16 v[92:95], v[206:209], v[168:171], v[92:95]
	v_mfma_f32_16x16x32_bf16 v[84:87], v[192:195], v[176:179], v[84:87]
	v_mfma_f32_16x16x32_bf16 v[76:79], v[206:209], v[176:179], v[76:79]
	v_mfma_f32_16x16x32_bf16 v[68:71], v[192:195], v[184:187], v[68:71]
	v_mfma_f32_16x16x32_bf16 v[64:67], v[206:209], v[184:187], v[64:67]
	v_mfma_f32_16x16x32_bf16 v[116:119], v[202:205], v[164:167], v[116:119]
	v_mfma_f32_16x16x32_bf16 v[108:111], v[210:213], v[164:167], v[108:111]
	v_mfma_f32_16x16x32_bf16 v[100:103], v[202:205], v[172:175], v[100:103]
	v_mfma_f32_16x16x32_bf16 v[92:95], v[210:213], v[172:175], v[92:95]
	v_mfma_f32_16x16x32_bf16 v[84:87], v[202:205], v[180:183], v[84:87]
	v_mfma_f32_16x16x32_bf16 v[76:79], v[210:213], v[180:183], v[76:79]
	v_mfma_f32_16x16x32_bf16 v[68:71], v[202:205], v[188:191], v[68:71]
	v_mfma_f32_16x16x32_bf16 v[64:67], v[210:213], v[188:191], v[64:67]
	s_mov_b32 m0, s17
	v_lshl_add_u64 v[218:219], s[24:25], 0, v[128:129]
	s_barrier
	ds_read_b128 v[160:163], v200 offset:16384
	ds_read_b128 v[164:167], v200 offset:17408
	ds_read_b128 v[168:171], v200 offset:18432
	ds_read_b128 v[172:175], v200 offset:19456
	ds_read_b128 v[176:179], v200 offset:20480
	ds_read_b128 v[180:183], v200 offset:21504
	ds_read_b128 v[184:187], v200 offset:22528
	ds_read_b128 v[188:191], v200 offset:23552
	global_load_lds_dwordx4 v[218:219], off
	s_mov_b32 m0, s33
	v_lshl_add_u64 v[218:219], s[24:25], 0, v[132:133]
	global_load_lds_dwordx4 v[218:219], off
	s_barrier
	s_waitcnt lgkmcnt(0)
	v_mfma_f32_16x16x32_bf16 v[60:63], v[144:147], v[160:163], v[60:63]
	v_mfma_f32_16x16x32_bf16 v[56:59], v[152:155], v[160:163], v[56:59]
	v_mfma_f32_16x16x32_bf16 v[48:51], v[144:147], v[168:171], v[48:51]
	v_mfma_f32_16x16x32_bf16 v[40:43], v[152:155], v[168:171], v[40:43]
	v_mfma_f32_16x16x32_bf16 v[32:35], v[144:147], v[176:179], v[32:35]
	v_mfma_f32_16x16x32_bf16 v[24:27], v[152:155], v[176:179], v[24:27]
	v_mfma_f32_16x16x32_bf16 v[16:19], v[144:147], v[184:187], v[16:19]
	v_mfma_f32_16x16x32_bf16 v[8:11], v[152:155], v[184:187], v[8:11]
	v_mfma_f32_16x16x32_bf16 v[60:63], v[148:151], v[164:167], v[60:63]
	v_mfma_f32_16x16x32_bf16 v[56:59], v[156:159], v[164:167], v[56:59]
	v_mfma_f32_16x16x32_bf16 v[48:51], v[148:151], v[172:175], v[48:51]
	v_mfma_f32_16x16x32_bf16 v[40:43], v[156:159], v[172:175], v[40:43]
	v_mfma_f32_16x16x32_bf16 v[32:35], v[148:151], v[180:183], v[32:35]
	v_mfma_f32_16x16x32_bf16 v[24:27], v[156:159], v[180:183], v[24:27]
	v_mfma_f32_16x16x32_bf16 v[16:19], v[148:151], v[188:191], v[16:19]
	v_mfma_f32_16x16x32_bf16 v[8:11], v[156:159], v[188:191], v[8:11]
	s_barrier
; #define PG8_STAGE(bufoff, gbase, voff) do { _Pragma("unroll") for (int _i = 0; _i < 2; ++_i) \
;         __builtin_amdgcn_global_load_lds((const unsigned*)((const char*)(gbase) + (voff)[_i]), (LAS unsigned*)(lds + (bufoff) + ldsw + _i * 8192), 16, 0, 0); } while (0)
; #define PG8_LDA(dst, b, h) do { _Pragma("unroll") for (int m = 0; m < 4; ++m) _Pragma("unroll") for (int k = 0; k < 2; ++k) dst[m][k] = *(const LAS bf16x8*)(lds + PG8_SA(b, h) + aoff + m * 2048 + k * 1024); } while (0)
; #define PG8_LDB(dst, b, h) do { _Pragma("unroll") for (int n = 0; n < 2; ++n) _Pragma("unroll") for (int k = 0; k < 2; ++k) dst[n][k] = *(const LAS bf16x8*)(lds + PG8_SB(b, h) + boff + n * 2048 + k * 1024); } while (0)
; #define PG8_MMA(ai, bj, At, Bt) do { __builtin_amdgcn_s_setprio(1); _Pragma("unroll") for (int m = 0; m < 4; ++m) _Pragma("unroll") for (int n = 0; n < 2; ++n) _Pragma("unroll") for (int k = 0; k < 2; ++k) \
;         acc[ai][bj][m][n] = __builtin_amdgcn_mfma_f32_16x16x32_bf16(Bt[n][k], At[m][k], acc[ai][bj][m][n], 0, 0, 0); __builtin_amdgcn_s_setprio(0); } while (0)
; #define PG8_WAIT_V(n) asm volatile("s_waitcnt vmcnt(" #n ")" ::: "memory")
; #define PG8_WAIT_L(n) asm volatile("s_waitcnt lgkmcnt(" #n ")" ::: "memory")
; #define PG8_BAR __builtin_amdgcn_s_barrier()
; #define PG8_SCHED __builtin_amdgcn_sched_barrier(0)
; template <class Epi, class Sched>
; __device__ __forceinline__ void gemm_phase(const int wv, LAS unsigned char* lds, const Gemm g, const Sched& S, const Epi& E) {
;     ...
;             PG8_STAGE(PG8_SB(0, 1), b2 + hstepB, voffB);
;             PG8_WAIT_V(6); PG8_BAR; PG8_MMA(1, 1, At, B1); PG8_BAR;
;             PG8_LDB(B0, 1, 0); PG8_SCHED; PG8_LDA(At, 1, 0); PG8_STAGE(PG8_SA(0, 1), a2 + hstepA, voffA);
;             PG8_WAIT_L(8); PG8_BAR; PG8_WAIT_L(0); PG8_MMA(0, 0, At, B0); PG8_BAR; PG8_SCHED;
;             PG8_LDB(B1, 1, 1); PG8_STAGE(PG8_SB(1, 0), b3, voffB);
;             PG8_BAR; PG8_WAIT_L(0); PG8_MMA(0, 1, At, B1); PG8_BAR;
;             PG8_LDA(At, 1, 1); PG8_STAGE(PG8_SA(1, 0), a3, voffA);
;             PG8_BAR; PG8_WAIT_L(0); PG8_MMA(1, 0, At, B0); PG8_BAR; PG8_SCHED;
	s_add_u32 s48, s20, 0x100000
	s_addc_u32 s49, s21, 0
	s_add_i32 s47, s40, s31
	s_mov_b32 m0, s47
	v_lshl_add_u64 v[144:145], s[48:49], 0, v[130:131]
	global_load_lds_dwordx4 v[144:145], off
	s_add_i32 m0, s47, 0x2000
	v_lshl_add_u64 v[144:145], s[48:49], 0, v[134:135]
	global_load_lds_dwordx4 v[144:145], off
	s_waitcnt vmcnt(6)
	s_barrier
	v_mfma_f32_16x16x32_bf16 v[52:55], v[192:195], v[160:163], v[52:55]
	v_mfma_f32_16x16x32_bf16 v[44:47], v[206:209], v[160:163], v[44:47]
	v_mfma_f32_16x16x32_bf16 v[36:39], v[192:195], v[168:171], v[36:39]
	v_mfma_f32_16x16x32_bf16 v[28:31], v[206:209], v[168:171], v[28:31]
	v_mfma_f32_16x16x32_bf16 v[20:23], v[192:195], v[176:179], v[20:23]
	v_mfma_f32_16x16x32_bf16 v[12:15], v[206:209], v[176:179], v[12:15]
	v_mfma_f32_16x16x32_bf16 v[4:7], v[192:195], v[184:187], v[4:7]
	v_mfma_f32_16x16x32_bf16 v[0:3], v[206:209], v[184:187], v[0:3]
	v_mfma_f32_16x16x32_bf16 v[52:55], v[202:205], v[164:167], v[52:55]
	v_mfma_f32_16x16x32_bf16 v[44:47], v[210:213], v[164:167], v[44:47]
	v_mfma_f32_16x16x32_bf16 v[36:39], v[202:205], v[172:175], v[36:39]
	v_mfma_f32_16x16x32_bf16 v[28:31], v[210:213], v[172:175], v[28:31]
	v_mfma_f32_16x16x32_bf16 v[20:23], v[202:205], v[180:183], v[20:23]
	v_mfma_f32_16x16x32_bf16 v[12:15], v[210:213], v[180:183], v[12:15]
	v_mfma_f32_16x16x32_bf16 v[4:7], v[202:205], v[188:191], v[4:7]
	v_mfma_f32_16x16x32_bf16 v[0:3], v[210:213], v[188:191], v[0:3]
	s_add_i32 s47, 0, 0x18000
	v_add_u32_e32 v156, s47, v197
	s_barrier
	ds_read_b128 v[144:147], v156
	ds_read_b128 v[148:151], v156 offset:1024
	ds_read_b128 v[152:155], v156 offset:2048
	ds_read_b128 v[156:159], v156 offset:3072
	s_add_u32 s24, s24, 0x4000
	s_addc_u32 s25, s25, 0
	s_mov_b32 m0, s34
	v_lshl_add_u64 v[192:193], s[24:25], 0, v[128:129]
	ds_read_b128 v[160:163], v200 offset:32768
	ds_read_b128 v[164:167], v200 offset:33792
	ds_read_b128 v[168:171], v200 offset:34816
	ds_read_b128 v[172:175], v200 offset:35840
	ds_read_b128 v[176:179], v200 offset:36864
	ds_read_b128 v[180:183], v200 offset:37888
	ds_read_b128 v[184:187], v200 offset:38912
	ds_read_b128 v[188:191], v200 offset:39936
	global_load_lds_dwordx4 v[192:193], off
	s_mov_b32 m0, s35
	v_lshl_add_u64 v[192:193], s[24:25], 0, v[132:133]
	global_load_lds_dwordx4 v[192:193], off
	s_waitcnt lgkmcnt(8)
	s_barrier
	s_waitcnt lgkmcnt(0)
	v_mfma_f32_16x16x32_bf16 v[124:127], v[144:147], v[160:163], v[124:127]
	v_mfma_f32_16x16x32_bf16 v[120:123], v[152:155], v[160:163], v[120:123]
	v_mfma_f32_16x16x32_bf16 v[112:115], v[144:147], v[168:171], v[112:115]
	v_mfma_f32_16x16x32_bf16 v[104:107], v[152:155], v[168:171], v[104:107]
	v_mfma_f32_16x16x32_bf16 v[96:99], v[144:147], v[176:179], v[96:99]
	v_mfma_f32_16x16x32_bf16 v[88:91], v[152:155], v[176:179], v[88:91]
	v_mfma_f32_16x16x32_bf16 v[80:83], v[144:147], v[184:187], v[80:83]
	v_mfma_f32_16x16x32_bf16 v[72:75], v[152:155], v[184:187], v[72:75]
	v_mfma_f32_16x16x32_bf16 v[124:127], v[148:151], v[164:167], v[124:127]
	v_mfma_f32_16x16x32_bf16 v[120:123], v[156:159], v[164:167], v[120:123]
	v_mfma_f32_16x16x32_bf16 v[112:115], v[148:151], v[172:175], v[112:115]
	v_mfma_f32_16x16x32_bf16 v[104:107], v[156:159], v[172:175], v[104:107]
	v_mfma_f32_16x16x32_bf16 v[96:99], v[148:151], v[180:183], v[96:99]
	v_mfma_f32_16x16x32_bf16 v[88:91], v[156:159], v[180:183], v[88:91]
	v_mfma_f32_16x16x32_bf16 v[80:83], v[148:151], v[188:191], v[80:83]
	v_mfma_f32_16x16x32_bf16 v[72:75], v[156:159], v[188:191], v[72:75]
	s_barrier
	s_add_i32 s24, 0, 0x1c000
	s_add_i32 s25, s47, s31
	v_add_u32_e32 v210, s24, v197
	v_lshl_add_u64 v[214:215], v[214:215], 0, s[6:7]
	s_mov_b32 m0, s25
	ds_read_b128 v[192:195], v210
	ds_read_b128 v[202:205], v210 offset:1024
	ds_read_b128 v[206:209], v210 offset:2048
	ds_read_b128 v[210:213], v210 offset:3072
	global_load_lds_dwordx4 v[214:215], off
	s_add_i32 m0, s25, 0x2000
	v_lshl_add_u64 v[214:215], v[216:217], 0, s[6:7]
	global_load_lds_dwordx4 v[214:215], off
	s_barrier
	s_waitcnt lgkmcnt(0)
	v_mfma_f32_16x16x32_bf16 v[116:119], v[192:195], v[160:163], v[116:119]
	v_mfma_f32_16x16x32_bf16 v[108:111], v[206:209], v[160:163], v[108:111]
	v_mfma_f32_16x16x32_bf16 v[100:103], v[192:195], v[168:171], v[100:103]
	v_mfma_f32_16x16x32_bf16 v[92:95], v[206:209], v[168:171], v[92:95]
	v_mfma_f32_16x16x32_bf16 v[84:87], v[192:195], v[176:179], v[84:87]
	v_mfma_f32_16x16x32_bf16 v[76:79], v[206:209], v[176:179], v[76:79]
	v_mfma_f32_16x16x32_bf16 v[68:71], v[192:195], v[184:187], v[68:71]
	v_mfma_f32_16x16x32_bf16 v[64:67], v[206:209], v[184:187], v[64:67]
	v_mfma_f32_16x16x32_bf16 v[116:119], v[202:205], v[164:167], v[116:119]
	v_mfma_f32_16x16x32_bf16 v[108:111], v[210:213], v[164:167], v[108:111]
	v_mfma_f32_16x16x32_bf16 v[100:103], v[202:205], v[172:175], v[100:103]
	v_mfma_f32_16x16x32_bf16 v[92:95], v[210:213], v[172:175], v[92:95]
	v_mfma_f32_16x16x32_bf16 v[84:87], v[202:205], v[180:183], v[84:87]
	v_mfma_f32_16x16x32_bf16 v[76:79], v[210:213], v[180:183], v[76:79]
	v_mfma_f32_16x16x32_bf16 v[68:71], v[202:205], v[188:191], v[68:71]
	v_mfma_f32_16x16x32_bf16 v[64:67], v[210:213], v[188:191], v[64:67]
	s_mov_b32 m0, s37
	v_lshl_add_u64 v[214:215], s[22:23], 0, v[128:129]
	s_barrier
	ds_read_b128 v[160:163], v200 offset:49152
	ds_read_b128 v[164:167], v200 offset:50176
	ds_read_b128 v[168:171], v200 offset:51200
	ds_read_b128 v[172:175], v200 offset:52224
	ds_read_b128 v[176:179], v200 offset:53248
	ds_read_b128 v[180:183], v200 offset:54272
	ds_read_b128 v[184:187], v200 offset:55296
	ds_read_b128 v[188:191], v200 offset:56320
	global_load_lds_dwordx4 v[214:215], off
	s_mov_b32 m0, s38
	v_lshl_add_u64 v[214:215], s[22:23], 0, v[132:133]
	global_load_lds_dwordx4 v[214:215], off
	s_barrier
; #define PG8_STAGE(bufoff, gbase, voff) do { _Pragma("unroll") for (int _i = 0; _i < 2; ++_i) \
;         __builtin_amdgcn_global_load_lds((const unsigned*)((const char*)(gbase) + (voff)[_i]), (LAS unsigned*)(lds + (bufoff) + ldsw + _i * 8192), 16, 0, 0); } while (0)
; #define PG8_MMA(ai, bj, At, Bt) do { __builtin_amdgcn_s_setprio(1); _Pragma("unroll") for (int m = 0; m < 4; ++m) _Pragma("unroll") for (int n = 0; n < 2; ++n) _Pragma("unroll") for (int k = 0; k < 2; ++k) \
;         acc[ai][bj][m][n] = __builtin_amdgcn_mfma_f32_16x16x32_bf16(Bt[n][k], At[m][k], acc[ai][bj][m][n], 0, 0, 0); __builtin_amdgcn_s_setprio(0); } while (0)
; #define PG8_WAIT_V(n) asm volatile("s_waitcnt vmcnt(" #n ")" ::: "memory")
; #define PG8_WAIT_L(n) asm volatile("s_waitcnt lgkmcnt(" #n ")" ::: "memory")
; #define PG8_BAR __builtin_amdgcn_s_barrier()
; #define PG8_SCHED __builtin_amdgcn_sched_barrier(0)
; template <class Epi, class Sched>
; __device__ __forceinline__ void gemm_phase(const int wv, LAS unsigned char* lds, const Gemm g, const Sched& S, const Epi& E) {
;     ...
;             PG8_BAR; PG8_WAIT_L(0); PG8_MMA(1, 0, At, B0); PG8_BAR; PG8_SCHED;
;             PG8_STAGE(PG8_SB(1, 1), b3 + hstepB, voffB);
;             PG8_WAIT_V(6); PG8_BAR; PG8_MMA(1, 1, At, B1); PG8_BAR;
;         }
;     __device__ __forceinline__ void operator()(const f32x4 (&acc)[2][2][4][2], const Unit& u, int wr, int wc, int fr, int fq) const {
;     ...
; #pragma unroll
;         for (int ai = 0; ai < 2; ++ai)
; #pragma unroll
;             for (int m = 0; m < 4; ++m)
; #pragma unroll
;                 for (int bj = 0; bj < 2; ++bj)
; #pragma unroll
;                     for (int n = 0; n < 2; ++n) xv[ai][m][bj][n] = *(const u32x2*)(x1b + (size_t)(row0 + ai * 128 + m * 16) * 1024 + col0 + bj * 128 + n * 16);
	s_waitcnt lgkmcnt(0)
	v_mfma_f32_16x16x32_bf16 v[60:63], v[144:147], v[160:163], v[60:63]
	v_mfma_f32_16x16x32_bf16 v[56:59], v[152:155], v[160:163], v[56:59]
	v_mfma_f32_16x16x32_bf16 v[48:51], v[144:147], v[168:171], v[48:51]
	v_mfma_f32_16x16x32_bf16 v[40:43], v[152:155], v[168:171], v[40:43]
	v_mfma_f32_16x16x32_bf16 v[32:35], v[144:147], v[176:179], v[32:35]
	v_mfma_f32_16x16x32_bf16 v[24:27], v[152:155], v[176:179], v[24:27]
	v_mfma_f32_16x16x32_bf16 v[16:19], v[144:147], v[184:187], v[16:19]
	v_mfma_f32_16x16x32_bf16 v[8:11], v[152:155], v[184:187], v[8:11]
	v_mfma_f32_16x16x32_bf16 v[60:63], v[148:151], v[164:167], v[60:63]
	v_mfma_f32_16x16x32_bf16 v[56:59], v[156:159], v[164:167], v[56:59]
	v_mfma_f32_16x16x32_bf16 v[48:51], v[148:151], v[172:175], v[48:51]
	v_mfma_f32_16x16x32_bf16 v[40:43], v[156:159], v[172:175], v[40:43]
	v_mfma_f32_16x16x32_bf16 v[32:35], v[148:151], v[180:183], v[32:35]
	v_mfma_f32_16x16x32_bf16 v[24:27], v[156:159], v[180:183], v[24:27]
	v_mfma_f32_16x16x32_bf16 v[16:19], v[148:151], v[188:191], v[16:19]
	v_mfma_f32_16x16x32_bf16 v[8:11], v[156:159], v[188:191], v[8:11]
	s_barrier
	s_add_u32 s20, s20, 0x100080
	s_addc_u32 s21, s21, 0
	s_add_i32 s22, s24, s31
	s_mov_b32 m0, s22
	v_lshl_add_u64 v[144:145], s[20:21], 0, v[130:131]
	global_load_lds_dwordx4 v[144:145], off
	s_add_i32 m0, s22, 0x2000
	v_lshl_add_u64 v[144:145], s[20:21], 0, v[134:135]
	global_load_lds_dwordx4 v[144:145], off
	s_waitcnt vmcnt(6)
	s_barrier
	v_mfma_f32_16x16x32_bf16 v[52:55], v[192:195], v[160:163], v[52:55]
	v_mfma_f32_16x16x32_bf16 v[44:47], v[206:209], v[160:163], v[44:47]
	v_mfma_f32_16x16x32_bf16 v[36:39], v[192:195], v[168:171], v[36:39]
	v_mfma_f32_16x16x32_bf16 v[28:31], v[206:209], v[168:171], v[28:31]
	v_mfma_f32_16x16x32_bf16 v[20:23], v[192:195], v[176:179], v[20:23]
	v_mfma_f32_16x16x32_bf16 v[12:15], v[206:209], v[176:179], v[12:15]
	v_mfma_f32_16x16x32_bf16 v[4:7], v[192:195], v[184:187], v[4:7]
	v_mfma_f32_16x16x32_bf16 v[0:3], v[206:209], v[184:187], v[0:3]
	v_mfma_f32_16x16x32_bf16 v[52:55], v[202:205], v[164:167], v[52:55]
	v_mfma_f32_16x16x32_bf16 v[44:47], v[210:213], v[164:167], v[44:47]
	v_mfma_f32_16x16x32_bf16 v[36:39], v[202:205], v[172:175], v[36:39]
	v_mfma_f32_16x16x32_bf16 v[28:31], v[210:213], v[172:175], v[28:31]
	v_mfma_f32_16x16x32_bf16 v[20:23], v[202:205], v[180:183], v[20:23]
	v_mfma_f32_16x16x32_bf16 v[12:15], v[210:213], v[180:183], v[12:15]
	v_mfma_f32_16x16x32_bf16 v[4:7], v[202:205], v[188:191], v[4:7]
	v_mfma_f32_16x16x32_bf16 v[0:3], v[210:213], v[188:191], v[0:3]
	s_add_i32 s46, s46, 2
	s_add_u32 s44, s44, 0x100
	s_addc_u32 s45, s45, 0
	s_add_u32 s18, s18, 0x10000
	s_addc_u32 s19, s19, 0
	s_cmp_gt_u32 s46, 61
	s_barrier
	s_cbranch_scc0 .LBB0_789
	v_lshl_add_u32 v146, s16, 8, v196
	v_lshl_or_b32 v148, s41, 8, v198
	v_ashrrev_i32_e32 v149, 31, v148
	v_ashrrev_i32_e32 v147, 31, v146
	v_lshl_add_u64 v[150:151], v[148:149], 1, s[2:3]
	v_lshlrev_b64 v[144:145], 11, v[146:147]
	v_lshl_add_u64 v[144:145], v[150:151], 0, v[144:145]
	global_load_dwordx2 v[202:203], v[144:145], off
	global_load_dwordx2 v[204:205], v[144:145], off offset:32
	global_load_dwordx2 v[206:207], v[144:145], off offset:256
	v_or_b32_e32 v208, 16, v146
	global_load_dwordx2 v[210:211], v[144:145], off offset:288
	v_ashrrev_i32_e32 v209, 31, v208
	v_lshlrev_b64 v[144:145], 11, v[208:209]
	v_lshl_add_u64 v[152:153], v[150:151], 0, v[144:145]
	global_load_dwordx2 v[212:213], v[152:153], off
	global_load_dwordx2 v[214:215], v[152:153], off offset:32
	global_load_dwordx2 v[216:217], v[152:153], off offset:256
	global_load_dwordx2 v[218:219], v[152:153], off offset:288
	v_or_b32_e32 v192, 32, v146
	v_or_b32_e32 v182, 48, v146
	v_add_u32_e32 v174, 0x80, v146
	v_add_u32_e32 v164, 0x90, v146
	v_add_u32_e32 v154, 0xa0, v146
	v_add_u32_e32 v144, 0xb0, v146
	v_ashrrev_i32_e32 v193, 31, v192
	v_ashrrev_i32_e32 v183, 31, v182
	v_ashrrev_i32_e32 v175, 31, v174
	v_ashrrev_i32_e32 v165, 31, v164
	v_ashrrev_i32_e32 v155, 31, v154
	v_ashrrev_i32_e32 v145, 31, v144
	v_lshlrev_b64 v[146:147], 12, v[146:147]
	v_lshlrev_b64 v[156:157], 11, v[192:193]
	v_lshlrev_b64 v[158:159], 11, v[182:183]
	v_lshlrev_b64 v[160:161], 11, v[174:175]
	v_lshlrev_b64 v[162:163], 11, v[164:165]
	v_lshlrev_b64 v[166:167], 11, v[154:155]
	v_lshlrev_b64 v[148:149], 2, v[148:149]
	v_lshlrev_b64 v[168:169], 11, v[144:145]
	v_lshl_add_u64 v[146:147], s[4:5], 0, v[146:147]
	v_lshl_add_u64 v[156:157], v[150:151], 0, v[156:157]
	v_lshl_add_u64 v[158:159], v[150:151], 0, v[158:159]
	v_lshl_add_u64 v[160:161], v[150:151], 0, v[160:161]
	v_lshl_add_u64 v[162:163], v[150:151], 0, v[162:163]
	v_lshl_add_u64 v[152:153], v[150:151], 0, v[166:167]
	v_lshl_add_u64 v[220:221], v[150:151], 0, v[168:169]
	v_lshl_add_u64 v[222:223], v[146:147], 0, v[148:149]
	global_load_dwordx2 v[224:225], v[156:157], off
	global_load_dwordx2 v[226:227], v[156:157], off offset:32
	global_load_dwordx2 v[228:229], v[156:157], off offset:256
	global_load_dwordx2 v[230:231], v[156:157], off offset:288
	global_load_dwordx2 v[232:233], v[158:159], off
	global_load_dwordx2 v[194:195], v[158:159], off offset:32
	global_load_dwordx2 v[190:191], v[158:159], off offset:256
	global_load_dwordx2 v[188:189], v[158:159], off offset:288
	global_load_dwordx2 v[186:187], v[160:161], off
	global_load_dwordx2 v[184:185], v[160:161], off offset:32
	global_load_dwordx2 v[180:181], v[160:161], off offset:256
	global_load_dwordx2 v[178:179], v[160:161], off offset:288
	global_load_dwordx2 v[176:177], v[162:163], off
	global_load_dwordx2 v[172:173], v[162:163], off offset:32
	global_load_dwordx2 v[170:171], v[162:163], off offset:256
	global_load_dwordx2 v[168:169], v[162:163], off offset:288
	global_load_dwordx2 v[166:167], v[152:153], off
	s_nop 0
	global_load_dwordx2 v[162:163], v[152:153], off offset:32
	global_load_dwordx2 v[160:161], v[152:153], off offset:256
	global_load_dwordx2 v[158:159], v[152:153], off offset:288
	global_load_dwordx2 v[156:157], v[220:221], off
	s_nop 0
	global_load_dwordx2 v[152:153], v[220:221], off offset:32
	global_load_dwordx2 v[150:151], v[220:221], off offset:256
	global_load_dwordx2 v[146:147], v[220:221], off offset:288
	s_and_b64 vcc, exec, s[0:1]
	s_mov_b32 s41, s8
	s_mov_b32 s16, s10
	s_mov_b64 s[18:19], s[14:15]
	s_mov_b64 s[20:21], s[12:13]
	s_waitcnt vmcnt(31)
; __device__ __forceinline__ float bflo(unsigned u) { return __uint_as_float(u << 16); }
; __device__ __forceinline__ float bfhi(unsigned u) { return __uint_as_float(u & 0xffff0000u); }
;     __device__ __forceinline__ void operator()(const f32x4 (&acc)[2][2][4][2], const Unit& u, int wr, int wc, int fr, int fq) const {
;     ...
;         for (int ai = 0; ai < 2; ++ai)
; #pragma unroll
;             for (int m = 0; m < 4; ++m)
; #pragma unroll
;                 for (int bj = 0; bj < 2; ++bj)
; #pragma unroll
;                     for (int n = 0; n < 2; ++n) {
;                         const size_t o = (size_t)(row0 + ai * 128 + m * 16) * 1024 + col0 + bj * 128 + n * 16;
;                         const u32x2 v = xv[ai][m][bj][n]; const f32x4 a = acc[ai][bj][m][n];
;                         *(f32x4*)(out + o) = (f32x4){bflo(v.x) + a[0], bfhi(v.x) + a[1], bflo(v.y) + a[2], bfhi(v.y) + a[3]};
	v_lshlrev_b32_e32 v220, 16, v202
	v_and_b32_e32 v221, 0xffff0000, v202
	v_lshlrev_b32_e32 v202, 16, v203
	v_and_b32_e32 v203, 0xffff0000, v203
	s_waitcnt vmcnt(30)
	v_lshlrev_b32_e32 v234, 16, v204
	v_and_b32_e32 v235, 0xffff0000, v204
	v_lshlrev_b32_e32 v204, 16, v205
	v_and_b32_e32 v205, 0xffff0000, v205
	v_pk_add_f32 v[124:125], v[124:125], v[220:221]
	v_pk_add_f32 v[126:127], v[126:127], v[202:203]
	v_pk_add_f32 v[120:121], v[120:121], v[234:235]
	s_waitcnt vmcnt(29)
	v_lshlrev_b32_e32 v236, 16, v206
	v_and_b32_e32 v237, 0xffff0000, v206
	v_pk_add_f32 v[122:123], v[122:123], v[204:205]
	global_store_dwordx4 v[222:223], v[124:127], off
	global_store_dwordx4 v[222:223], v[120:123], off offset:64
	v_pk_add_f32 v[116:117], v[116:117], v[236:237]
	s_nop 0
	v_lshlrev_b32_e32 v120, 16, v207
	v_and_b32_e32 v121, 0xffff0000, v207
	v_pk_add_f32 v[118:119], v[118:119], v[120:121]
	global_store_dwordx4 v[222:223], v[116:119], off offset:512
	s_nop 1
	s_waitcnt vmcnt(31)
	v_lshlrev_b32_e32 v116, 16, v210
	v_and_b32_e32 v117, 0xffff0000, v210
	v_pk_add_f32 v[108:109], v[108:109], v[116:117]
	v_lshlrev_b32_e32 v116, 16, v211
	v_and_b32_e32 v117, 0xffff0000, v211
	v_pk_add_f32 v[110:111], v[110:111], v[116:117]
	global_store_dwordx4 v[222:223], v[108:111], off offset:576
	v_lshlrev_b64 v[116:117], 12, v[208:209]
	s_nop 0
	s_waitcnt vmcnt(31)
	v_lshlrev_b32_e32 v108, 16, v212
	v_and_b32_e32 v109, 0xffff0000, v212
	v_pk_add_f32 v[108:109], v[112:113], v[108:109]
	v_lshlrev_b32_e32 v110, 16, v213
	v_and_b32_e32 v111, 0xffff0000, v213
	v_lshl_add_u64 v[112:113], s[4:5], 0, v[116:117]
	v_pk_add_f32 v[110:111], v[114:115], v[110:111]
	v_lshl_add_u64 v[112:113], v[112:113], 0, v[148:149]
	global_store_dwordx4 v[112:113], v[108:111], off
	s_nop 1
	s_waitcnt vmcnt(31)
	v_lshlrev_b32_e32 v108, 16, v214
	v_and_b32_e32 v109, 0xffff0000, v214
	v_pk_add_f32 v[104:105], v[104:105], v[108:109]
	v_lshlrev_b32_e32 v108, 16, v215
	v_and_b32_e32 v109, 0xffff0000, v215
	v_pk_add_f32 v[106:107], v[106:107], v[108:109]
	global_store_dwordx4 v[112:113], v[104:107], off offset:64
	s_nop 1
	s_waitcnt vmcnt(31)
	v_lshlrev_b32_e32 v104, 16, v216
	v_and_b32_e32 v105, 0xffff0000, v216
	v_pk_add_f32 v[100:101], v[100:101], v[104:105]
	v_lshlrev_b32_e32 v104, 16, v217
	v_and_b32_e32 v105, 0xffff0000, v217
	v_pk_add_f32 v[102:103], v[102:103], v[104:105]
	global_store_dwordx4 v[112:113], v[100:103], off offset:512
	s_nop 1
	s_waitcnt vmcnt(31)
	v_lshlrev_b32_e32 v100, 16, v218
	v_and_b32_e32 v101, 0xffff0000, v218
	v_pk_add_f32 v[92:93], v[92:93], v[100:101]
	v_lshlrev_b32_e32 v100, 16, v219
	v_and_b32_e32 v101, 0xffff0000, v219
	v_pk_add_f32 v[94:95], v[94:95], v[100:101]
	global_store_dwordx4 v[112:113], v[92:95], off offset:576
	v_lshlrev_b64 v[100:101], 12, v[192:193]
	s_nop 0
	s_waitcnt vmcnt(31)
	v_lshlrev_b32_e32 v92, 16, v224
	v_and_b32_e32 v93, 0xffff0000, v224
	v_pk_add_f32 v[92:93], v[96:97], v[92:93]
	v_lshlrev_b32_e32 v94, 16, v225
	v_and_b32_e32 v95, 0xffff0000, v225
	v_lshl_add_u64 v[96:97], s[4:5], 0, v[100:101]
	v_pk_add_f32 v[94:95], v[98:99], v[94:95]
	v_lshl_add_u64 v[96:97], v[96:97], 0, v[148:149]
	global_store_dwordx4 v[96:97], v[92:95], off
	s_nop 1
	s_waitcnt vmcnt(31)
	v_lshlrev_b32_e32 v92, 16, v226
	v_and_b32_e32 v93, 0xffff0000, v226
	v_pk_add_f32 v[88:89], v[88:89], v[92:93]
	v_lshlrev_b32_e32 v92, 16, v227
	v_and_b32_e32 v93, 0xffff0000, v227
	v_pk_add_f32 v[90:91], v[90:91], v[92:93]
	global_store_dwordx4 v[96:97], v[88:91], off offset:64
	s_nop 1
	s_waitcnt vmcnt(31)
	v_lshlrev_b32_e32 v88, 16, v228
	v_and_b32_e32 v89, 0xffff0000, v228
	v_pk_add_f32 v[84:85], v[84:85], v[88:89]
	v_lshlrev_b32_e32 v88, 16, v229
	v_and_b32_e32 v89, 0xffff0000, v229
	v_pk_add_f32 v[86:87], v[86:87], v[88:89]
	global_store_dwordx4 v[96:97], v[84:87], off offset:512
	s_nop 1
	s_waitcnt vmcnt(31)
	v_lshlrev_b32_e32 v84, 16, v230
	v_and_b32_e32 v85, 0xffff0000, v230
	v_pk_add_f32 v[76:77], v[76:77], v[84:85]
	v_lshlrev_b32_e32 v84, 16, v231
	v_and_b32_e32 v85, 0xffff0000, v231
	v_pk_add_f32 v[78:79], v[78:79], v[84:85]
	global_store_dwordx4 v[96:97], v[76:79], off offset:576
	v_lshlrev_b64 v[84:85], 12, v[182:183]
	s_nop 0
	s_waitcnt vmcnt(31)
	v_lshlrev_b32_e32 v76, 16, v232
	v_and_b32_e32 v77, 0xffff0000, v232
	v_pk_add_f32 v[76:77], v[80:81], v[76:77]
	v_lshlrev_b32_e32 v78, 16, v233
	v_and_b32_e32 v79, 0xffff0000, v233
	v_lshl_add_u64 v[80:81], s[4:5], 0, v[84:85]
	v_pk_add_f32 v[78:79], v[82:83], v[78:79]
	v_lshl_add_u64 v[80:81], v[80:81], 0, v[148:149]
	global_store_dwordx4 v[80:81], v[76:79], off
	s_nop 1
	s_waitcnt vmcnt(31)
	v_lshlrev_b32_e32 v76, 16, v194
	v_and_b32_e32 v77, 0xffff0000, v194
	v_pk_add_f32 v[72:73], v[72:73], v[76:77]
	v_lshlrev_b32_e32 v76, 16, v195
	v_and_b32_e32 v77, 0xffff0000, v195
	v_pk_add_f32 v[74:75], v[74:75], v[76:77]
	global_store_dwordx4 v[80:81], v[72:75], off offset:64
	s_nop 1
	s_waitcnt vmcnt(31)
	v_lshlrev_b32_e32 v72, 16, v190
	v_and_b32_e32 v73, 0xffff0000, v190
	v_pk_add_f32 v[68:69], v[68:69], v[72:73]
	v_lshlrev_b32_e32 v72, 16, v191
	v_and_b32_e32 v73, 0xffff0000, v191
	v_pk_add_f32 v[70:71], v[70:71], v[72:73]
	global_store_dwordx4 v[80:81], v[68:71], off offset:512
	s_nop 1
	s_waitcnt vmcnt(31)
	v_lshlrev_b32_e32 v68, 16, v188
	v_and_b32_e32 v69, 0xffff0000, v188
	v_pk_add_f32 v[64:65], v[64:65], v[68:69]
	v_lshlrev_b32_e32 v68, 16, v189
	v_and_b32_e32 v69, 0xffff0000, v189
	v_pk_add_f32 v[66:67], v[66:67], v[68:69]
	global_store_dwordx4 v[80:81], v[64:67], off offset:576
	s_nop 1
	v_lshlrev_b64 v[64:65], 12, v[174:175]
	s_waitcnt vmcnt(31)
; __device__ __forceinline__ float bflo(unsigned u) { return __uint_as_float(u << 16); }
; __device__ __forceinline__ float bfhi(unsigned u) { return __uint_as_float(u & 0xffff0000u); }
; #define PG8_WAIT_V(n) asm volatile("s_waitcnt vmcnt(" #n ")" ::: "memory")
; #define PG8_BAR __builtin_amdgcn_s_barrier()
; template <class Epi, class Sched>
; __device__ __forceinline__ void gemm_phase(const int wv, LAS unsigned char* lds, const Gemm g, const Sched& S, const Epi& E) {
;     ...
;     PG8_WAIT_V(0);
;     if (wr == 0) PG8_BAR;
;     PG8_BAR;
;     __device__ __forceinline__ void operator()(const f32x4 (&acc)[2][2][4][2], const Unit& u, int wr, int wc, int fr, int fq) const {
;     ...
;         for (int ai = 0; ai < 2; ++ai)
; #pragma unroll
;             for (int m = 0; m < 4; ++m)
; #pragma unroll
;                 for (int bj = 0; bj < 2; ++bj)
; #pragma unroll
;                     for (int n = 0; n < 2; ++n) {
;                         const size_t o = (size_t)(row0 + ai * 128 + m * 16) * 1024 + col0 + bj * 128 + n * 16;
;                         const u32x2 v = xv[ai][m][bj][n]; const f32x4 a = acc[ai][bj][m][n];
;                         *(f32x4*)(out + o) = (f32x4){bflo(v.x) + a[0], bfhi(v.x) + a[1], bflo(v.y) + a[2], bfhi(v.y) + a[3]};
	v_lshlrev_b32_e32 v66, 16, v186
	v_and_b32_e32 v67, 0xffff0000, v186
	v_pk_add_f32 v[60:61], v[60:61], v[66:67]
	v_lshlrev_b32_e32 v66, 16, v187
	v_and_b32_e32 v67, 0xffff0000, v187
	v_lshl_add_u64 v[64:65], s[4:5], 0, v[64:65]
	v_pk_add_f32 v[62:63], v[62:63], v[66:67]
	v_lshl_add_u64 v[64:65], v[64:65], 0, v[148:149]
	global_store_dwordx4 v[64:65], v[60:63], off
	s_nop 1
	s_waitcnt vmcnt(31)
	v_lshlrev_b32_e32 v60, 16, v184
	v_and_b32_e32 v61, 0xffff0000, v184
	v_pk_add_f32 v[56:57], v[56:57], v[60:61]
	v_lshlrev_b32_e32 v60, 16, v185
	v_and_b32_e32 v61, 0xffff0000, v185
	v_pk_add_f32 v[58:59], v[58:59], v[60:61]
	global_store_dwordx4 v[64:65], v[56:59], off offset:64
	s_nop 1
	s_waitcnt vmcnt(31)
	v_lshlrev_b32_e32 v56, 16, v180
	v_and_b32_e32 v57, 0xffff0000, v180
	v_pk_add_f32 v[52:53], v[52:53], v[56:57]
	v_lshlrev_b32_e32 v56, 16, v181
	v_and_b32_e32 v57, 0xffff0000, v181
	v_pk_add_f32 v[54:55], v[54:55], v[56:57]
	global_store_dwordx4 v[64:65], v[52:55], off offset:512
	s_nop 1
	s_waitcnt vmcnt(31)
	v_lshlrev_b32_e32 v52, 16, v178
	v_and_b32_e32 v53, 0xffff0000, v178
	v_pk_add_f32 v[44:45], v[44:45], v[52:53]
	v_lshlrev_b32_e32 v52, 16, v179
	v_and_b32_e32 v53, 0xffff0000, v179
	v_pk_add_f32 v[46:47], v[46:47], v[52:53]
	global_store_dwordx4 v[64:65], v[44:47], off offset:576
	v_lshlrev_b64 v[52:53], 12, v[164:165]
	s_nop 0
	s_waitcnt vmcnt(31)
	v_lshlrev_b32_e32 v44, 16, v176
	v_and_b32_e32 v45, 0xffff0000, v176
	v_pk_add_f32 v[44:45], v[48:49], v[44:45]
	v_lshlrev_b32_e32 v46, 16, v177
	v_and_b32_e32 v47, 0xffff0000, v177
	v_lshl_add_u64 v[48:49], s[4:5], 0, v[52:53]
	v_pk_add_f32 v[46:47], v[50:51], v[46:47]
	v_lshl_add_u64 v[48:49], v[48:49], 0, v[148:149]
	global_store_dwordx4 v[48:49], v[44:47], off
	s_nop 1
	s_waitcnt vmcnt(31)
	v_lshlrev_b32_e32 v44, 16, v172
	v_and_b32_e32 v45, 0xffff0000, v172
	v_pk_add_f32 v[40:41], v[40:41], v[44:45]
	v_lshlrev_b32_e32 v44, 16, v173
	v_and_b32_e32 v45, 0xffff0000, v173
	v_pk_add_f32 v[42:43], v[42:43], v[44:45]
	global_store_dwordx4 v[48:49], v[40:43], off offset:64
	s_nop 1
	s_waitcnt vmcnt(31)
	v_lshlrev_b32_e32 v40, 16, v170
	v_and_b32_e32 v41, 0xffff0000, v170
	v_pk_add_f32 v[36:37], v[36:37], v[40:41]
	v_lshlrev_b32_e32 v40, 16, v171
	v_and_b32_e32 v41, 0xffff0000, v171
	v_pk_add_f32 v[38:39], v[38:39], v[40:41]
	global_store_dwordx4 v[48:49], v[36:39], off offset:512
	s_nop 1
	s_waitcnt vmcnt(31)
	v_lshlrev_b32_e32 v36, 16, v168
	v_and_b32_e32 v37, 0xffff0000, v168
	v_pk_add_f32 v[28:29], v[28:29], v[36:37]
	v_lshlrev_b32_e32 v36, 16, v169
	v_and_b32_e32 v37, 0xffff0000, v169
	v_pk_add_f32 v[30:31], v[30:31], v[36:37]
	global_store_dwordx4 v[48:49], v[28:31], off offset:576
	v_lshlrev_b64 v[36:37], 12, v[154:155]
	s_nop 0
	s_waitcnt vmcnt(31)
	v_lshlrev_b32_e32 v28, 16, v166
	v_and_b32_e32 v29, 0xffff0000, v166
	v_pk_add_f32 v[28:29], v[32:33], v[28:29]
	v_lshlrev_b32_e32 v30, 16, v167
	v_and_b32_e32 v31, 0xffff0000, v167
	v_lshl_add_u64 v[32:33], s[4:5], 0, v[36:37]
	v_pk_add_f32 v[30:31], v[34:35], v[30:31]
	v_lshl_add_u64 v[32:33], v[32:33], 0, v[148:149]
	global_store_dwordx4 v[32:33], v[28:31], off
	s_nop 1
	s_waitcnt vmcnt(31)
	v_lshlrev_b32_e32 v28, 16, v162
	v_and_b32_e32 v29, 0xffff0000, v162
	v_pk_add_f32 v[24:25], v[24:25], v[28:29]
	v_lshlrev_b32_e32 v28, 16, v163
	v_and_b32_e32 v29, 0xffff0000, v163
	v_pk_add_f32 v[26:27], v[26:27], v[28:29]
	global_store_dwordx4 v[32:33], v[24:27], off offset:64
	s_nop 1
	s_waitcnt vmcnt(31)
	v_lshlrev_b32_e32 v24, 16, v160
	v_and_b32_e32 v25, 0xffff0000, v160
	v_pk_add_f32 v[20:21], v[20:21], v[24:25]
	v_lshlrev_b32_e32 v24, 16, v161
	v_and_b32_e32 v25, 0xffff0000, v161
	v_pk_add_f32 v[22:23], v[22:23], v[24:25]
	global_store_dwordx4 v[32:33], v[20:23], off offset:512
	s_nop 1
	s_waitcnt vmcnt(31)
	v_lshlrev_b32_e32 v20, 16, v158
	v_and_b32_e32 v21, 0xffff0000, v158
	v_pk_add_f32 v[12:13], v[12:13], v[20:21]
	v_lshlrev_b32_e32 v20, 16, v159
	v_and_b32_e32 v21, 0xffff0000, v159
	v_pk_add_f32 v[14:15], v[14:15], v[20:21]
	global_store_dwordx4 v[32:33], v[12:15], off offset:576
	v_lshlrev_b64 v[20:21], 12, v[144:145]
	s_nop 0
	s_waitcnt vmcnt(31)
	v_lshlrev_b32_e32 v12, 16, v156
	v_and_b32_e32 v13, 0xffff0000, v156
	v_pk_add_f32 v[12:13], v[16:17], v[12:13]
	v_lshlrev_b32_e32 v14, 16, v157
	v_and_b32_e32 v15, 0xffff0000, v157
	v_lshl_add_u64 v[16:17], s[4:5], 0, v[20:21]
	v_pk_add_f32 v[14:15], v[18:19], v[14:15]
	v_lshl_add_u64 v[16:17], v[16:17], 0, v[148:149]
	global_store_dwordx4 v[16:17], v[12:15], off
	s_nop 1
	s_waitcnt vmcnt(31)
	v_lshlrev_b32_e32 v12, 16, v152
	v_and_b32_e32 v13, 0xffff0000, v152
	v_pk_add_f32 v[8:9], v[8:9], v[12:13]
	v_lshlrev_b32_e32 v12, 16, v153
	v_and_b32_e32 v13, 0xffff0000, v153
	v_pk_add_f32 v[10:11], v[10:11], v[12:13]
	global_store_dwordx4 v[16:17], v[8:11], off offset:64
	s_nop 1
	s_waitcnt vmcnt(31)
	v_lshlrev_b32_e32 v8, 16, v150
	v_and_b32_e32 v9, 0xffff0000, v150
	v_pk_add_f32 v[4:5], v[4:5], v[8:9]
	v_lshlrev_b32_e32 v8, 16, v151
	v_and_b32_e32 v9, 0xffff0000, v151
	v_pk_add_f32 v[6:7], v[6:7], v[8:9]
	global_store_dwordx4 v[16:17], v[4:7], off offset:512
	s_nop 1
	s_waitcnt vmcnt(31)
	v_lshlrev_b32_e32 v4, 16, v146
	v_and_b32_e32 v5, 0xffff0000, v146
	v_pk_add_f32 v[0:1], v[0:1], v[4:5]
	v_lshlrev_b32_e32 v4, 16, v147
	v_and_b32_e32 v5, 0xffff0000, v147
	v_pk_add_f32 v[2:3], v[2:3], v[4:5]
	global_store_dwordx4 v[16:17], v[0:3], off offset:576
	s_cbranch_vccz .LBB0_782
	s_waitcnt vmcnt(0)
	s_cmpk_gt_u32 s26, 0xff
	s_cbranch_scc1 .LBB0_793
	s_barrier
